# GEMM sub-phases: s_setprio 1 moved in front of the pre-MFMA barrier and s_setprio 0 moved behind the post-MFMA barrier, so neither sits between a barrier release/arrival and the MFMA burst
# speedup vs baseline: 1.0160x; 1.0005x over previous
; #define PG8_STAGE(bufoff, gbase, voff) do { _Pragma("unroll") for (int _i = 0; _i < 2; ++_i) \
;         __builtin_amdgcn_global_load_lds((const unsigned*)((const char*)(gbase) + (voff)[_i]), (PG8_LAS unsigned*)(lds + (bufoff) + ldsw + _i * 8192), 16, 0, 0); } while (0)
; #define PG8_WAIT_V(n) asm volatile("s_waitcnt vmcnt(" #n ")" ::: "memory")
; #define PG8_WAIT_L(n) asm volatile("s_waitcnt lgkmcnt(" #n ")" ::: "memory")
; #define PG8_BAR __builtin_amdgcn_s_barrier()
; template <class Epi, class Sched, bool ALIGN_EPI = false, bool SP2 = false>
; __device__ __forceinline__ void gemm_phase(PG8_LAS unsigned char* lds, const Gemm g, const Sched& S, const Epi& E, const int tid) {
;     ...
;     for (;;) {
;         const bool has_next = S.next(ui + 1, nxt);
;         const char* nA = has_next ? (const char*)g.A + (size_t)nxt.pm * tstep : cA; const char* nB = has_next ? (const char*)g.Bt + (size_t)nxt.pn * tstep : cB;
;         for (int t = 0; t < nt; t += 2) {
;             const bool last = (t == nt - 2);
;             const char* a1 = cA + (size_t)(t + 1) * kstep;
;             const char* a2 = last ? nA : cA + (size_t)(t + 2) * kstep; const char* b2 = last ? nB : cB + (size_t)(t + 2) * kstep;
;             const char* a3 = a2 + kstep; const char* b3 = b2 + kstep;
;             if (last && has_next) S.a_ready(nxt);
;             if constexpr (SP2) {
;             PG8_LDB(B0, 0, 0); PG8_LDB(B1, 0, 1); PG8_SCHED; PG8_LDA(At, 0, 0); PG8_STAGE(PG8_SA(1, 1), a1 + hstep, voffA);
;             PG8_WAIT_V(8); PG8_WAIT_L(0); PG8_BAR; PG8_MMA(0, 0, At, B0); PG8_MMA(0, 1, At, B1); PG8_BAR; PG8_SCHED;
;             PG8_LDA(At, 0, 1); PG8_STAGE(PG8_SB(0, 0), b2, voffB); PG8_STAGE(PG8_SB(0, 1), b2 + hstep, voffB); PG8_STAGE(PG8_SA(0, 0), a2, voffA);
;             PG8_WAIT_V(8); PG8_WAIT_L(0); PG8_BAR; PG8_MMA(1, 0, At, B0); PG8_MMA(1, 1, At, B1); PG8_BAR; PG8_SCHED;
;             PG8_LDB(B0, 1, 0); PG8_LDB(B1, 1, 1); PG8_SCHED; PG8_LDA(At, 1, 0); PG8_STAGE(PG8_SA(0, 1), a2 + hstep, voffA);
;             PG8_WAIT_V(8); PG8_WAIT_L(0); PG8_BAR; PG8_MMA(0, 0, At, B0); PG8_MMA(0, 1, At, B1); PG8_BAR; PG8_SCHED;
;             PG8_LDA(At, 1, 1); PG8_STAGE(PG8_SB(1, 0), b3, voffB); PG8_STAGE(PG8_SB(1, 1), b3 + hstep, voffB); PG8_STAGE(PG8_SA(1, 0), a3, voffA);
;             PG8_WAIT_V(8); PG8_WAIT_L(0); PG8_BAR; PG8_MMA(1, 0, At, B0); PG8_MMA(1, 1, At, B1); PG8_BAR; PG8_SCHED;
.LBB0_137:
	s_add_u32 s16, s10, s14
	s_addc_u32 s17, s11, s15
	s_add_u32 s16, s16, 0x100
	s_addc_u32 s17, s17, 0
	s_add_u32 s52, s49, s14
	s_addc_u32 s53, s50, s15
	s_add_i32 s54, 0, 0x10000
	s_cmpk_eq_i32 s14, 0x1500
	s_cselect_b32 s19, s13, s17
	s_cselect_b32 s18, s12, s16
	v_add_u32_e32 v147, s54, v145
	s_cselect_b32 s17, s5, s53
	s_cselect_b32 s16, s4, s52
	s_add_i32 s55, 0, 0x14000
	ds_read_b128 v[148:151], v147
	ds_read_b128 v[152:155], v147 offset:1024
	ds_read_b128 v[160:163], v147 offset:2048
	ds_read_b128 v[164:167], v147 offset:3072
	v_add_u32_e32 v147, s55, v145
	ds_read_b128 v[168:171], v147
	ds_read_b128 v[172:175], v147 offset:1024
	ds_read_b128 v[176:179], v147 offset:2048
	ds_read_b128 v[180:183], v147 offset:3072
	v_lshl_add_u64 v[156:157], v[142:143], 0, s[14:15]
	s_add_i32 m0, s29, 0xc000
	ds_read_b128 v[184:187], v146
	ds_read_b128 v[188:191], v146 offset:1024
	ds_read_b128 v[192:195], v146 offset:2048
	ds_read_b128 v[196:199], v146 offset:3072
	ds_read_b128 v[200:203], v146 offset:4096
	ds_read_b128 v[206:209], v146 offset:5120
	ds_read_b128 v[214:217], v146 offset:6144
	ds_read_b128 v[218:221], v146 offset:7168
	global_load_lds_dwordx4 v[156:157], off
	v_lshl_add_u64 v[156:157], v[140:141], 0, s[14:15]
	s_add_i32 m0, s29, 0xe000
	s_nop 0
	global_load_lds_dwordx4 v[156:157], off
	s_waitcnt vmcnt(8)
	s_waitcnt lgkmcnt(0)
	s_setprio 1
	s_barrier
	v_mfma_f32_16x16x32_bf16 v[32:35], v[148:151], v[184:187], v[32:35]
	v_mfma_f32_16x16x32_bf16 v[36:39], v[160:163], v[184:187], v[36:39]
	v_mfma_f32_16x16x32_bf16 v[48:51], v[148:151], v[192:195], v[48:51]
	v_mfma_f32_16x16x32_bf16 v[52:55], v[160:163], v[192:195], v[52:55]
	v_mfma_f32_16x16x32_bf16 v[56:59], v[148:151], v[200:203], v[56:59]
	v_mfma_f32_16x16x32_bf16 v[60:63], v[160:163], v[200:203], v[60:63]
	v_mfma_f32_16x16x32_bf16 v[74:77], v[148:151], v[214:217], v[74:77]
	v_mfma_f32_16x16x32_bf16 v[78:81], v[160:163], v[214:217], v[78:81]
	v_mfma_f32_16x16x32_bf16 v[32:35], v[152:155], v[188:191], v[32:35]
	v_mfma_f32_16x16x32_bf16 v[36:39], v[164:167], v[188:191], v[36:39]
	v_mfma_f32_16x16x32_bf16 v[48:51], v[152:155], v[196:199], v[48:51]
	v_mfma_f32_16x16x32_bf16 v[52:55], v[164:167], v[196:199], v[52:55]
	v_mfma_f32_16x16x32_bf16 v[56:59], v[152:155], v[206:209], v[56:59]
	v_mfma_f32_16x16x32_bf16 v[60:63], v[164:167], v[206:209], v[60:63]
	v_mfma_f32_16x16x32_bf16 v[74:77], v[152:155], v[218:221], v[74:77]
	v_mfma_f32_16x16x32_bf16 v[78:81], v[164:167], v[218:221], v[78:81]
	v_mfma_f32_16x16x32_bf16 v[106:109], v[168:171], v[184:187], v[106:109]
	v_mfma_f32_16x16x32_bf16 v[110:113], v[176:179], v[184:187], v[110:113]
	v_mfma_f32_16x16x32_bf16 v[102:105], v[168:171], v[192:195], v[102:105]
	v_mfma_f32_16x16x32_bf16 v[98:101], v[176:179], v[192:195], v[98:101]
	v_mfma_f32_16x16x32_bf16 v[70:73], v[168:171], v[200:203], v[70:73]
	v_mfma_f32_16x16x32_bf16 v[66:69], v[176:179], v[200:203], v[66:69]
	v_mfma_f32_16x16x32_bf16 v[44:47], v[168:171], v[214:217], v[44:47]
	v_mfma_f32_16x16x32_bf16 v[40:43], v[176:179], v[214:217], v[40:43]
	v_mfma_f32_16x16x32_bf16 v[106:109], v[172:175], v[188:191], v[106:109]
	v_mfma_f32_16x16x32_bf16 v[110:113], v[180:183], v[188:191], v[110:113]
	v_mfma_f32_16x16x32_bf16 v[102:105], v[172:175], v[196:199], v[102:105]
	v_mfma_f32_16x16x32_bf16 v[98:101], v[180:183], v[196:199], v[98:101]
	v_mfma_f32_16x16x32_bf16 v[70:73], v[172:175], v[206:209], v[70:73]
	v_mfma_f32_16x16x32_bf16 v[66:69], v[180:183], v[206:209], v[66:69]
	v_mfma_f32_16x16x32_bf16 v[44:47], v[172:175], v[218:221], v[44:47]
	v_mfma_f32_16x16x32_bf16 v[40:43], v[180:183], v[218:221], v[40:43]
	s_barrier
	s_setprio 0
	s_add_i32 s52, s54, s28
	v_lshl_add_u64 v[156:157], s[16:17], 0, v[64:65]
	s_mov_b32 m0, s52
	ds_read_b128 v[184:187], v146 offset:16384
	ds_read_b128 v[188:191], v146 offset:17408
	ds_read_b128 v[192:195], v146 offset:18432
	ds_read_b128 v[196:199], v146 offset:19456
	ds_read_b128 v[200:203], v146 offset:20480
	ds_read_b128 v[206:209], v146 offset:21504
	ds_read_b128 v[214:217], v146 offset:22528
	ds_read_b128 v[218:221], v146 offset:23552
	global_load_lds_dwordx4 v[156:157], off
	s_add_i32 m0, s52, 0x2000
	s_add_u32 s52, s16, 0xb0000
	v_lshl_add_u64 v[210:211], s[16:17], 0, v[130:131]
	s_addc_u32 s53, s17, 0
	s_add_i32 s54, s55, s28
	global_load_lds_dwordx4 v[210:211], off
	v_lshl_add_u64 v[222:223], s[52:53], 0, v[64:65]
	s_mov_b32 m0, s54
	v_lshl_add_u64 v[224:225], s[18:19], 0, v[132:133]
	global_load_lds_dwordx4 v[222:223], off
	v_lshl_add_u64 v[222:223], s[52:53], 0, v[130:131]
	s_add_i32 m0, s54, 0x2000
	s_nop 0
	global_load_lds_dwordx4 v[222:223], off
	v_lshl_add_u64 v[222:223], s[18:19], 0, v[134:135]
	s_mov_b32 m0, s29
	s_nop 0
	global_load_lds_dwordx4 v[222:223], off
	s_mov_b32 m0, s30
	s_nop 0
	global_load_lds_dwordx4 v[224:225], off
	s_waitcnt vmcnt(8)
	s_waitcnt lgkmcnt(0)
	s_setprio 1
	s_barrier
; #define PG8_STAGE(bufoff, gbase, voff) do { _Pragma("unroll") for (int _i = 0; _i < 2; ++_i) \
;         __builtin_amdgcn_global_load_lds((const unsigned*)((const char*)(gbase) + (voff)[_i]), (PG8_LAS unsigned*)(lds + (bufoff) + ldsw + _i * 8192), 16, 0, 0); } while (0)
; #define PG8_LDA(dst, b, h) do { _Pragma("unroll") for (int m = 0; m < 4; ++m) _Pragma("unroll") for (int k = 0; k < 2; ++k) dst[m][k] = *(const PG8_LAS bf16x8*)(lds + PG8_SA(b, h) + aoff + m * 2048 + k * 1024); } while (0)
; #define PG8_LDB(dst, b, h) do { _Pragma("unroll") for (int n = 0; n < 2; ++n) _Pragma("unroll") for (int k = 0; k < 2; ++k) dst[n][k] = *(const PG8_LAS bf16x8*)(lds + PG8_SB(b, h) + boff + n * 2048 + k * 1024); } while (0)
; #define PG8_MMA(ai, bj, At, Bt) do { __builtin_amdgcn_s_setprio(1); _Pragma("unroll") for (int m = 0; m < 4; ++m) _Pragma("unroll") for (int n = 0; n < 2; ++n) _Pragma("unroll") for (int k = 0; k < 2; ++k) \
;         acc[ai][bj][m][n] = __builtin_amdgcn_mfma_f32_16x16x32_bf16(Bt[n][k], At[m][k], acc[ai][bj][m][n], 0, 0, 0); __builtin_amdgcn_s_setprio(0); } while (0)
; #define PG8_WAIT_V(n) asm volatile("s_waitcnt vmcnt(" #n ")" ::: "memory")
; #define PG8_WAIT_L(n) asm volatile("s_waitcnt lgkmcnt(" #n ")" ::: "memory")
; #define PG8_BAR __builtin_amdgcn_s_barrier()
; #define PG8_SCHED __builtin_amdgcn_sched_barrier(0)
; template <class Epi, class Sched, bool ALIGN_EPI = false, bool SP2 = false>
; __device__ __forceinline__ void gemm_phase(PG8_LAS unsigned char* lds, const Gemm g, const Sched& S, const Epi& E, const int tid) {
;     ...
;             PG8_WAIT_V(8); PG8_WAIT_L(0); PG8_BAR; PG8_MMA(1, 0, At, B0); PG8_MMA(1, 1, At, B1); PG8_BAR; PG8_SCHED;
;             PG8_LDB(B0, 1, 0); PG8_LDB(B1, 1, 1); PG8_SCHED; PG8_LDA(At, 1, 0); PG8_STAGE(PG8_SA(0, 1), a2 + hstep, voffA);
;             PG8_WAIT_V(8); PG8_WAIT_L(0); PG8_BAR; PG8_MMA(0, 0, At, B0); PG8_MMA(0, 1, At, B1); PG8_BAR; PG8_SCHED;
	v_mfma_f32_16x16x32_bf16 v[82:85], v[148:151], v[184:187], v[82:85]
	v_mfma_f32_16x16x32_bf16 v[86:89], v[160:163], v[184:187], v[86:89]
	v_mfma_f32_16x16x32_bf16 v[90:93], v[148:151], v[192:195], v[90:93]
	v_mfma_f32_16x16x32_bf16 v[94:97], v[160:163], v[192:195], v[94:97]
	v_mfma_f32_16x16x32_bf16 v[114:117], v[148:151], v[200:203], v[114:117]
	v_mfma_f32_16x16x32_bf16 v[118:121], v[160:163], v[200:203], v[118:121]
	v_mfma_f32_16x16x32_bf16 v[122:125], v[148:151], v[214:217], v[122:125]
	v_mfma_f32_16x16x32_bf16 v[126:129], v[160:163], v[214:217], v[126:129]
	v_mfma_f32_16x16x32_bf16 v[82:85], v[152:155], v[188:191], v[82:85]
	v_mfma_f32_16x16x32_bf16 v[86:89], v[164:167], v[188:191], v[86:89]
	v_mfma_f32_16x16x32_bf16 v[90:93], v[152:155], v[196:199], v[90:93]
	v_mfma_f32_16x16x32_bf16 v[94:97], v[164:167], v[196:199], v[94:97]
	v_mfma_f32_16x16x32_bf16 v[114:117], v[152:155], v[206:209], v[114:117]
	v_mfma_f32_16x16x32_bf16 v[118:121], v[164:167], v[206:209], v[118:121]
	v_mfma_f32_16x16x32_bf16 v[122:125], v[152:155], v[218:221], v[122:125]
	v_mfma_f32_16x16x32_bf16 v[126:129], v[164:167], v[218:221], v[126:129]
	v_mfma_f32_16x16x32_bf16 v[28:31], v[168:171], v[184:187], v[28:31]
	v_mfma_f32_16x16x32_bf16 v[24:27], v[176:179], v[184:187], v[24:27]
	v_mfma_f32_16x16x32_bf16 v[20:23], v[168:171], v[192:195], v[20:23]
	v_mfma_f32_16x16x32_bf16 v[16:19], v[176:179], v[192:195], v[16:19]
	v_mfma_f32_16x16x32_bf16 v[12:15], v[168:171], v[200:203], v[12:15]
	v_mfma_f32_16x16x32_bf16 v[8:11], v[176:179], v[200:203], v[8:11]
	v_mfma_f32_16x16x32_bf16 v[4:7], v[168:171], v[214:217], v[4:7]
	v_mfma_f32_16x16x32_bf16 v[0:3], v[176:179], v[214:217], v[0:3]
	v_mfma_f32_16x16x32_bf16 v[28:31], v[172:175], v[188:191], v[28:31]
	v_mfma_f32_16x16x32_bf16 v[24:27], v[180:183], v[188:191], v[24:27]
	v_mfma_f32_16x16x32_bf16 v[20:23], v[172:175], v[196:199], v[20:23]
	v_mfma_f32_16x16x32_bf16 v[16:19], v[180:183], v[196:199], v[16:19]
	v_mfma_f32_16x16x32_bf16 v[12:15], v[172:175], v[206:209], v[12:15]
	v_mfma_f32_16x16x32_bf16 v[8:11], v[180:183], v[206:209], v[8:11]
	v_mfma_f32_16x16x32_bf16 v[4:7], v[172:175], v[218:221], v[4:7]
	v_mfma_f32_16x16x32_bf16 v[0:3], v[180:183], v[218:221], v[0:3]
	s_barrier
	s_setprio 0
	s_add_i32 s52, 0, 0x18000
	v_add_u32_e32 v147, s52, v145
	s_add_i32 s53, 0, 0x1c000
	ds_read_b128 v[148:151], v147
	ds_read_b128 v[152:155], v147 offset:1024
	ds_read_b128 v[160:163], v147 offset:2048
	ds_read_b128 v[164:167], v147 offset:3072
	v_add_u32_e32 v147, s53, v145
	ds_read_b128 v[168:171], v147
	ds_read_b128 v[172:175], v147 offset:1024
	ds_read_b128 v[176:179], v147 offset:2048
	ds_read_b128 v[180:183], v147 offset:3072
	s_add_u32 s18, s18, 0xb0000
	s_addc_u32 s19, s19, 0
	s_mov_b32 m0, s31
	v_lshl_add_u64 v[226:227], s[18:19], 0, v[134:135]
	ds_read_b128 v[184:187], v146 offset:32768
	ds_read_b128 v[188:191], v146 offset:33792
	ds_read_b128 v[192:195], v146 offset:34816
	ds_read_b128 v[196:199], v146 offset:35840
	ds_read_b128 v[200:203], v146 offset:36864
	ds_read_b128 v[206:209], v146 offset:37888
	ds_read_b128 v[214:217], v146 offset:38912
	ds_read_b128 v[218:221], v146 offset:39936
	global_load_lds_dwordx4 v[226:227], off
	v_lshl_add_u64 v[226:227], s[18:19], 0, v[132:133]
	s_mov_b32 m0, s34
	s_nop 0
	global_load_lds_dwordx4 v[226:227], off
	s_waitcnt vmcnt(8)
	s_waitcnt lgkmcnt(0)
	s_setprio 1
	s_barrier
	v_mfma_f32_16x16x32_bf16 v[32:35], v[148:151], v[184:187], v[32:35]
	v_mfma_f32_16x16x32_bf16 v[36:39], v[160:163], v[184:187], v[36:39]
	v_mfma_f32_16x16x32_bf16 v[48:51], v[148:151], v[192:195], v[48:51]
	v_mfma_f32_16x16x32_bf16 v[52:55], v[160:163], v[192:195], v[52:55]
	v_mfma_f32_16x16x32_bf16 v[56:59], v[148:151], v[200:203], v[56:59]
	v_mfma_f32_16x16x32_bf16 v[60:63], v[160:163], v[200:203], v[60:63]
	v_mfma_f32_16x16x32_bf16 v[74:77], v[148:151], v[214:217], v[74:77]
	v_mfma_f32_16x16x32_bf16 v[78:81], v[160:163], v[214:217], v[78:81]
	v_mfma_f32_16x16x32_bf16 v[32:35], v[152:155], v[188:191], v[32:35]
	v_mfma_f32_16x16x32_bf16 v[36:39], v[164:167], v[188:191], v[36:39]
	v_mfma_f32_16x16x32_bf16 v[48:51], v[152:155], v[196:199], v[48:51]
	v_mfma_f32_16x16x32_bf16 v[52:55], v[164:167], v[196:199], v[52:55]
	v_mfma_f32_16x16x32_bf16 v[56:59], v[152:155], v[206:209], v[56:59]
	v_mfma_f32_16x16x32_bf16 v[60:63], v[164:167], v[206:209], v[60:63]
	v_mfma_f32_16x16x32_bf16 v[74:77], v[152:155], v[218:221], v[74:77]
	v_mfma_f32_16x16x32_bf16 v[78:81], v[164:167], v[218:221], v[78:81]
	v_mfma_f32_16x16x32_bf16 v[106:109], v[168:171], v[184:187], v[106:109]
	v_mfma_f32_16x16x32_bf16 v[110:113], v[176:179], v[184:187], v[110:113]
	v_mfma_f32_16x16x32_bf16 v[102:105], v[168:171], v[192:195], v[102:105]
	v_mfma_f32_16x16x32_bf16 v[98:101], v[176:179], v[192:195], v[98:101]
	v_mfma_f32_16x16x32_bf16 v[70:73], v[168:171], v[200:203], v[70:73]
	v_mfma_f32_16x16x32_bf16 v[66:69], v[176:179], v[200:203], v[66:69]
	v_mfma_f32_16x16x32_bf16 v[44:47], v[168:171], v[214:217], v[44:47]
	v_mfma_f32_16x16x32_bf16 v[40:43], v[176:179], v[214:217], v[40:43]
	v_mfma_f32_16x16x32_bf16 v[106:109], v[172:175], v[188:191], v[106:109]
	v_mfma_f32_16x16x32_bf16 v[110:113], v[180:183], v[188:191], v[110:113]
	v_mfma_f32_16x16x32_bf16 v[102:105], v[172:175], v[196:199], v[102:105]
	v_mfma_f32_16x16x32_bf16 v[98:101], v[180:183], v[196:199], v[98:101]
	v_mfma_f32_16x16x32_bf16 v[70:73], v[172:175], v[206:209], v[70:73]
	v_mfma_f32_16x16x32_bf16 v[66:69], v[180:183], v[206:209], v[66:69]
	v_mfma_f32_16x16x32_bf16 v[44:47], v[172:175], v[218:221], v[44:47]
	v_mfma_f32_16x16x32_bf16 v[40:43], v[180:183], v[218:221], v[40:43]
	s_barrier
; #define PG8_STAGE(bufoff, gbase, voff) do { _Pragma("unroll") for (int _i = 0; _i < 2; ++_i) \
;         __builtin_amdgcn_global_load_lds((const unsigned*)((const char*)(gbase) + (voff)[_i]), (PG8_LAS unsigned*)(lds + (bufoff) + ldsw + _i * 8192), 16, 0, 0); } while (0)
; #define PG8_LDA(dst, b, h) do { _Pragma("unroll") for (int m = 0; m < 4; ++m) _Pragma("unroll") for (int k = 0; k < 2; ++k) dst[m][k] = *(const PG8_LAS bf16x8*)(lds + PG8_SA(b, h) + aoff + m * 2048 + k * 1024); } while (0)
; #define PG8_MMA(ai, bj, At, Bt) do { __builtin_amdgcn_s_setprio(1); _Pragma("unroll") for (int m = 0; m < 4; ++m) _Pragma("unroll") for (int n = 0; n < 2; ++n) _Pragma("unroll") for (int k = 0; k < 2; ++k) \
;         acc[ai][bj][m][n] = __builtin_amdgcn_mfma_f32_16x16x32_bf16(Bt[n][k], At[m][k], acc[ai][bj][m][n], 0, 0, 0); __builtin_amdgcn_s_setprio(0); } while (0)
; #define PG8_WAIT_V(n) asm volatile("s_waitcnt vmcnt(" #n ")" ::: "memory")
; #define PG8_WAIT_L(n) asm volatile("s_waitcnt lgkmcnt(" #n ")" ::: "memory")
; #define PG8_BAR __builtin_amdgcn_s_barrier()
; #define PG8_SCHED __builtin_amdgcn_sched_barrier(0)
; template <class Epi, class Sched, bool ALIGN_EPI = false, bool SP2 = false>
; __device__ __forceinline__ void gemm_phase(PG8_LAS unsigned char* lds, const Gemm g, const Sched& S, const Epi& E, const int tid) {
;     ...
;             PG8_LDA(At, 1, 1); PG8_STAGE(PG8_SB(1, 0), b3, voffB); PG8_STAGE(PG8_SB(1, 1), b3 + hstep, voffB); PG8_STAGE(PG8_SA(1, 0), a3, voffA);
;             PG8_WAIT_V(8); PG8_WAIT_L(0); PG8_BAR; PG8_MMA(1, 0, At, B0); PG8_MMA(1, 1, At, B1); PG8_BAR; PG8_SCHED;
;     ...
;         if (!has_next) break;
; #pragma unroll
;         for (int a = 0; a < 2; ++a)
; #pragma unroll
;             for (int b = 0; b < 2; ++b)
; #pragma unroll
;                 for (int m = 0; m < 4; ++m)
; #pragma unroll
;                     for (int n = 0; n < 2; ++n) acc[a][b][m][n] = (f32x4){0.f, 0.f, 0.f, 0.f};
;         cur = nxt; cA = nA; cB = nB; ++ui;
	s_setprio 0
	s_add_i32 s18, s52, s28
	v_lshl_add_u64 v[156:157], v[156:157], 0, s[94:95]
	s_mov_b32 m0, s18
	ds_read_b128 v[184:187], v146 offset:49152
	ds_read_b128 v[188:191], v146 offset:50176
	ds_read_b128 v[192:195], v146 offset:51200
	ds_read_b128 v[196:199], v146 offset:52224
	ds_read_b128 v[200:203], v146 offset:53248
	ds_read_b128 v[206:209], v146 offset:54272
	ds_read_b128 v[214:217], v146 offset:55296
	ds_read_b128 v[218:221], v146 offset:56320
	global_load_lds_dwordx4 v[156:157], off
	s_add_i32 m0, s18, 0x2000
	s_add_u32 s16, s16, 0xb0080
	v_lshl_add_u64 v[156:157], v[210:211], 0, s[94:95]
	s_addc_u32 s17, s17, 0
	s_add_i32 s18, s53, s28
	global_load_lds_dwordx4 v[156:157], off
	v_lshl_add_u64 v[156:157], s[16:17], 0, v[64:65]
	s_mov_b32 m0, s18
	s_nop 0
	global_load_lds_dwordx4 v[156:157], off
	v_lshl_add_u64 v[156:157], s[16:17], 0, v[130:131]
	s_add_i32 m0, s18, 0x2000
	s_nop 0
	global_load_lds_dwordx4 v[156:157], off
	v_lshl_add_u64 v[156:157], v[222:223], 0, s[94:95]
	s_mov_b32 m0, s42
	s_nop 0
	global_load_lds_dwordx4 v[156:157], off
	v_lshl_add_u64 v[156:157], v[224:225], 0, s[94:95]
	s_mov_b32 m0, s44
	s_nop 0
	global_load_lds_dwordx4 v[156:157], off
	s_waitcnt vmcnt(8)
	s_waitcnt lgkmcnt(0)
	s_setprio 1
	s_barrier
	v_mfma_f32_16x16x32_bf16 v[82:85], v[148:151], v[184:187], v[82:85]
	v_mfma_f32_16x16x32_bf16 v[86:89], v[160:163], v[184:187], v[86:89]
	v_mfma_f32_16x16x32_bf16 v[90:93], v[148:151], v[192:195], v[90:93]
	v_mfma_f32_16x16x32_bf16 v[94:97], v[160:163], v[192:195], v[94:97]
	v_mfma_f32_16x16x32_bf16 v[114:117], v[148:151], v[200:203], v[114:117]
	v_mfma_f32_16x16x32_bf16 v[118:121], v[160:163], v[200:203], v[118:121]
	v_mfma_f32_16x16x32_bf16 v[122:125], v[148:151], v[214:217], v[122:125]
	v_mfma_f32_16x16x32_bf16 v[126:129], v[160:163], v[214:217], v[126:129]
	v_mfma_f32_16x16x32_bf16 v[82:85], v[152:155], v[188:191], v[82:85]
	v_mfma_f32_16x16x32_bf16 v[86:89], v[164:167], v[188:191], v[86:89]
	v_mfma_f32_16x16x32_bf16 v[90:93], v[152:155], v[196:199], v[90:93]
	v_mfma_f32_16x16x32_bf16 v[94:97], v[164:167], v[196:199], v[94:97]
	v_mfma_f32_16x16x32_bf16 v[114:117], v[152:155], v[206:209], v[114:117]
	v_mfma_f32_16x16x32_bf16 v[118:121], v[164:167], v[206:209], v[118:121]
	v_mfma_f32_16x16x32_bf16 v[122:125], v[152:155], v[218:221], v[122:125]
	v_mfma_f32_16x16x32_bf16 v[126:129], v[164:167], v[218:221], v[126:129]
	v_mfma_f32_16x16x32_bf16 v[28:31], v[168:171], v[184:187], v[28:31]
	v_mfma_f32_16x16x32_bf16 v[24:27], v[176:179], v[184:187], v[24:27]
	v_mfma_f32_16x16x32_bf16 v[20:23], v[168:171], v[192:195], v[20:23]
	v_mfma_f32_16x16x32_bf16 v[16:19], v[176:179], v[192:195], v[16:19]
	v_mfma_f32_16x16x32_bf16 v[12:15], v[168:171], v[200:203], v[12:15]
	v_mfma_f32_16x16x32_bf16 v[8:11], v[176:179], v[200:203], v[8:11]
	v_mfma_f32_16x16x32_bf16 v[4:7], v[168:171], v[214:217], v[4:7]
	v_mfma_f32_16x16x32_bf16 v[0:3], v[176:179], v[214:217], v[0:3]
	v_mfma_f32_16x16x32_bf16 v[28:31], v[172:175], v[188:191], v[28:31]
	v_mfma_f32_16x16x32_bf16 v[24:27], v[180:183], v[188:191], v[24:27]
	v_mfma_f32_16x16x32_bf16 v[20:23], v[172:175], v[196:199], v[20:23]
	v_mfma_f32_16x16x32_bf16 v[16:19], v[180:183], v[196:199], v[16:19]
	v_mfma_f32_16x16x32_bf16 v[12:15], v[172:175], v[206:209], v[12:15]
	v_mfma_f32_16x16x32_bf16 v[8:11], v[180:183], v[206:209], v[8:11]
	v_mfma_f32_16x16x32_bf16 v[4:7], v[172:175], v[218:221], v[4:7]
	v_mfma_f32_16x16x32_bf16 v[0:3], v[180:183], v[218:221], v[0:3]
	s_barrier
	s_setprio 0
	s_add_i32 s51, s51, 2
	s_add_u32 s14, s14, 0x100
	s_addc_u32 s15, s15, 0
	s_cmp_gt_u32 s51, 41
	s_cbranch_scc0 .LBB0_137
	s_add_u32 s14, s49, 0xffffff00
	s_addc_u32 s15, s50, -1
	s_and_b64 vcc, exec, s[2:3]
	s_cbranch_vccnz .LBB0_140
	v_mov_b32_e32 v0, 0
	s_mov_b32 s8, s46
	s_mov_b32 s22, s47
	s_mov_b64 s[10:11], s[12:13]
	s_mov_b32 s45, s48
	v_mov_b32_e32 v1, v0
	v_mov_b32_e32 v2, v0
	v_mov_b32_e32 v3, v0
	v_mov_b32_e32 v4, v0
	v_mov_b32_e32 v5, v0
	v_mov_b32_e32 v6, v0
	v_mov_b32_e32 v7, v0
	v_mov_b32_e32 v8, v0
	v_mov_b32_e32 v9, v0
	v_mov_b32_e32 v10, v0
	v_mov_b32_e32 v11, v0
	v_mov_b32_e32 v12, v0
	v_mov_b32_e32 v13, v0
	v_mov_b32_e32 v14, v0
	v_mov_b32_e32 v15, v0
	v_mov_b32_e32 v16, v0
	v_mov_b32_e32 v17, v0
	v_mov_b32_e32 v18, v0
	v_mov_b32_e32 v19, v0
	v_mov_b32_e32 v20, v0
	v_mov_b32_e32 v21, v0
	v_mov_b32_e32 v22, v0
	v_mov_b32_e32 v23, v0
	v_mov_b32_e32 v24, v0
	v_mov_b32_e32 v25, v0
	v_mov_b32_e32 v26, v0
	v_mov_b32_e32 v27, v0
	v_mov_b32_e32 v28, v0
	v_mov_b32_e32 v29, v0
	v_mov_b32_e32 v30, v0
	v_mov_b32_e32 v31, v0
	v_mov_b32_e32 v126, v0
	v_mov_b32_e32 v127, v0
	v_mov_b32_e32 v128, v0
	v_mov_b32_e32 v129, v0
	v_mov_b32_e32 v122, v0
	v_mov_b32_e32 v123, v0
	v_mov_b32_e32 v124, v0
	v_mov_b32_e32 v125, v0
	v_mov_b32_e32 v118, v0
	v_mov_b32_e32 v119, v0
	v_mov_b32_e32 v120, v0
	v_mov_b32_e32 v121, v0
	v_mov_b32_e32 v114, v0
	v_mov_b32_e32 v115, v0
	v_mov_b32_e32 v116, v0
	v_mov_b32_e32 v117, v0
	v_mov_b32_e32 v94, v0
	v_mov_b32_e32 v95, v0
	v_mov_b32_e32 v96, v0
	v_mov_b32_e32 v97, v0
	v_mov_b32_e32 v90, v0
	v_mov_b32_e32 v91, v0
	v_mov_b32_e32 v92, v0
	v_mov_b32_e32 v93, v0
	v_mov_b32_e32 v86, v0
	v_mov_b32_e32 v87, v0
	v_mov_b32_e32 v88, v0
	v_mov_b32_e32 v89, v0
	v_mov_b32_e32 v82, v0
	v_mov_b32_e32 v83, v0
	v_mov_b32_e32 v84, v0
	v_mov_b32_e32 v85, v0
	v_mov_b32_e32 v40, v0
	v_mov_b32_e32 v41, v0
	v_mov_b32_e32 v42, v0
	v_mov_b32_e32 v43, v0
	v_mov_b32_e32 v44, v0
	v_mov_b32_e32 v45, v0
	v_mov_b32_e32 v46, v0
	v_mov_b32_e32 v47, v0
	v_mov_b32_e32 v66, v0
	v_mov_b32_e32 v67, v0
	v_mov_b32_e32 v68, v0
	v_mov_b32_e32 v69, v0
	v_mov_b32_e32 v70, v0
	v_mov_b32_e32 v71, v0
	v_mov_b32_e32 v72, v0
	v_mov_b32_e32 v73, v0
	v_mov_b32_e32 v98, v0
	v_mov_b32_e32 v99, v0
	v_mov_b32_e32 v100, v0
	v_mov_b32_e32 v101, v0
	v_mov_b32_e32 v102, v0
	v_mov_b32_e32 v103, v0
	v_mov_b32_e32 v104, v0
	v_mov_b32_e32 v105, v0
	v_mov_b32_e32 v110, v0
	v_mov_b32_e32 v111, v0
	v_mov_b32_e32 v112, v0
	v_mov_b32_e32 v113, v0
	v_mov_b32_e32 v106, v0
	v_mov_b32_e32 v107, v0
	v_mov_b32_e32 v108, v0
	v_mov_b32_e32 v109, v0
	v_mov_b32_e32 v78, v0
	v_mov_b32_e32 v79, v0
	v_mov_b32_e32 v80, v0
	v_mov_b32_e32 v81, v0
	v_mov_b32_e32 v74, v0
	v_mov_b32_e32 v75, v0
	v_mov_b32_e32 v76, v0
	v_mov_b32_e32 v77, v0
	v_mov_b32_e32 v60, v0
	v_mov_b32_e32 v61, v0
	v_mov_b32_e32 v62, v0
	v_mov_b32_e32 v63, v0
	v_mov_b32_e32 v56, v0
	v_mov_b32_e32 v57, v0
	v_mov_b32_e32 v58, v0
	v_mov_b32_e32 v59, v0
	v_mov_b32_e32 v52, v0
	v_mov_b32_e32 v53, v0
	v_mov_b32_e32 v54, v0
	v_mov_b32_e32 v55, v0
	v_mov_b32_e32 v48, v0
	v_mov_b32_e32 v49, v0
	v_mov_b32_e32 v50, v0
	v_mov_b32_e32 v51, v0
	v_mov_b32_e32 v36, v0
	v_mov_b32_e32 v37, v0
	v_mov_b32_e32 v38, v0
	v_mov_b32_e32 v39, v0
	v_mov_b32_e32 v32, v0
	v_mov_b32_e32 v33, v0
	v_mov_b32_e32 v34, v0
	v_mov_b32_e32 v35, v0
	s_andn2_b64 vcc, exec, s[0:1]
	s_cbranch_vccnz .LBB0_141
	s_branch .LBB0_142

; #define PG8_STAGE(bufoff, gbase, voff) do { _Pragma("unroll") for (int _i = 0; _i < 2; ++_i) \
;         __builtin_amdgcn_global_load_lds((const unsigned*)((const char*)(gbase) + (voff)[_i]), (PG8_LAS unsigned*)(lds + (bufoff) + ldsw + _i * 8192), 16, 0, 0); } while (0)
; #define PG8_LDA(dst, b, h) do { _Pragma("unroll") for (int m = 0; m < 4; ++m) _Pragma("unroll") for (int k = 0; k < 2; ++k) dst[m][k] = *(const PG8_LAS bf16x8*)(lds + PG8_SA(b, h) + aoff + m * 2048 + k * 1024); } while (0)
; #define PG8_LDB(dst, b, h) do { _Pragma("unroll") for (int n = 0; n < 2; ++n) _Pragma("unroll") for (int k = 0; k < 2; ++k) dst[n][k] = *(const PG8_LAS bf16x8*)(lds + PG8_SB(b, h) + boff + n * 2048 + k * 1024); } while (0)
; #define PG8_MMA(ai, bj, At, Bt) do { __builtin_amdgcn_s_setprio(1); _Pragma("unroll") for (int m = 0; m < 4; ++m) _Pragma("unroll") for (int n = 0; n < 2; ++n) _Pragma("unroll") for (int k = 0; k < 2; ++k) \
;         acc[ai][bj][m][n] = __builtin_amdgcn_mfma_f32_16x16x32_bf16(Bt[n][k], At[m][k], acc[ai][bj][m][n], 0, 0, 0); __builtin_amdgcn_s_setprio(0); } while (0)
; #define PG8_WAIT_V(n) asm volatile("s_waitcnt vmcnt(" #n ")" ::: "memory")
; #define PG8_BAR __builtin_amdgcn_s_barrier()
; template <class Epi, class Sched, bool ALIGN_EPI = false, bool SP2 = false>
; __device__ __forceinline__ void gemm_phase(PG8_LAS unsigned char* lds, const Gemm g, const Sched& S, const Epi& E, const int tid) {
;     ...
;         for (int t = 0; t < nt; t += 2) {
;             const bool last = (t == nt - 2);
;             const char* a1 = cA + (size_t)(t + 1) * kstep;
;             const char* a2 = last ? nA : cA + (size_t)(t + 2) * kstep; const char* b2 = last ? nB : cB + (size_t)(t + 2) * kstep;
;             const char* a3 = a2 + kstep; const char* b3 = b2 + kstep;
;             if (last && has_next) S.a_ready(nxt);
;             if constexpr (SP2) {
;             PG8_LDB(B0, 0, 0); PG8_LDB(B1, 0, 1); PG8_SCHED; PG8_LDA(At, 0, 0); PG8_STAGE(PG8_SA(1, 1), a1 + hstep, voffA);
;             PG8_WAIT_V(8); PG8_WAIT_L(0); PG8_BAR; PG8_MMA(0, 0, At, B0); PG8_MMA(0, 1, At, B1); PG8_BAR; PG8_SCHED;
;             PG8_LDA(At, 0, 1); PG8_STAGE(PG8_SB(0, 0), b2, voffB); PG8_STAGE(PG8_SB(0, 1), b2 + hstep, voffB); PG8_STAGE(PG8_SA(0, 0), a2, voffA);
;             PG8_WAIT_V(8); PG8_WAIT_L(0); PG8_BAR; PG8_MMA(1, 0, At, B0); PG8_MMA(1, 1, At, B1); PG8_BAR; PG8_SCHED;
.LBB0_254:
	s_add_u32 s18, s16, 0xfffc0080
	s_addc_u32 s19, s17, -1
	s_add_i32 s48, 0, 0x10000
	s_cmp_eq_u32 s47, 12
	s_cselect_b32 s21, s11, s19
	s_cselect_b32 s20, s42, s18
	v_add_u32_e32 v64, s48, v143
	s_cselect_b32 s19, s9, s46
	s_cselect_b32 s18, s44, s45
	s_add_i32 s50, 0, 0x14000
	ds_read_b128 v[146:149], v64
	ds_read_b128 v[150:153], v64 offset:1024
	ds_read_b128 v[154:157], v64 offset:2048
	ds_read_b128 v[158:161], v64 offset:3072
	v_add_u32_e32 v64, s50, v143
	ds_read_b128 v[162:165], v64
	ds_read_b128 v[166:169], v64 offset:1024
	ds_read_b128 v[170:173], v64 offset:2048
	ds_read_b128 v[174:177], v64 offset:3072
	v_lshl_add_u64 v[202:203], s[16:17], 0, v[140:141]
	s_add_i32 m0, s25, 0xc000
	ds_read_b128 v[178:181], v145
	ds_read_b128 v[182:185], v145 offset:1024
	ds_read_b128 v[186:189], v145 offset:2048
	ds_read_b128 v[190:193], v145 offset:3072
	ds_read_b128 v[194:197], v145 offset:4096
	ds_read_b128 v[198:201], v145 offset:5120
	ds_read_b128 v[206:209], v145 offset:6144
	ds_read_b128 v[214:217], v145 offset:7168
	global_load_lds_dwordx4 v[202:203], off
	v_lshl_add_u64 v[202:203], s[16:17], 0, v[138:139]
	s_add_i32 m0, s25, 0xe000
	s_nop 0
	global_load_lds_dwordx4 v[202:203], off
	s_waitcnt vmcnt(8)
	s_waitcnt lgkmcnt(0)
	s_setprio 1
	s_barrier
	v_mfma_f32_16x16x32_bf16 v[126:129], v[146:149], v[178:181], v[126:129]
	v_mfma_f32_16x16x32_bf16 v[122:125], v[154:157], v[178:181], v[122:125]
	v_mfma_f32_16x16x32_bf16 v[110:113], v[146:149], v[186:189], v[110:113]
	v_mfma_f32_16x16x32_bf16 v[106:109], v[154:157], v[186:189], v[106:109]
	v_mfma_f32_16x16x32_bf16 v[94:97], v[146:149], v[194:197], v[94:97]
	v_mfma_f32_16x16x32_bf16 v[90:93], v[154:157], v[194:197], v[90:93]
	v_mfma_f32_16x16x32_bf16 v[78:81], v[146:149], v[206:209], v[78:81]
	v_mfma_f32_16x16x32_bf16 v[74:77], v[154:157], v[206:209], v[74:77]
	v_mfma_f32_16x16x32_bf16 v[126:129], v[150:153], v[182:185], v[126:129]
	v_mfma_f32_16x16x32_bf16 v[122:125], v[158:161], v[182:185], v[122:125]
	v_mfma_f32_16x16x32_bf16 v[110:113], v[150:153], v[190:193], v[110:113]
	v_mfma_f32_16x16x32_bf16 v[106:109], v[158:161], v[190:193], v[106:109]
	v_mfma_f32_16x16x32_bf16 v[94:97], v[150:153], v[198:201], v[94:97]
	v_mfma_f32_16x16x32_bf16 v[90:93], v[158:161], v[198:201], v[90:93]
	v_mfma_f32_16x16x32_bf16 v[78:81], v[150:153], v[214:217], v[78:81]
	v_mfma_f32_16x16x32_bf16 v[74:77], v[158:161], v[214:217], v[74:77]
	v_mfma_f32_16x16x32_bf16 v[118:121], v[162:165], v[178:181], v[118:121]
	v_mfma_f32_16x16x32_bf16 v[114:117], v[170:173], v[178:181], v[114:117]
	v_mfma_f32_16x16x32_bf16 v[102:105], v[162:165], v[186:189], v[102:105]
	v_mfma_f32_16x16x32_bf16 v[98:101], v[170:173], v[186:189], v[98:101]
	v_mfma_f32_16x16x32_bf16 v[86:89], v[162:165], v[194:197], v[86:89]
	v_mfma_f32_16x16x32_bf16 v[82:85], v[170:173], v[194:197], v[82:85]
	v_mfma_f32_16x16x32_bf16 v[70:73], v[162:165], v[206:209], v[70:73]
	v_mfma_f32_16x16x32_bf16 v[66:69], v[170:173], v[206:209], v[66:69]
	v_mfma_f32_16x16x32_bf16 v[118:121], v[166:169], v[182:185], v[118:121]
	v_mfma_f32_16x16x32_bf16 v[114:117], v[174:177], v[182:185], v[114:117]
	v_mfma_f32_16x16x32_bf16 v[102:105], v[166:169], v[190:193], v[102:105]
	v_mfma_f32_16x16x32_bf16 v[98:101], v[174:177], v[190:193], v[98:101]
	v_mfma_f32_16x16x32_bf16 v[86:89], v[166:169], v[198:201], v[86:89]
	v_mfma_f32_16x16x32_bf16 v[82:85], v[174:177], v[198:201], v[82:85]
	v_mfma_f32_16x16x32_bf16 v[70:73], v[166:169], v[214:217], v[70:73]
	v_mfma_f32_16x16x32_bf16 v[66:69], v[174:177], v[214:217], v[66:69]
	s_barrier
	s_setprio 0
	s_add_i32 s48, s48, s24
	v_lshl_add_u64 v[202:203], s[18:19], 0, v[134:135]
	s_mov_b32 m0, s48
	ds_read_b128 v[178:181], v145 offset:16384
	ds_read_b128 v[182:185], v145 offset:17408
	ds_read_b128 v[186:189], v145 offset:18432
	ds_read_b128 v[190:193], v145 offset:19456
	ds_read_b128 v[194:197], v145 offset:20480
	ds_read_b128 v[198:201], v145 offset:21504
	ds_read_b128 v[206:209], v145 offset:22528
	ds_read_b128 v[214:217], v145 offset:23552
	global_load_lds_dwordx4 v[202:203], off
	s_add_i32 m0, s48, 0x2000
	s_add_u32 s48, s18, 0x40000
	v_lshl_add_u64 v[210:211], s[18:19], 0, v[130:131]
	s_addc_u32 s49, s19, 0
	s_add_i32 s50, s50, s24
	global_load_lds_dwordx4 v[210:211], off
	v_lshl_add_u64 v[218:219], s[48:49], 0, v[134:135]
	s_mov_b32 m0, s50
	v_lshl_add_u64 v[220:221], s[20:21], 0, v[132:133]
	global_load_lds_dwordx4 v[218:219], off
	v_lshl_add_u64 v[218:219], s[48:49], 0, v[130:131]
	s_add_i32 m0, s50, 0x2000
	s_nop 0
	global_load_lds_dwordx4 v[218:219], off
	v_lshl_add_u64 v[218:219], s[20:21], 0, v[136:137]
	s_mov_b32 m0, s25
	s_nop 0
	global_load_lds_dwordx4 v[218:219], off
	s_mov_b32 m0, s26
	s_nop 0
	global_load_lds_dwordx4 v[220:221], off
	s_waitcnt vmcnt(8)
	s_waitcnt lgkmcnt(0)
	s_setprio 1
	s_barrier
; #define PG8_STAGE(bufoff, gbase, voff) do { _Pragma("unroll") for (int _i = 0; _i < 2; ++_i) \
;         __builtin_amdgcn_global_load_lds((const unsigned*)((const char*)(gbase) + (voff)[_i]), (PG8_LAS unsigned*)(lds + (bufoff) + ldsw + _i * 8192), 16, 0, 0); } while (0)
; #define PG8_LDA(dst, b, h) do { _Pragma("unroll") for (int m = 0; m < 4; ++m) _Pragma("unroll") for (int k = 0; k < 2; ++k) dst[m][k] = *(const PG8_LAS bf16x8*)(lds + PG8_SA(b, h) + aoff + m * 2048 + k * 1024); } while (0)
; #define PG8_LDB(dst, b, h) do { _Pragma("unroll") for (int n = 0; n < 2; ++n) _Pragma("unroll") for (int k = 0; k < 2; ++k) dst[n][k] = *(const PG8_LAS bf16x8*)(lds + PG8_SB(b, h) + boff + n * 2048 + k * 1024); } while (0)
; #define PG8_MMA(ai, bj, At, Bt) do { __builtin_amdgcn_s_setprio(1); _Pragma("unroll") for (int m = 0; m < 4; ++m) _Pragma("unroll") for (int n = 0; n < 2; ++n) _Pragma("unroll") for (int k = 0; k < 2; ++k) \
;         acc[ai][bj][m][n] = __builtin_amdgcn_mfma_f32_16x16x32_bf16(Bt[n][k], At[m][k], acc[ai][bj][m][n], 0, 0, 0); __builtin_amdgcn_s_setprio(0); } while (0)
; #define PG8_WAIT_V(n) asm volatile("s_waitcnt vmcnt(" #n ")" ::: "memory")
; #define PG8_WAIT_L(n) asm volatile("s_waitcnt lgkmcnt(" #n ")" ::: "memory")
; #define PG8_BAR __builtin_amdgcn_s_barrier()
; #define PG8_SCHED __builtin_amdgcn_sched_barrier(0)
; template <class Epi, class Sched, bool ALIGN_EPI = false, bool SP2 = false>
; __device__ __forceinline__ void gemm_phase(PG8_LAS unsigned char* lds, const Gemm g, const Sched& S, const Epi& E, const int tid) {
;     ...
;             PG8_WAIT_V(8); PG8_WAIT_L(0); PG8_BAR; PG8_MMA(1, 0, At, B0); PG8_MMA(1, 1, At, B1); PG8_BAR; PG8_SCHED;
;             PG8_LDB(B0, 1, 0); PG8_LDB(B1, 1, 1); PG8_SCHED; PG8_LDA(At, 1, 0); PG8_STAGE(PG8_SA(0, 1), a2 + hstep, voffA);
;             PG8_WAIT_V(8); PG8_WAIT_L(0); PG8_BAR; PG8_MMA(0, 0, At, B0); PG8_MMA(0, 1, At, B1); PG8_BAR; PG8_SCHED;
	v_mfma_f32_16x16x32_bf16 v[60:63], v[146:149], v[178:181], v[60:63]
	v_mfma_f32_16x16x32_bf16 v[56:59], v[154:157], v[178:181], v[56:59]
	v_mfma_f32_16x16x32_bf16 v[44:47], v[146:149], v[186:189], v[44:47]
	v_mfma_f32_16x16x32_bf16 v[40:43], v[154:157], v[186:189], v[40:43]
	v_mfma_f32_16x16x32_bf16 v[28:31], v[146:149], v[194:197], v[28:31]
	v_mfma_f32_16x16x32_bf16 v[24:27], v[154:157], v[194:197], v[24:27]
	v_mfma_f32_16x16x32_bf16 v[12:15], v[146:149], v[206:209], v[12:15]
	v_mfma_f32_16x16x32_bf16 v[8:11], v[154:157], v[206:209], v[8:11]
	v_mfma_f32_16x16x32_bf16 v[60:63], v[150:153], v[182:185], v[60:63]
	v_mfma_f32_16x16x32_bf16 v[56:59], v[158:161], v[182:185], v[56:59]
	v_mfma_f32_16x16x32_bf16 v[44:47], v[150:153], v[190:193], v[44:47]
	v_mfma_f32_16x16x32_bf16 v[40:43], v[158:161], v[190:193], v[40:43]
	v_mfma_f32_16x16x32_bf16 v[28:31], v[150:153], v[198:201], v[28:31]
	v_mfma_f32_16x16x32_bf16 v[24:27], v[158:161], v[198:201], v[24:27]
	v_mfma_f32_16x16x32_bf16 v[12:15], v[150:153], v[214:217], v[12:15]
	v_mfma_f32_16x16x32_bf16 v[8:11], v[158:161], v[214:217], v[8:11]
	v_mfma_f32_16x16x32_bf16 v[52:55], v[162:165], v[178:181], v[52:55]
	v_mfma_f32_16x16x32_bf16 v[48:51], v[170:173], v[178:181], v[48:51]
	v_mfma_f32_16x16x32_bf16 v[36:39], v[162:165], v[186:189], v[36:39]
	v_mfma_f32_16x16x32_bf16 v[32:35], v[170:173], v[186:189], v[32:35]
	v_mfma_f32_16x16x32_bf16 v[20:23], v[162:165], v[194:197], v[20:23]
	v_mfma_f32_16x16x32_bf16 v[16:19], v[170:173], v[194:197], v[16:19]
	v_mfma_f32_16x16x32_bf16 v[4:7], v[162:165], v[206:209], v[4:7]
	v_mfma_f32_16x16x32_bf16 v[0:3], v[170:173], v[206:209], v[0:3]
	v_mfma_f32_16x16x32_bf16 v[52:55], v[166:169], v[182:185], v[52:55]
	v_mfma_f32_16x16x32_bf16 v[48:51], v[174:177], v[182:185], v[48:51]
	v_mfma_f32_16x16x32_bf16 v[36:39], v[166:169], v[190:193], v[36:39]
	v_mfma_f32_16x16x32_bf16 v[32:35], v[174:177], v[190:193], v[32:35]
	v_mfma_f32_16x16x32_bf16 v[20:23], v[166:169], v[198:201], v[20:23]
	v_mfma_f32_16x16x32_bf16 v[16:19], v[174:177], v[198:201], v[16:19]
	v_mfma_f32_16x16x32_bf16 v[4:7], v[166:169], v[214:217], v[4:7]
	v_mfma_f32_16x16x32_bf16 v[0:3], v[174:177], v[214:217], v[0:3]
	s_barrier
	s_setprio 0
	s_add_i32 s48, 0, 0x18000
	v_add_u32_e32 v64, s48, v143
	s_add_i32 s49, 0, 0x1c000
	ds_read_b128 v[146:149], v64
	ds_read_b128 v[150:153], v64 offset:1024
	ds_read_b128 v[154:157], v64 offset:2048
	ds_read_b128 v[158:161], v64 offset:3072
	v_add_u32_e32 v64, s49, v143
	ds_read_b128 v[162:165], v64
	ds_read_b128 v[166:169], v64 offset:1024
	ds_read_b128 v[170:173], v64 offset:2048
	ds_read_b128 v[174:177], v64 offset:3072
	s_add_u32 s20, s20, 0x40000
	s_addc_u32 s21, s21, 0
	s_mov_b32 m0, s27
	v_lshl_add_u64 v[222:223], s[20:21], 0, v[136:137]
	ds_read_b128 v[178:181], v145 offset:32768
	ds_read_b128 v[182:185], v145 offset:33792
	ds_read_b128 v[186:189], v145 offset:34816
	ds_read_b128 v[190:193], v145 offset:35840
	ds_read_b128 v[194:197], v145 offset:36864
	ds_read_b128 v[198:201], v145 offset:37888
	ds_read_b128 v[206:209], v145 offset:38912
	ds_read_b128 v[214:217], v145 offset:39936
	global_load_lds_dwordx4 v[222:223], off
	v_lshl_add_u64 v[222:223], s[20:21], 0, v[132:133]
	s_mov_b32 m0, s28
	s_nop 0
	global_load_lds_dwordx4 v[222:223], off
	s_waitcnt vmcnt(8)
	s_waitcnt lgkmcnt(0)
	s_setprio 1
	s_barrier
	v_mfma_f32_16x16x32_bf16 v[126:129], v[146:149], v[178:181], v[126:129]
	v_mfma_f32_16x16x32_bf16 v[122:125], v[154:157], v[178:181], v[122:125]
	v_mfma_f32_16x16x32_bf16 v[110:113], v[146:149], v[186:189], v[110:113]
	v_mfma_f32_16x16x32_bf16 v[106:109], v[154:157], v[186:189], v[106:109]
	v_mfma_f32_16x16x32_bf16 v[94:97], v[146:149], v[194:197], v[94:97]
	v_mfma_f32_16x16x32_bf16 v[90:93], v[154:157], v[194:197], v[90:93]
	v_mfma_f32_16x16x32_bf16 v[78:81], v[146:149], v[206:209], v[78:81]
	v_mfma_f32_16x16x32_bf16 v[74:77], v[154:157], v[206:209], v[74:77]
	v_mfma_f32_16x16x32_bf16 v[126:129], v[150:153], v[182:185], v[126:129]
	v_mfma_f32_16x16x32_bf16 v[122:125], v[158:161], v[182:185], v[122:125]
	v_mfma_f32_16x16x32_bf16 v[110:113], v[150:153], v[190:193], v[110:113]
	v_mfma_f32_16x16x32_bf16 v[106:109], v[158:161], v[190:193], v[106:109]
	v_mfma_f32_16x16x32_bf16 v[94:97], v[150:153], v[198:201], v[94:97]
	v_mfma_f32_16x16x32_bf16 v[90:93], v[158:161], v[198:201], v[90:93]
	v_mfma_f32_16x16x32_bf16 v[78:81], v[150:153], v[214:217], v[78:81]
	v_mfma_f32_16x16x32_bf16 v[74:77], v[158:161], v[214:217], v[74:77]
	v_mfma_f32_16x16x32_bf16 v[118:121], v[162:165], v[178:181], v[118:121]
	v_mfma_f32_16x16x32_bf16 v[114:117], v[170:173], v[178:181], v[114:117]
	v_mfma_f32_16x16x32_bf16 v[102:105], v[162:165], v[186:189], v[102:105]
	v_mfma_f32_16x16x32_bf16 v[98:101], v[170:173], v[186:189], v[98:101]
	v_mfma_f32_16x16x32_bf16 v[86:89], v[162:165], v[194:197], v[86:89]
	v_mfma_f32_16x16x32_bf16 v[82:85], v[170:173], v[194:197], v[82:85]
	v_mfma_f32_16x16x32_bf16 v[70:73], v[162:165], v[206:209], v[70:73]
	v_mfma_f32_16x16x32_bf16 v[66:69], v[170:173], v[206:209], v[66:69]
	v_mfma_f32_16x16x32_bf16 v[118:121], v[166:169], v[182:185], v[118:121]
	v_mfma_f32_16x16x32_bf16 v[114:117], v[174:177], v[182:185], v[114:117]
	v_mfma_f32_16x16x32_bf16 v[102:105], v[166:169], v[190:193], v[102:105]
	v_mfma_f32_16x16x32_bf16 v[98:101], v[174:177], v[190:193], v[98:101]
	v_mfma_f32_16x16x32_bf16 v[86:89], v[166:169], v[198:201], v[86:89]
	v_mfma_f32_16x16x32_bf16 v[82:85], v[174:177], v[198:201], v[82:85]
	v_mfma_f32_16x16x32_bf16 v[70:73], v[166:169], v[214:217], v[70:73]
	v_mfma_f32_16x16x32_bf16 v[66:69], v[174:177], v[214:217], v[66:69]
	s_barrier
; #define PG8_STAGE(bufoff, gbase, voff) do { _Pragma("unroll") for (int _i = 0; _i < 2; ++_i) \
;         __builtin_amdgcn_global_load_lds((const unsigned*)((const char*)(gbase) + (voff)[_i]), (PG8_LAS unsigned*)(lds + (bufoff) + ldsw + _i * 8192), 16, 0, 0); } while (0)
; #define PG8_LDA(dst, b, h) do { _Pragma("unroll") for (int m = 0; m < 4; ++m) _Pragma("unroll") for (int k = 0; k < 2; ++k) dst[m][k] = *(const PG8_LAS bf16x8*)(lds + PG8_SA(b, h) + aoff + m * 2048 + k * 1024); } while (0)
; #define PG8_MMA(ai, bj, At, Bt) do { __builtin_amdgcn_s_setprio(1); _Pragma("unroll") for (int m = 0; m < 4; ++m) _Pragma("unroll") for (int n = 0; n < 2; ++n) _Pragma("unroll") for (int k = 0; k < 2; ++k) \
;         acc[ai][bj][m][n] = __builtin_amdgcn_mfma_f32_16x16x32_bf16(Bt[n][k], At[m][k], acc[ai][bj][m][n], 0, 0, 0); __builtin_amdgcn_s_setprio(0); } while (0)
; #define PG8_WAIT_V(n) asm volatile("s_waitcnt vmcnt(" #n ")" ::: "memory")
; #define PG8_WAIT_L(n) asm volatile("s_waitcnt lgkmcnt(" #n ")" ::: "memory")
; #define PG8_BAR __builtin_amdgcn_s_barrier()
; #define PG8_SCHED __builtin_amdgcn_sched_barrier(0)
; template <class Epi, class Sched, bool ALIGN_EPI = false, bool SP2 = false>
; __device__ __forceinline__ void gemm_phase(PG8_LAS unsigned char* lds, const Gemm g, const Sched& S, const Epi& E, const int tid) {
;     ...
;             PG8_LDA(At, 1, 1); PG8_STAGE(PG8_SB(1, 0), b3, voffB); PG8_STAGE(PG8_SB(1, 1), b3 + hstep, voffB); PG8_STAGE(PG8_SA(1, 0), a3, voffA);
;             PG8_WAIT_V(8); PG8_WAIT_L(0); PG8_BAR; PG8_MMA(1, 0, At, B0); PG8_MMA(1, 1, At, B1); PG8_BAR; PG8_SCHED;
;     ...
;         if constexpr (ALIGN_EPI) { if (wr == 0) PG8_BAR; }
	s_setprio 0
	s_add_i32 s20, s48, s24
	v_lshl_add_u64 v[202:203], v[202:203], 0, s[94:95]
	s_mov_b32 m0, s20
	ds_read_b128 v[178:181], v145 offset:49152
	ds_read_b128 v[182:185], v145 offset:50176
	ds_read_b128 v[186:189], v145 offset:51200
	ds_read_b128 v[190:193], v145 offset:52224
	ds_read_b128 v[194:197], v145 offset:53248
	ds_read_b128 v[198:201], v145 offset:54272
	ds_read_b128 v[206:209], v145 offset:55296
	ds_read_b128 v[214:217], v145 offset:56320
	global_load_lds_dwordx4 v[202:203], off
	s_add_i32 m0, s20, 0x2000
	s_add_u32 s18, s18, 0x40080
	v_lshl_add_u64 v[202:203], v[210:211], 0, s[94:95]
	s_addc_u32 s19, s19, 0
	s_add_i32 s20, s49, s24
	global_load_lds_dwordx4 v[202:203], off
	v_lshl_add_u64 v[202:203], s[18:19], 0, v[134:135]
	s_mov_b32 m0, s20
	s_nop 0
	global_load_lds_dwordx4 v[202:203], off
	v_lshl_add_u64 v[202:203], s[18:19], 0, v[130:131]
	s_add_i32 m0, s20, 0x2000
	s_nop 0
	global_load_lds_dwordx4 v[202:203], off
	v_lshl_add_u64 v[202:203], v[218:219], 0, s[94:95]
	s_mov_b32 m0, s29
	s_nop 0
	global_load_lds_dwordx4 v[202:203], off
	v_lshl_add_u64 v[202:203], v[220:221], 0, s[94:95]
	s_mov_b32 m0, s30
	s_nop 0
	global_load_lds_dwordx4 v[202:203], off
	s_waitcnt vmcnt(8)
	s_waitcnt lgkmcnt(0)
	s_setprio 1
	s_barrier
	v_mfma_f32_16x16x32_bf16 v[60:63], v[146:149], v[178:181], v[60:63]
	v_mfma_f32_16x16x32_bf16 v[56:59], v[154:157], v[178:181], v[56:59]
	v_mfma_f32_16x16x32_bf16 v[44:47], v[146:149], v[186:189], v[44:47]
	v_mfma_f32_16x16x32_bf16 v[40:43], v[154:157], v[186:189], v[40:43]
	v_mfma_f32_16x16x32_bf16 v[28:31], v[146:149], v[194:197], v[28:31]
	v_mfma_f32_16x16x32_bf16 v[24:27], v[154:157], v[194:197], v[24:27]
	v_mfma_f32_16x16x32_bf16 v[12:15], v[146:149], v[206:209], v[12:15]
	v_mfma_f32_16x16x32_bf16 v[8:11], v[154:157], v[206:209], v[8:11]
	v_mfma_f32_16x16x32_bf16 v[60:63], v[150:153], v[182:185], v[60:63]
	v_mfma_f32_16x16x32_bf16 v[56:59], v[158:161], v[182:185], v[56:59]
	v_mfma_f32_16x16x32_bf16 v[44:47], v[150:153], v[190:193], v[44:47]
	v_mfma_f32_16x16x32_bf16 v[40:43], v[158:161], v[190:193], v[40:43]
	v_mfma_f32_16x16x32_bf16 v[28:31], v[150:153], v[198:201], v[28:31]
	v_mfma_f32_16x16x32_bf16 v[24:27], v[158:161], v[198:201], v[24:27]
	v_mfma_f32_16x16x32_bf16 v[12:15], v[150:153], v[214:217], v[12:15]
	v_mfma_f32_16x16x32_bf16 v[8:11], v[158:161], v[214:217], v[8:11]
	v_mfma_f32_16x16x32_bf16 v[52:55], v[162:165], v[178:181], v[52:55]
	v_mfma_f32_16x16x32_bf16 v[48:51], v[170:173], v[178:181], v[48:51]
	v_mfma_f32_16x16x32_bf16 v[36:39], v[162:165], v[186:189], v[36:39]
	v_mfma_f32_16x16x32_bf16 v[32:35], v[170:173], v[186:189], v[32:35]
	v_mfma_f32_16x16x32_bf16 v[20:23], v[162:165], v[194:197], v[20:23]
	v_mfma_f32_16x16x32_bf16 v[16:19], v[170:173], v[194:197], v[16:19]
	v_mfma_f32_16x16x32_bf16 v[4:7], v[162:165], v[206:209], v[4:7]
	v_mfma_f32_16x16x32_bf16 v[0:3], v[170:173], v[206:209], v[0:3]
	v_mfma_f32_16x16x32_bf16 v[52:55], v[166:169], v[182:185], v[52:55]
	v_mfma_f32_16x16x32_bf16 v[48:51], v[174:177], v[182:185], v[48:51]
	v_mfma_f32_16x16x32_bf16 v[36:39], v[166:169], v[190:193], v[36:39]
	v_mfma_f32_16x16x32_bf16 v[32:35], v[174:177], v[190:193], v[32:35]
	v_mfma_f32_16x16x32_bf16 v[20:23], v[166:169], v[198:201], v[20:23]
	v_mfma_f32_16x16x32_bf16 v[16:19], v[174:177], v[198:201], v[16:19]
	v_mfma_f32_16x16x32_bf16 v[4:7], v[166:169], v[214:217], v[4:7]
	v_mfma_f32_16x16x32_bf16 v[0:3], v[174:177], v[214:217], v[0:3]
	s_barrier
	s_setprio 0
	s_add_i32 s47, s47, 2
	s_add_u32 s45, s45, 0x100
	s_addc_u32 s46, s46, 0
	s_add_u32 s16, s16, 0x100
	s_addc_u32 s17, s17, 0
	s_cmp_gt_u32 s47, 13
	s_cbranch_scc0 .LBB0_254
	s_and_b64 vcc, exec, s[4:5]
	s_cbranch_vccz .LBB0_257
	s_barrier

; #define PG8_STAGE(bufoff, gbase, voff) do { _Pragma("unroll") for (int _i = 0; _i < 2; ++_i) \
;         __builtin_amdgcn_global_load_lds((const unsigned*)((const char*)(gbase) + (voff)[_i]), (PG8_LAS unsigned*)(lds + (bufoff) + ldsw + _i * 8192), 16, 0, 0); } while (0)
; #define PG8_LDA(dst, b, h) do { _Pragma("unroll") for (int m = 0; m < 4; ++m) _Pragma("unroll") for (int k = 0; k < 2; ++k) dst[m][k] = *(const PG8_LAS bf16x8*)(lds + PG8_SA(b, h) + aoff + m * 2048 + k * 1024); } while (0)
; #define PG8_LDB(dst, b, h) do { _Pragma("unroll") for (int n = 0; n < 2; ++n) _Pragma("unroll") for (int k = 0; k < 2; ++k) dst[n][k] = *(const PG8_LAS bf16x8*)(lds + PG8_SB(b, h) + boff + n * 2048 + k * 1024); } while (0)
; #define PG8_MMA(ai, bj, At, Bt) do { __builtin_amdgcn_s_setprio(1); _Pragma("unroll") for (int m = 0; m < 4; ++m) _Pragma("unroll") for (int n = 0; n < 2; ++n) _Pragma("unroll") for (int k = 0; k < 2; ++k) \
;         acc[ai][bj][m][n] = __builtin_amdgcn_mfma_f32_16x16x32_bf16(Bt[n][k], At[m][k], acc[ai][bj][m][n], 0, 0, 0); __builtin_amdgcn_s_setprio(0); } while (0)
; #define PG8_WAIT_V(n) asm volatile("s_waitcnt vmcnt(" #n ")" ::: "memory")
; #define PG8_BAR __builtin_amdgcn_s_barrier()
; template <class Epi, class Sched, bool ALIGN_EPI = false, bool SP2 = false>
; __device__ __forceinline__ void gemm_phase(PG8_LAS unsigned char* lds, const Gemm g, const Sched& S, const Epi& E, const int tid) {
;     ...
;         for (int t = 0; t < nt; t += 2) {
;             const bool last = (t == nt - 2);
;             const char* a1 = cA + (size_t)(t + 1) * kstep;
;             const char* a2 = last ? nA : cA + (size_t)(t + 2) * kstep; const char* b2 = last ? nB : cB + (size_t)(t + 2) * kstep;
;             const char* a3 = a2 + kstep; const char* b3 = b2 + kstep;
;             if (last && has_next) S.a_ready(nxt);
;             if constexpr (SP2) {
;             PG8_LDB(B0, 0, 0); PG8_LDB(B1, 0, 1); PG8_SCHED; PG8_LDA(At, 0, 0); PG8_STAGE(PG8_SA(1, 1), a1 + hstep, voffA);
;             PG8_WAIT_V(8); PG8_WAIT_L(0); PG8_BAR; PG8_MMA(0, 0, At, B0); PG8_MMA(0, 1, At, B1); PG8_BAR; PG8_SCHED;
;             PG8_LDA(At, 0, 1); PG8_STAGE(PG8_SB(0, 0), b2, voffB); PG8_STAGE(PG8_SB(0, 1), b2 + hstep, voffB); PG8_STAGE(PG8_SA(0, 0), a2, voffA);
;             PG8_WAIT_V(8); PG8_WAIT_L(0); PG8_BAR; PG8_MMA(1, 0, At, B0); PG8_MMA(1, 1, At, B1); PG8_BAR; PG8_SCHED;
.LBB0_286:
	s_add_u32 s20, s8, s18
	s_addc_u32 s21, s9, s19
	s_add_u32 s20, s20, 0x100
	s_addc_u32 s21, s21, 0
	s_add_u32 s54, s49, s18
	s_addc_u32 s55, s50, s19
	s_add_i32 s56, 0, 0x10000
	s_cmpk_eq_i32 s18, 0x700
	s_cselect_b32 s23, s13, s21
	s_cselect_b32 s22, s51, s20
	s_cselect_b32 s21, s11, s55
	s_cselect_b32 s20, s52, s54
	s_add_i32 s57, 0, 0x14000
	v_add_u32_e32 v86, s56, v72
	v_add_u32_e32 v110, s57, v72
	ds_read_b128 v[74:77], v86
	ds_read_b128 v[78:81], v86 offset:1024
	ds_read_b128 v[82:85], v86 offset:2048
	ds_read_b128 v[86:89], v86 offset:3072
	ds_read_b128 v[90:93], v110
	ds_read_b128 v[94:97], v110 offset:1024
	ds_read_b128 v[106:109], v110 offset:2048
	ds_read_b128 v[110:113], v110 offset:3072
	v_lshl_add_u64 v[202:203], v[70:71], 0, s[18:19]
	s_add_i32 m0, s31, 0xc000
	ds_read_b128 v[114:117], v73
	ds_read_b128 v[118:121], v73 offset:1024
	ds_read_b128 v[122:125], v73 offset:2048
	ds_read_b128 v[126:129], v73 offset:3072
	ds_read_b128 v[194:197], v73 offset:4096
	ds_read_b128 v[198:201], v73 offset:5120
	ds_read_b128 v[206:209], v73 offset:6144
	ds_read_b128 v[214:217], v73 offset:7168
	global_load_lds_dwordx4 v[202:203], off
	v_lshl_add_u64 v[202:203], v[68:69], 0, s[18:19]
	s_add_i32 m0, s31, 0xe000
	s_nop 0
	global_load_lds_dwordx4 v[202:203], off
	s_waitcnt vmcnt(8)
	s_waitcnt lgkmcnt(0)
	s_setprio 1
	s_barrier
	v_mfma_f32_16x16x32_bf16 v[190:193], v[74:77], v[114:117], v[190:193]
	v_mfma_f32_16x16x32_bf16 v[186:189], v[82:85], v[114:117], v[186:189]
	v_mfma_f32_16x16x32_bf16 v[182:185], v[74:77], v[122:125], v[182:185]
	v_mfma_f32_16x16x32_bf16 v[178:181], v[82:85], v[122:125], v[178:181]
	v_mfma_f32_16x16x32_bf16 v[174:177], v[74:77], v[194:197], v[174:177]
	v_mfma_f32_16x16x32_bf16 v[170:173], v[82:85], v[194:197], v[170:173]
	v_mfma_f32_16x16x32_bf16 v[166:169], v[74:77], v[206:209], v[166:169]
	v_mfma_f32_16x16x32_bf16 v[162:165], v[82:85], v[206:209], v[162:165]
	v_mfma_f32_16x16x32_bf16 v[190:193], v[78:81], v[118:121], v[190:193]
	v_mfma_f32_16x16x32_bf16 v[186:189], v[86:89], v[118:121], v[186:189]
	v_mfma_f32_16x16x32_bf16 v[182:185], v[78:81], v[126:129], v[182:185]
	v_mfma_f32_16x16x32_bf16 v[178:181], v[86:89], v[126:129], v[178:181]
	v_mfma_f32_16x16x32_bf16 v[174:177], v[78:81], v[198:201], v[174:177]
	v_mfma_f32_16x16x32_bf16 v[170:173], v[86:89], v[198:201], v[170:173]
	v_mfma_f32_16x16x32_bf16 v[166:169], v[78:81], v[214:217], v[166:169]
	v_mfma_f32_16x16x32_bf16 v[162:165], v[86:89], v[214:217], v[162:165]
	v_mfma_f32_16x16x32_bf16 v[102:105], v[90:93], v[114:117], v[102:105]
	v_mfma_f32_16x16x32_bf16 v[98:101], v[106:109], v[114:117], v[98:101]
	v_mfma_f32_16x16x32_bf16 v[56:59], v[90:93], v[122:125], v[56:59]
	v_mfma_f32_16x16x32_bf16 v[48:51], v[106:109], v[122:125], v[48:51]
	v_mfma_f32_16x16x32_bf16 v[44:47], v[90:93], v[194:197], v[44:47]
	v_mfma_f32_16x16x32_bf16 v[40:43], v[106:109], v[194:197], v[40:43]
	v_mfma_f32_16x16x32_bf16 v[36:39], v[90:93], v[206:209], v[36:39]
	v_mfma_f32_16x16x32_bf16 v[32:35], v[106:109], v[206:209], v[32:35]
	v_mfma_f32_16x16x32_bf16 v[102:105], v[94:97], v[118:121], v[102:105]
	v_mfma_f32_16x16x32_bf16 v[98:101], v[110:113], v[118:121], v[98:101]
	v_mfma_f32_16x16x32_bf16 v[56:59], v[94:97], v[126:129], v[56:59]
	v_mfma_f32_16x16x32_bf16 v[48:51], v[110:113], v[126:129], v[48:51]
	v_mfma_f32_16x16x32_bf16 v[44:47], v[94:97], v[198:201], v[44:47]
	v_mfma_f32_16x16x32_bf16 v[40:43], v[110:113], v[198:201], v[40:43]
	v_mfma_f32_16x16x32_bf16 v[36:39], v[94:97], v[214:217], v[36:39]
	v_mfma_f32_16x16x32_bf16 v[32:35], v[110:113], v[214:217], v[32:35]
	s_barrier
	s_setprio 0
	s_add_i32 s54, s56, s30
	v_lshl_add_u64 v[202:203], s[20:21], 0, v[64:65]
	s_mov_b32 m0, s54
	ds_read_b128 v[114:117], v73 offset:16384
	ds_read_b128 v[118:121], v73 offset:17408
	ds_read_b128 v[122:125], v73 offset:18432
	ds_read_b128 v[126:129], v73 offset:19456
	ds_read_b128 v[194:197], v73 offset:20480
	ds_read_b128 v[198:201], v73 offset:21504
	ds_read_b128 v[206:209], v73 offset:22528
	ds_read_b128 v[214:217], v73 offset:23552
	global_load_lds_dwordx4 v[202:203], off
	s_add_i32 m0, s54, 0x2000
	s_add_u32 s54, s20, 0x40000
	v_lshl_add_u64 v[210:211], s[20:21], 0, v[52:53]
	s_addc_u32 s55, s21, 0
	s_add_i32 s56, s57, s30
	global_load_lds_dwordx4 v[210:211], off
	v_lshl_add_u64 v[218:219], s[54:55], 0, v[64:65]
	s_mov_b32 m0, s56
	v_lshl_add_u64 v[226:227], s[22:23], 0, v[60:61]
	global_load_lds_dwordx4 v[218:219], off
	v_lshl_add_u64 v[218:219], s[54:55], 0, v[52:53]
	s_add_i32 m0, s56, 0x2000
	v_lshl_add_u64 v[228:229], s[22:23], 0, v[54:55]
	global_load_lds_dwordx4 v[218:219], off
	s_mov_b32 m0, s31
	s_nop 0
	global_load_lds_dwordx4 v[226:227], off
	s_mov_b32 m0, s35
	s_nop 0
	global_load_lds_dwordx4 v[228:229], off
	s_waitcnt vmcnt(8)
	s_waitcnt lgkmcnt(0)
	s_setprio 1
	s_barrier
; #define PG8_STAGE(bufoff, gbase, voff) do { _Pragma("unroll") for (int _i = 0; _i < 2; ++_i) \
;         __builtin_amdgcn_global_load_lds((const unsigned*)((const char*)(gbase) + (voff)[_i]), (PG8_LAS unsigned*)(lds + (bufoff) + ldsw + _i * 8192), 16, 0, 0); } while (0)
; #define PG8_LDA(dst, b, h) do { _Pragma("unroll") for (int m = 0; m < 4; ++m) _Pragma("unroll") for (int k = 0; k < 2; ++k) dst[m][k] = *(const PG8_LAS bf16x8*)(lds + PG8_SA(b, h) + aoff + m * 2048 + k * 1024); } while (0)
; #define PG8_LDB(dst, b, h) do { _Pragma("unroll") for (int n = 0; n < 2; ++n) _Pragma("unroll") for (int k = 0; k < 2; ++k) dst[n][k] = *(const PG8_LAS bf16x8*)(lds + PG8_SB(b, h) + boff + n * 2048 + k * 1024); } while (0)
; #define PG8_MMA(ai, bj, At, Bt) do { __builtin_amdgcn_s_setprio(1); _Pragma("unroll") for (int m = 0; m < 4; ++m) _Pragma("unroll") for (int n = 0; n < 2; ++n) _Pragma("unroll") for (int k = 0; k < 2; ++k) \
;         acc[ai][bj][m][n] = __builtin_amdgcn_mfma_f32_16x16x32_bf16(Bt[n][k], At[m][k], acc[ai][bj][m][n], 0, 0, 0); __builtin_amdgcn_s_setprio(0); } while (0)
; #define PG8_WAIT_V(n) asm volatile("s_waitcnt vmcnt(" #n ")" ::: "memory")
; #define PG8_WAIT_L(n) asm volatile("s_waitcnt lgkmcnt(" #n ")" ::: "memory")
; #define PG8_BAR __builtin_amdgcn_s_barrier()
; #define PG8_SCHED __builtin_amdgcn_sched_barrier(0)
; template <class Epi, class Sched, bool ALIGN_EPI = false, bool SP2 = false>
; __device__ __forceinline__ void gemm_phase(PG8_LAS unsigned char* lds, const Gemm g, const Sched& S, const Epi& E, const int tid) {
;     ...
;             PG8_WAIT_V(8); PG8_WAIT_L(0); PG8_BAR; PG8_MMA(1, 0, At, B0); PG8_MMA(1, 1, At, B1); PG8_BAR; PG8_SCHED;
;             PG8_LDB(B0, 1, 0); PG8_LDB(B1, 1, 1); PG8_SCHED; PG8_LDA(At, 1, 0); PG8_STAGE(PG8_SA(0, 1), a2 + hstep, voffA);
;             PG8_WAIT_V(8); PG8_WAIT_L(0); PG8_BAR; PG8_MMA(0, 0, At, B0); PG8_MMA(0, 1, At, B1); PG8_BAR; PG8_SCHED;
	v_mfma_f32_16x16x32_bf16 v[158:161], v[74:77], v[114:117], v[158:161]
	v_mfma_f32_16x16x32_bf16 v[154:157], v[82:85], v[114:117], v[154:157]
	v_mfma_f32_16x16x32_bf16 v[150:153], v[74:77], v[122:125], v[150:153]
	v_mfma_f32_16x16x32_bf16 v[146:149], v[82:85], v[122:125], v[146:149]
	v_mfma_f32_16x16x32_bf16 v[142:145], v[74:77], v[194:197], v[142:145]
	v_mfma_f32_16x16x32_bf16 v[138:141], v[82:85], v[194:197], v[138:141]
	v_mfma_f32_16x16x32_bf16 v[74:77], v[74:77], v[206:209], v[134:137]
	v_mfma_f32_16x16x32_bf16 v[158:161], v[78:81], v[118:121], v[158:161]
	v_mfma_f32_16x16x32_bf16 v[154:157], v[86:89], v[118:121], v[154:157]
	v_mfma_f32_16x16x32_bf16 v[150:153], v[78:81], v[126:129], v[150:153]
	v_mfma_f32_16x16x32_bf16 v[146:149], v[86:89], v[126:129], v[146:149]
	v_mfma_f32_16x16x32_bf16 v[142:145], v[78:81], v[198:201], v[142:145]
	v_mfma_f32_16x16x32_bf16 v[138:141], v[86:89], v[198:201], v[138:141]
	v_mfma_f32_16x16x32_bf16 v[74:77], v[78:81], v[214:217], v[74:77]
	v_mfma_f32_16x16x32_bf16 v[78:81], v[82:85], v[206:209], v[130:133]
	v_mfma_f32_16x16x32_bf16 v[78:81], v[86:89], v[214:217], v[78:81]
	v_mfma_f32_16x16x32_bf16 v[28:31], v[90:93], v[114:117], v[28:31]
	v_mfma_f32_16x16x32_bf16 v[24:27], v[106:109], v[114:117], v[24:27]
	v_mfma_f32_16x16x32_bf16 v[20:23], v[90:93], v[122:125], v[20:23]
	v_mfma_f32_16x16x32_bf16 v[16:19], v[106:109], v[122:125], v[16:19]
	v_mfma_f32_16x16x32_bf16 v[12:15], v[90:93], v[194:197], v[12:15]
	v_mfma_f32_16x16x32_bf16 v[8:11], v[106:109], v[194:197], v[8:11]
	v_mfma_f32_16x16x32_bf16 v[4:7], v[90:93], v[206:209], v[4:7]
	v_mfma_f32_16x16x32_bf16 v[0:3], v[106:109], v[206:209], v[0:3]
	v_mfma_f32_16x16x32_bf16 v[28:31], v[94:97], v[118:121], v[28:31]
	v_mfma_f32_16x16x32_bf16 v[24:27], v[110:113], v[118:121], v[24:27]
	v_mfma_f32_16x16x32_bf16 v[20:23], v[94:97], v[126:129], v[20:23]
	v_mfma_f32_16x16x32_bf16 v[16:19], v[110:113], v[126:129], v[16:19]
	v_mfma_f32_16x16x32_bf16 v[12:15], v[94:97], v[198:201], v[12:15]
	v_mfma_f32_16x16x32_bf16 v[8:11], v[110:113], v[198:201], v[8:11]
	v_mfma_f32_16x16x32_bf16 v[4:7], v[94:97], v[214:217], v[4:7]
	v_mfma_f32_16x16x32_bf16 v[0:3], v[110:113], v[214:217], v[0:3]
	s_barrier
	s_setprio 0
	s_add_i32 s54, 0, 0x18000
	s_add_i32 s55, 0, 0x1c000
	v_add_u32_e32 v94, s54, v72
	v_add_u32_e32 v118, s55, v72
	ds_read_b128 v[82:85], v94
	ds_read_b128 v[86:89], v94 offset:1024
	ds_read_b128 v[90:93], v94 offset:2048
	ds_read_b128 v[94:97], v94 offset:3072
	ds_read_b128 v[106:109], v118
	ds_read_b128 v[110:113], v118 offset:1024
	ds_read_b128 v[114:117], v118 offset:2048
	ds_read_b128 v[118:121], v118 offset:3072
	s_add_u32 s22, s22, 0x40000
	s_addc_u32 s23, s23, 0
	s_mov_b32 m0, s42
	v_lshl_add_u64 v[218:219], s[22:23], 0, v[60:61]
	ds_read_b128 v[122:125], v73 offset:32768
	ds_read_b128 v[126:129], v73 offset:33792
	ds_read_b128 v[130:133], v73 offset:34816
	ds_read_b128 v[134:137], v73 offset:35840
	ds_read_b128 v[194:197], v73 offset:36864
	ds_read_b128 v[198:201], v73 offset:37888
	ds_read_b128 v[206:209], v73 offset:38912
	ds_read_b128 v[214:217], v73 offset:39936
	global_load_lds_dwordx4 v[218:219], off
	v_lshl_add_u64 v[218:219], s[22:23], 0, v[54:55]
	s_mov_b32 m0, s44
	s_nop 0
	global_load_lds_dwordx4 v[218:219], off
	s_waitcnt vmcnt(8)
	s_waitcnt lgkmcnt(0)
	s_setprio 1
	s_barrier
	v_mfma_f32_16x16x32_bf16 v[190:193], v[82:85], v[122:125], v[190:193]
	v_mfma_f32_16x16x32_bf16 v[186:189], v[90:93], v[122:125], v[186:189]
	v_mfma_f32_16x16x32_bf16 v[182:185], v[82:85], v[130:133], v[182:185]
	v_mfma_f32_16x16x32_bf16 v[178:181], v[90:93], v[130:133], v[178:181]
	v_mfma_f32_16x16x32_bf16 v[174:177], v[82:85], v[194:197], v[174:177]
	v_mfma_f32_16x16x32_bf16 v[170:173], v[90:93], v[194:197], v[170:173]
	v_mfma_f32_16x16x32_bf16 v[166:169], v[82:85], v[206:209], v[166:169]
	v_mfma_f32_16x16x32_bf16 v[162:165], v[90:93], v[206:209], v[162:165]
	v_mfma_f32_16x16x32_bf16 v[190:193], v[86:89], v[126:129], v[190:193]
	v_mfma_f32_16x16x32_bf16 v[186:189], v[94:97], v[126:129], v[186:189]
	v_mfma_f32_16x16x32_bf16 v[182:185], v[86:89], v[134:137], v[182:185]
	v_mfma_f32_16x16x32_bf16 v[178:181], v[94:97], v[134:137], v[178:181]
	v_mfma_f32_16x16x32_bf16 v[174:177], v[86:89], v[198:201], v[174:177]
	v_mfma_f32_16x16x32_bf16 v[170:173], v[94:97], v[198:201], v[170:173]
	v_mfma_f32_16x16x32_bf16 v[166:169], v[86:89], v[214:217], v[166:169]
	v_mfma_f32_16x16x32_bf16 v[162:165], v[94:97], v[214:217], v[162:165]
	v_mfma_f32_16x16x32_bf16 v[102:105], v[106:109], v[122:125], v[102:105]
	v_mfma_f32_16x16x32_bf16 v[98:101], v[114:117], v[122:125], v[98:101]
	v_mfma_f32_16x16x32_bf16 v[56:59], v[106:109], v[130:133], v[56:59]
	v_mfma_f32_16x16x32_bf16 v[48:51], v[114:117], v[130:133], v[48:51]
	v_mfma_f32_16x16x32_bf16 v[44:47], v[106:109], v[194:197], v[44:47]
	v_mfma_f32_16x16x32_bf16 v[40:43], v[114:117], v[194:197], v[40:43]
	v_mfma_f32_16x16x32_bf16 v[36:39], v[106:109], v[206:209], v[36:39]
	v_mfma_f32_16x16x32_bf16 v[32:35], v[114:117], v[206:209], v[32:35]
	v_mfma_f32_16x16x32_bf16 v[102:105], v[110:113], v[126:129], v[102:105]
	v_mfma_f32_16x16x32_bf16 v[98:101], v[118:121], v[126:129], v[98:101]
	v_mfma_f32_16x16x32_bf16 v[56:59], v[110:113], v[134:137], v[56:59]
	v_mfma_f32_16x16x32_bf16 v[48:51], v[118:121], v[134:137], v[48:51]
	v_mfma_f32_16x16x32_bf16 v[44:47], v[110:113], v[198:201], v[44:47]
	v_mfma_f32_16x16x32_bf16 v[40:43], v[118:121], v[198:201], v[40:43]
	v_mfma_f32_16x16x32_bf16 v[36:39], v[110:113], v[214:217], v[36:39]
	v_mfma_f32_16x16x32_bf16 v[32:35], v[118:121], v[214:217], v[32:35]
	s_barrier
; #define PG8_STAGE(bufoff, gbase, voff) do { _Pragma("unroll") for (int _i = 0; _i < 2; ++_i) \
;         __builtin_amdgcn_global_load_lds((const unsigned*)((const char*)(gbase) + (voff)[_i]), (PG8_LAS unsigned*)(lds + (bufoff) + ldsw + _i * 8192), 16, 0, 0); } while (0)
; #define PG8_LDA(dst, b, h) do { _Pragma("unroll") for (int m = 0; m < 4; ++m) _Pragma("unroll") for (int k = 0; k < 2; ++k) dst[m][k] = *(const PG8_LAS bf16x8*)(lds + PG8_SA(b, h) + aoff + m * 2048 + k * 1024); } while (0)
; #define PG8_MMA(ai, bj, At, Bt) do { __builtin_amdgcn_s_setprio(1); _Pragma("unroll") for (int m = 0; m < 4; ++m) _Pragma("unroll") for (int n = 0; n < 2; ++n) _Pragma("unroll") for (int k = 0; k < 2; ++k) \
;         acc[ai][bj][m][n] = __builtin_amdgcn_mfma_f32_16x16x32_bf16(Bt[n][k], At[m][k], acc[ai][bj][m][n], 0, 0, 0); __builtin_amdgcn_s_setprio(0); } while (0)
; #define PG8_WAIT_V(n) asm volatile("s_waitcnt vmcnt(" #n ")" ::: "memory")
; #define PG8_WAIT_L(n) asm volatile("s_waitcnt lgkmcnt(" #n ")" ::: "memory")
; #define PG8_BAR __builtin_amdgcn_s_barrier()
; #define PG8_SCHED __builtin_amdgcn_sched_barrier(0)
; template <class Epi, class Sched, bool ALIGN_EPI = false, bool SP2 = false>
; __device__ __forceinline__ void gemm_phase(PG8_LAS unsigned char* lds, const Gemm g, const Sched& S, const Epi& E, const int tid) {
;     ...
;             PG8_LDA(At, 1, 1); PG8_STAGE(PG8_SB(1, 0), b3, voffB); PG8_STAGE(PG8_SB(1, 1), b3 + hstep, voffB); PG8_STAGE(PG8_SA(1, 0), a3, voffA);
;             PG8_WAIT_V(8); PG8_WAIT_L(0); PG8_BAR; PG8_MMA(1, 0, At, B0); PG8_MMA(1, 1, At, B1); PG8_BAR; PG8_SCHED;
;     ...
;         if (!has_next) break;
; #pragma unroll
;         for (int a = 0; a < 2; ++a)
; #pragma unroll
;             for (int b = 0; b < 2; ++b)
; #pragma unroll
;                 for (int m = 0; m < 4; ++m)
; #pragma unroll
;                     for (int n = 0; n < 2; ++n) acc[a][b][m][n] = (f32x4){0.f, 0.f, 0.f, 0.f};
;         cur = nxt; cA = nA; cB = nB; ++ui;
	s_setprio 0
	s_add_i32 s22, s54, s30
	v_lshl_add_u64 v[130:131], v[202:203], 0, s[94:95]
	s_mov_b32 m0, s22
	ds_read_b128 v[122:125], v73 offset:49152
	ds_read_b128 v[126:129], v73 offset:50176
	ds_read_b128 v[194:197], v73 offset:51200
	ds_read_b128 v[198:201], v73 offset:52224
	ds_read_b128 v[206:209], v73 offset:53248
	ds_read_b128 v[214:217], v73 offset:54272
	ds_read_b128 v[218:221], v73 offset:55296
	ds_read_b128 v[222:225], v73 offset:56320
	global_load_lds_dwordx4 v[130:131], off
	s_add_i32 m0, s22, 0x2000
	s_add_u32 s20, s20, 0x40080
	v_lshl_add_u64 v[130:131], v[210:211], 0, s[94:95]
	s_addc_u32 s21, s21, 0
	s_add_i32 s22, s55, s30
	global_load_lds_dwordx4 v[130:131], off
	v_lshl_add_u64 v[130:131], s[20:21], 0, v[64:65]
	s_mov_b32 m0, s22
	s_nop 0
	global_load_lds_dwordx4 v[130:131], off
	v_lshl_add_u64 v[130:131], s[20:21], 0, v[52:53]
	s_add_i32 m0, s22, 0x2000
	s_nop 0
	global_load_lds_dwordx4 v[130:131], off
	v_lshl_add_u64 v[130:131], v[226:227], 0, s[94:95]
	s_mov_b32 m0, s45
	s_nop 0
	global_load_lds_dwordx4 v[130:131], off
	v_lshl_add_u64 v[130:131], v[228:229], 0, s[94:95]
	s_mov_b32 m0, s46
	s_nop 0
	global_load_lds_dwordx4 v[130:131], off
	s_waitcnt vmcnt(8)
	s_waitcnt lgkmcnt(0)
	s_setprio 1
	s_barrier
	v_mfma_f32_16x16x32_bf16 v[130:133], v[82:85], v[122:125], v[158:161]
	v_mfma_f32_16x16x32_bf16 v[158:161], v[86:89], v[126:129], v[130:133]
	v_mfma_f32_16x16x32_bf16 v[130:133], v[90:93], v[122:125], v[154:157]
	v_mfma_f32_16x16x32_bf16 v[154:157], v[94:97], v[126:129], v[130:133]
	v_mfma_f32_16x16x32_bf16 v[130:133], v[82:85], v[194:197], v[150:153]
	v_mfma_f32_16x16x32_bf16 v[150:153], v[86:89], v[198:201], v[130:133]
	v_mfma_f32_16x16x32_bf16 v[130:133], v[90:93], v[194:197], v[146:149]
	v_mfma_f32_16x16x32_bf16 v[146:149], v[94:97], v[198:201], v[130:133]
	v_mfma_f32_16x16x32_bf16 v[130:133], v[82:85], v[206:209], v[142:145]
	v_mfma_f32_16x16x32_bf16 v[74:77], v[82:85], v[218:221], v[74:77]
	v_mfma_f32_16x16x32_bf16 v[142:145], v[86:89], v[214:217], v[130:133]
	v_mfma_f32_16x16x32_bf16 v[130:133], v[90:93], v[206:209], v[138:141]
	v_mfma_f32_16x16x32_bf16 v[134:137], v[86:89], v[222:225], v[74:77]
	v_mfma_f32_16x16x32_bf16 v[74:77], v[90:93], v[218:221], v[78:81]
	v_mfma_f32_16x16x32_bf16 v[138:141], v[94:97], v[214:217], v[130:133]
	v_mfma_f32_16x16x32_bf16 v[130:133], v[94:97], v[222:225], v[74:77]
	v_mfma_f32_16x16x32_bf16 v[28:31], v[106:109], v[122:125], v[28:31]
	v_mfma_f32_16x16x32_bf16 v[24:27], v[114:117], v[122:125], v[24:27]
	v_mfma_f32_16x16x32_bf16 v[20:23], v[106:109], v[194:197], v[20:23]
	v_mfma_f32_16x16x32_bf16 v[16:19], v[114:117], v[194:197], v[16:19]
	v_mfma_f32_16x16x32_bf16 v[12:15], v[106:109], v[206:209], v[12:15]
	v_mfma_f32_16x16x32_bf16 v[8:11], v[114:117], v[206:209], v[8:11]
	v_mfma_f32_16x16x32_bf16 v[4:7], v[106:109], v[218:221], v[4:7]
	v_mfma_f32_16x16x32_bf16 v[0:3], v[114:117], v[218:221], v[0:3]
	v_mfma_f32_16x16x32_bf16 v[28:31], v[110:113], v[126:129], v[28:31]
	v_mfma_f32_16x16x32_bf16 v[24:27], v[118:121], v[126:129], v[24:27]
	v_mfma_f32_16x16x32_bf16 v[20:23], v[110:113], v[198:201], v[20:23]
	v_mfma_f32_16x16x32_bf16 v[16:19], v[118:121], v[198:201], v[16:19]
	v_mfma_f32_16x16x32_bf16 v[12:15], v[110:113], v[214:217], v[12:15]
	v_mfma_f32_16x16x32_bf16 v[8:11], v[118:121], v[214:217], v[8:11]
	v_mfma_f32_16x16x32_bf16 v[4:7], v[110:113], v[222:225], v[4:7]
	v_mfma_f32_16x16x32_bf16 v[0:3], v[118:121], v[222:225], v[0:3]
	s_barrier
	s_setprio 0
	s_add_i32 s53, s53, 2
	s_add_u32 s18, s18, 0x100
	s_addc_u32 s19, s19, 0
	s_cmp_gt_u32 s53, 13
	s_cbranch_scc0 .LBB0_286
	s_add_u32 s18, s49, 0xffffff00
	s_addc_u32 s19, s50, -1
	s_andn2_b64 vcc, exec, s[2:3]
	s_cbranch_vccnz .LBB0_289
	v_mov_b32_e32 v0, 0
	s_mov_b32 s4, s10
	s_mov_b32 s24, s12
	s_mov_b64 s[8:9], s[16:17]
	s_mov_b32 s47, s48
	v_mov_b32_e32 v1, v0
	v_mov_b32_e32 v2, v0
	v_mov_b32_e32 v3, v0
	v_mov_b32_e32 v4, v0
	v_mov_b32_e32 v5, v0
	v_mov_b32_e32 v6, v0
	v_mov_b32_e32 v7, v0
	v_mov_b32_e32 v8, v0
	v_mov_b32_e32 v9, v0
	v_mov_b32_e32 v10, v0
	v_mov_b32_e32 v11, v0
	v_mov_b32_e32 v12, v0
	v_mov_b32_e32 v13, v0
	v_mov_b32_e32 v14, v0
	v_mov_b32_e32 v15, v0
	v_mov_b32_e32 v16, v0
	v_mov_b32_e32 v17, v0
	v_mov_b32_e32 v18, v0
	v_mov_b32_e32 v19, v0
	v_mov_b32_e32 v20, v0
	v_mov_b32_e32 v21, v0
	v_mov_b32_e32 v22, v0
	v_mov_b32_e32 v23, v0
	v_mov_b32_e32 v24, v0
	v_mov_b32_e32 v25, v0
	v_mov_b32_e32 v26, v0
	v_mov_b32_e32 v27, v0
	v_mov_b32_e32 v28, v0
	v_mov_b32_e32 v29, v0
	v_mov_b32_e32 v30, v0
	v_mov_b32_e32 v31, v0
	v_mov_b32_e32 v130, v0
	v_mov_b32_e32 v131, v0
	v_mov_b32_e32 v132, v0
	v_mov_b32_e32 v133, v0
	v_mov_b32_e32 v134, v0
	v_mov_b32_e32 v135, v0
	v_mov_b32_e32 v136, v0
	v_mov_b32_e32 v137, v0
	v_mov_b32_e32 v138, v0
	v_mov_b32_e32 v139, v0
	v_mov_b32_e32 v140, v0
	v_mov_b32_e32 v141, v0
	v_mov_b32_e32 v142, v0
	v_mov_b32_e32 v143, v0
	v_mov_b32_e32 v144, v0
	v_mov_b32_e32 v145, v0
	v_mov_b32_e32 v146, v0
	v_mov_b32_e32 v147, v0
	v_mov_b32_e32 v148, v0
	v_mov_b32_e32 v149, v0
	v_mov_b32_e32 v150, v0
	v_mov_b32_e32 v151, v0
	v_mov_b32_e32 v152, v0
	v_mov_b32_e32 v153, v0
	v_mov_b32_e32 v154, v0
	v_mov_b32_e32 v155, v0
	v_mov_b32_e32 v156, v0
	v_mov_b32_e32 v157, v0
	v_mov_b32_e32 v158, v0
	v_mov_b32_e32 v159, v0
	v_mov_b32_e32 v160, v0
	v_mov_b32_e32 v161, v0
	v_mov_b32_e32 v32, v0
	v_mov_b32_e32 v33, v0
	v_mov_b32_e32 v34, v0
	v_mov_b32_e32 v35, v0
	v_mov_b32_e32 v36, v0
	v_mov_b32_e32 v37, v0
	v_mov_b32_e32 v38, v0
	v_mov_b32_e32 v39, v0
	v_mov_b32_e32 v40, v0
	v_mov_b32_e32 v41, v0
	v_mov_b32_e32 v42, v0
	v_mov_b32_e32 v43, v0
	v_mov_b32_e32 v44, v0
	v_mov_b32_e32 v45, v0
	v_mov_b32_e32 v46, v0
	v_mov_b32_e32 v47, v0
	v_mov_b32_e32 v48, v0
	v_mov_b32_e32 v49, v0
	v_mov_b32_e32 v50, v0
	v_mov_b32_e32 v51, v0
	v_mov_b32_e32 v56, v0
	v_mov_b32_e32 v57, v0
	v_mov_b32_e32 v58, v0
	v_mov_b32_e32 v59, v0
	v_mov_b32_e32 v98, v0
	v_mov_b32_e32 v99, v0
	v_mov_b32_e32 v100, v0
	v_mov_b32_e32 v101, v0
	v_mov_b32_e32 v102, v0
	v_mov_b32_e32 v103, v0
	v_mov_b32_e32 v104, v0
	v_mov_b32_e32 v105, v0
	v_mov_b32_e32 v162, v0
	v_mov_b32_e32 v163, v0
	v_mov_b32_e32 v164, v0
	v_mov_b32_e32 v165, v0
	v_mov_b32_e32 v166, v0
	v_mov_b32_e32 v167, v0
	v_mov_b32_e32 v168, v0
	v_mov_b32_e32 v169, v0
	v_mov_b32_e32 v170, v0
	v_mov_b32_e32 v171, v0
	v_mov_b32_e32 v172, v0
	v_mov_b32_e32 v173, v0
	v_mov_b32_e32 v174, v0
	v_mov_b32_e32 v175, v0
	v_mov_b32_e32 v176, v0
	v_mov_b32_e32 v177, v0
	v_mov_b32_e32 v178, v0
	v_mov_b32_e32 v179, v0
	v_mov_b32_e32 v180, v0
	v_mov_b32_e32 v181, v0
	v_mov_b32_e32 v182, v0
	v_mov_b32_e32 v183, v0
	v_mov_b32_e32 v184, v0
	v_mov_b32_e32 v185, v0
	v_mov_b32_e32 v186, v0
	v_mov_b32_e32 v187, v0
	v_mov_b32_e32 v188, v0
	v_mov_b32_e32 v189, v0
	v_mov_b32_e32 v190, v0
	v_mov_b32_e32 v191, v0
	v_mov_b32_e32 v192, v0
	v_mov_b32_e32 v193, v0
	s_andn2_b64 vcc, exec, s[0:1]
	s_cbranch_vccnz .LBB0_290
	s_branch .LBB0_291

; #define PG8_STAGE(bufoff, gbase, voff) do { _Pragma("unroll") for (int _i = 0; _i < 2; ++_i) \
;         __builtin_amdgcn_global_load_lds((const unsigned*)((const char*)(gbase) + (voff)[_i]), (PG8_LAS unsigned*)(lds + (bufoff) + ldsw + _i * 8192), 16, 0, 0); } while (0)
; #define PG8_LDA(dst, b, h) do { _Pragma("unroll") for (int m = 0; m < 4; ++m) _Pragma("unroll") for (int k = 0; k < 2; ++k) dst[m][k] = *(const PG8_LAS bf16x8*)(lds + PG8_SA(b, h) + aoff + m * 2048 + k * 1024); } while (0)
; #define PG8_LDB(dst, b, h) do { _Pragma("unroll") for (int n = 0; n < 2; ++n) _Pragma("unroll") for (int k = 0; k < 2; ++k) dst[n][k] = *(const PG8_LAS bf16x8*)(lds + PG8_SB(b, h) + boff + n * 2048 + k * 1024); } while (0)
; #define PG8_MMA(ai, bj, At, Bt) do { __builtin_amdgcn_s_setprio(1); _Pragma("unroll") for (int m = 0; m < 4; ++m) _Pragma("unroll") for (int n = 0; n < 2; ++n) _Pragma("unroll") for (int k = 0; k < 2; ++k) \
;         acc[ai][bj][m][n] = __builtin_amdgcn_mfma_f32_16x16x32_bf16(Bt[n][k], At[m][k], acc[ai][bj][m][n], 0, 0, 0); __builtin_amdgcn_s_setprio(0); } while (0)
; #define PG8_WAIT_V(n) asm volatile("s_waitcnt vmcnt(" #n ")" ::: "memory")
; #define PG8_WAIT_L(n) asm volatile("s_waitcnt lgkmcnt(" #n ")" ::: "memory")
; #define PG8_BAR __builtin_amdgcn_s_barrier()
; #define PG8_SCHED __builtin_amdgcn_sched_barrier(0)
; template <class Epi, class Sched, bool ALIGN_EPI = false, bool SP2 = false>
; __device__ __forceinline__ void gemm_phase(PG8_LAS unsigned char* lds, const Gemm g, const Sched& S, const Epi& E, const int tid) {
;     ...
;             if constexpr (SP2) {
;             PG8_LDB(B0, 0, 0); PG8_LDB(B1, 0, 1); PG8_SCHED; PG8_LDA(At, 0, 0); PG8_STAGE(PG8_SA(1, 1), a1 + hstep, voffA);
;             PG8_WAIT_V(8); PG8_WAIT_L(0); PG8_BAR; PG8_MMA(0, 0, At, B0); PG8_MMA(0, 1, At, B1); PG8_BAR; PG8_SCHED;
;             PG8_LDA(At, 0, 1); PG8_STAGE(PG8_SB(0, 0), b2, voffB); PG8_STAGE(PG8_SB(0, 1), b2 + hstep, voffB); PG8_STAGE(PG8_SA(0, 0), a2, voffA);
;             PG8_WAIT_V(8); PG8_WAIT_L(0); PG8_BAR; PG8_MMA(1, 0, At, B0); PG8_MMA(1, 1, At, B1); PG8_BAR; PG8_SCHED;
.LBB0_348:
	s_add_i32 s47, 0, 0x10000
	s_add_i32 s45, 0, 0x14000
	v_add_u32_e32 v8, s47, v141
	v_add_u32_e32 v9, s45, v141
	ds_read_b128 v[10:13], v8
	ds_read_b128 v[14:17], v8 offset:1024
	ds_read_b128 v[18:21], v8 offset:2048
	ds_read_b128 v[22:25], v8 offset:3072
	ds_read_b128 v[26:29], v9
	ds_read_b128 v[30:33], v9 offset:1024
	ds_read_b128 v[34:37], v9 offset:2048
	ds_read_b128 v[38:41], v9 offset:3072
	s_add_u32 s2, s14, 0x18080
	s_addc_u32 s3, s15, 0
	s_add_i32 s50, s23, 0xc000
	v_lshl_add_u64 v[62:63], s[2:3], 0, v[136:137]
	s_mov_b32 m0, s50
	ds_read_b128 v[0:3], v142
	ds_read_b128 v[4:7], v142 offset:1024
	ds_read_b128 v[42:45], v142 offset:2048
	ds_read_b128 v[46:49], v142 offset:3072
	ds_read_b128 v[50:53], v142 offset:4096
	ds_read_b128 v[54:57], v142 offset:5120
	ds_read_b128 v[58:61], v142 offset:6144
	ds_read_b128 v[66:69], v142 offset:7168
	global_load_lds_dwordx4 v[62:63], off
	v_lshl_add_u64 v[62:63], s[2:3], 0, v[132:133]
	s_add_i32 s2, s23, 0xe000
	s_mov_b32 m0, s2
	s_nop 0
	global_load_lds_dwordx4 v[62:63], off
	s_waitcnt vmcnt(8)
	s_waitcnt lgkmcnt(0)
	s_setprio 1
	s_barrier
	v_mfma_f32_16x16x32_bf16 v[70:73], v[10:13], v[0:3], 0
	v_mfma_f32_16x16x32_bf16 v[74:77], v[18:21], v[0:3], 0
	v_mfma_f32_16x16x32_bf16 v[78:81], v[10:13], v[42:45], 0
	v_mfma_f32_16x16x32_bf16 v[82:85], v[18:21], v[42:45], 0
	v_mfma_f32_16x16x32_bf16 v[86:89], v[10:13], v[50:53], 0
	v_mfma_f32_16x16x32_bf16 v[90:93], v[18:21], v[50:53], 0
	v_mfma_f32_16x16x32_bf16 v[94:97], v[10:13], v[58:61], 0
	v_mfma_f32_16x16x32_bf16 v[98:101], v[18:21], v[58:61], 0
	v_mfma_f32_16x16x32_bf16 v[70:73], v[14:17], v[4:7], v[70:73]
	v_mfma_f32_16x16x32_bf16 v[74:77], v[22:25], v[4:7], v[74:77]
	v_mfma_f32_16x16x32_bf16 v[78:81], v[14:17], v[46:49], v[78:81]
	v_mfma_f32_16x16x32_bf16 v[82:85], v[22:25], v[46:49], v[82:85]
	v_mfma_f32_16x16x32_bf16 v[86:89], v[14:17], v[54:57], v[86:89]
	v_mfma_f32_16x16x32_bf16 v[90:93], v[22:25], v[54:57], v[90:93]
	v_mfma_f32_16x16x32_bf16 v[94:97], v[14:17], v[66:69], v[94:97]
	v_mfma_f32_16x16x32_bf16 v[98:101], v[22:25], v[66:69], v[98:101]
	v_mfma_f32_16x16x32_bf16 v[102:105], v[26:29], v[0:3], 0
	v_mfma_f32_16x16x32_bf16 v[0:3], v[34:37], v[0:3], 0
	v_mfma_f32_16x16x32_bf16 v[106:109], v[38:41], v[4:7], v[0:3]
	v_mfma_f32_16x16x32_bf16 v[0:3], v[26:29], v[42:45], 0
	v_mfma_f32_16x16x32_bf16 v[110:113], v[30:33], v[46:49], v[0:3]
	v_mfma_f32_16x16x32_bf16 v[0:3], v[34:37], v[42:45], 0
	v_mfma_f32_16x16x32_bf16 v[42:45], v[38:41], v[46:49], v[0:3]
	v_mfma_f32_16x16x32_bf16 v[0:3], v[26:29], v[50:53], 0
	v_mfma_f32_16x16x32_bf16 v[46:49], v[30:33], v[54:57], v[0:3]
	v_mfma_f32_16x16x32_bf16 v[0:3], v[34:37], v[50:53], 0
	v_mfma_f32_16x16x32_bf16 v[50:53], v[38:41], v[54:57], v[0:3]
	v_mfma_f32_16x16x32_bf16 v[0:3], v[26:29], v[58:61], 0
	v_mfma_f32_16x16x32_bf16 v[54:57], v[30:33], v[66:69], v[0:3]
	v_mfma_f32_16x16x32_bf16 v[0:3], v[34:37], v[58:61], 0
	v_mfma_f32_16x16x32_bf16 v[102:105], v[30:33], v[4:7], v[102:105]
	v_mfma_f32_16x16x32_bf16 v[58:61], v[38:41], v[66:69], v[0:3]
	s_barrier
	s_setprio 0
	s_nop 3
	v_lshl_add_u64 v[0:1], s[16:17], 0, v[134:135]
	s_mov_b64 s[52:53], 0x100
	s_add_i32 s47, s47, s22
	v_lshl_add_u64 v[2:3], v[0:1], 0, s[52:53]
	s_mov_b32 m0, s47
	s_add_i32 s3, s47, 0x2000
	ds_read_b128 v[66:69], v142 offset:16384
	ds_read_b128 v[114:117], v142 offset:17408
	ds_read_b128 v[118:121], v142 offset:18432
	ds_read_b128 v[122:125], v142 offset:19456
	ds_read_b128 v[126:129], v142 offset:20480
	ds_read_b128 v[144:147], v142 offset:21504
	ds_read_b128 v[148:151], v142 offset:22528
	ds_read_b128 v[152:155], v142 offset:23552
	global_load_lds_dwordx4 v[2:3], off
	v_lshl_add_u64 v[2:3], s[16:17], 0, v[130:131]
	s_add_u32 s48, s16, 0x18100
	v_lshl_add_u64 v[4:5], v[2:3], 0, s[52:53]
	s_mov_b32 m0, s3
	s_addc_u32 s49, s17, 0
	s_add_i32 s45, s45, s22
	global_load_lds_dwordx4 v[4:5], off
	v_lshl_add_u64 v[4:5], s[48:49], 0, v[134:135]
	s_mov_b32 m0, s45
	s_add_i32 s46, s45, 0x2000
	global_load_lds_dwordx4 v[4:5], off
	v_lshl_add_u64 v[4:5], s[48:49], 0, v[130:131]
	s_mov_b32 m0, s46
	s_nop 0
	global_load_lds_dwordx4 v[4:5], off
	v_lshl_add_u64 v[4:5], s[14:15], 0, v[136:137]
	v_lshl_add_u64 v[6:7], v[4:5], 0, s[52:53]
	s_mov_b32 m0, s23
	s_nop 0
	global_load_lds_dwordx4 v[6:7], off
	v_lshl_add_u64 v[6:7], s[14:15], 0, v[132:133]
	v_lshl_add_u64 v[62:63], v[6:7], 0, s[52:53]
	s_mov_b32 m0, s24
	s_nop 0
	global_load_lds_dwordx4 v[62:63], off
	s_waitcnt vmcnt(8)
	s_waitcnt lgkmcnt(0)
	s_setprio 1
	s_barrier
	v_mfma_f32_16x16x32_bf16 v[156:159], v[10:13], v[66:69], 0
	v_mfma_f32_16x16x32_bf16 v[164:167], v[10:13], v[118:121], 0
	v_mfma_f32_16x16x32_bf16 v[172:175], v[10:13], v[126:129], 0
	v_mfma_f32_16x16x32_bf16 v[10:13], v[10:13], v[148:151], 0
	v_mfma_f32_16x16x32_bf16 v[156:159], v[14:17], v[114:117], v[156:159]
	v_mfma_f32_16x16x32_bf16 v[160:163], v[18:21], v[66:69], 0
	v_mfma_f32_16x16x32_bf16 v[164:167], v[14:17], v[122:125], v[164:167]
	v_mfma_f32_16x16x32_bf16 v[168:171], v[18:21], v[118:121], 0
	v_mfma_f32_16x16x32_bf16 v[172:175], v[14:17], v[144:147], v[172:175]
	v_mfma_f32_16x16x32_bf16 v[176:179], v[18:21], v[126:129], 0
	v_mfma_f32_16x16x32_bf16 v[12:15], v[14:17], v[152:155], v[10:13]
	v_mfma_f32_16x16x32_bf16 v[16:19], v[18:21], v[148:151], 0
	v_mfma_f32_16x16x32_bf16 v[16:19], v[22:25], v[152:155], v[16:19]
	v_mfma_f32_16x16x32_bf16 v[160:163], v[22:25], v[114:117], v[160:163]
	v_mfma_f32_16x16x32_bf16 v[168:171], v[22:25], v[122:125], v[168:171]
	v_mfma_f32_16x16x32_bf16 v[176:179], v[22:25], v[144:147], v[176:179]
	v_mfma_f32_16x16x32_bf16 v[20:23], v[26:29], v[66:69], 0
	v_mfma_f32_16x16x32_bf16 v[66:69], v[34:37], v[66:69], 0
	v_mfma_f32_16x16x32_bf16 v[20:23], v[30:33], v[114:117], v[20:23]
	v_mfma_f32_16x16x32_bf16 v[66:69], v[38:41], v[114:117], v[66:69]
	v_mfma_f32_16x16x32_bf16 v[114:117], v[26:29], v[118:121], 0
	v_mfma_f32_16x16x32_bf16 v[118:121], v[34:37], v[118:121], 0
	v_mfma_f32_16x16x32_bf16 v[114:117], v[30:33], v[122:125], v[114:117]
	v_mfma_f32_16x16x32_bf16 v[118:121], v[38:41], v[122:125], v[118:121]
	v_mfma_f32_16x16x32_bf16 v[122:125], v[26:29], v[126:129], 0
	v_mfma_f32_16x16x32_bf16 v[24:27], v[26:29], v[148:151], 0
	v_mfma_f32_16x16x32_bf16 v[122:125], v[30:33], v[144:147], v[122:125]
	v_mfma_f32_16x16x32_bf16 v[126:129], v[34:37], v[126:129], 0
	v_mfma_f32_16x16x32_bf16 v[24:27], v[30:33], v[152:155], v[24:27]
	v_mfma_f32_16x16x32_bf16 v[28:31], v[34:37], v[148:151], 0
	v_mfma_f32_16x16x32_bf16 v[126:129], v[38:41], v[144:147], v[126:129]
	v_mfma_f32_16x16x32_bf16 v[28:31], v[38:41], v[152:155], v[28:31]
	s_barrier
; #define PG8_STAGE(bufoff, gbase, voff) do { _Pragma("unroll") for (int _i = 0; _i < 2; ++_i) \
;         __builtin_amdgcn_global_load_lds((const unsigned*)((const char*)(gbase) + (voff)[_i]), (PG8_LAS unsigned*)(lds + (bufoff) + ldsw + _i * 8192), 16, 0, 0); } while (0)
; #define PG8_LDA(dst, b, h) do { _Pragma("unroll") for (int m = 0; m < 4; ++m) _Pragma("unroll") for (int k = 0; k < 2; ++k) dst[m][k] = *(const PG8_LAS bf16x8*)(lds + PG8_SA(b, h) + aoff + m * 2048 + k * 1024); } while (0)
; #define PG8_LDB(dst, b, h) do { _Pragma("unroll") for (int n = 0; n < 2; ++n) _Pragma("unroll") for (int k = 0; k < 2; ++k) dst[n][k] = *(const PG8_LAS bf16x8*)(lds + PG8_SB(b, h) + boff + n * 2048 + k * 1024); } while (0)
; #define PG8_MMA(ai, bj, At, Bt) do { __builtin_amdgcn_s_setprio(1); _Pragma("unroll") for (int m = 0; m < 4; ++m) _Pragma("unroll") for (int n = 0; n < 2; ++n) _Pragma("unroll") for (int k = 0; k < 2; ++k) \
;         acc[ai][bj][m][n] = __builtin_amdgcn_mfma_f32_16x16x32_bf16(Bt[n][k], At[m][k], acc[ai][bj][m][n], 0, 0, 0); __builtin_amdgcn_s_setprio(0); } while (0)
; #define PG8_WAIT_V(n) asm volatile("s_waitcnt vmcnt(" #n ")" ::: "memory")
; #define PG8_WAIT_L(n) asm volatile("s_waitcnt lgkmcnt(" #n ")" ::: "memory")
; #define PG8_BAR __builtin_amdgcn_s_barrier()
; #define PG8_SCHED __builtin_amdgcn_sched_barrier(0)
; template <class Epi, class Sched, bool ALIGN_EPI = false, bool SP2 = false>
; __device__ __forceinline__ void gemm_phase(PG8_LAS unsigned char* lds, const Gemm g, const Sched& S, const Epi& E, const int tid) {
;     ...
;             PG8_WAIT_V(8); PG8_WAIT_L(0); PG8_BAR; PG8_MMA(1, 0, At, B0); PG8_MMA(1, 1, At, B1); PG8_BAR; PG8_SCHED;
;             PG8_LDB(B0, 1, 0); PG8_LDB(B1, 1, 1); PG8_SCHED; PG8_LDA(At, 1, 0); PG8_STAGE(PG8_SA(0, 1), a2 + hstep, voffA);
;             PG8_WAIT_V(8); PG8_WAIT_L(0); PG8_BAR; PG8_MMA(0, 0, At, B0); PG8_MMA(0, 1, At, B1); PG8_BAR; PG8_SCHED;
	s_setprio 0
	s_add_i32 s52, 0, 0x18000
	s_add_i32 s51, 0, 0x1c000
	v_add_u32_e32 v10, s52, v141
	v_add_u32_e32 v11, s51, v141
	ds_read_b128 v[32:35], v10
	ds_read_b128 v[36:39], v10 offset:1024
	ds_read_b128 v[144:147], v10 offset:2048
	ds_read_b128 v[148:151], v10 offset:3072
	ds_read_b128 v[152:155], v11
	ds_read_b128 v[180:183], v11 offset:1024
	ds_read_b128 v[184:187], v11 offset:2048
	ds_read_b128 v[188:191], v11 offset:3072
	s_add_u32 s48, s14, 0x18100
	s_addc_u32 s49, s15, 0
	s_mov_b32 m0, s25
	v_lshl_add_u64 v[40:41], s[48:49], 0, v[136:137]
	ds_read_b128 v[192:195], v142 offset:32768
	ds_read_b128 v[196:199], v142 offset:33792
	ds_read_b128 v[214:217], v142 offset:34816
	ds_read_b128 v[218:221], v142 offset:35840
	ds_read_b128 v[222:225], v142 offset:36864
	ds_read_b128 v[226:229], v142 offset:37888
	ds_read_b128 v[248:251], v142 offset:38912
	ds_read_b128 v[206:209], v142 offset:39936
	global_load_lds_dwordx4 v[40:41], off
	v_lshl_add_u64 v[40:41], s[48:49], 0, v[132:133]
	s_mov_b32 m0, s26
	s_nop 0
	global_load_lds_dwordx4 v[40:41], off
	s_waitcnt vmcnt(8)
	s_waitcnt lgkmcnt(0)
	s_setprio 1
	s_barrier
	v_mfma_f32_16x16x32_bf16 v[70:73], v[32:35], v[192:195], v[70:73]
	v_mfma_f32_16x16x32_bf16 v[74:77], v[144:147], v[192:195], v[74:77]
	v_mfma_f32_16x16x32_bf16 v[78:81], v[32:35], v[214:217], v[78:81]
	v_mfma_f32_16x16x32_bf16 v[82:85], v[144:147], v[214:217], v[82:85]
	v_mfma_f32_16x16x32_bf16 v[86:89], v[32:35], v[222:225], v[86:89]
	v_mfma_f32_16x16x32_bf16 v[90:93], v[144:147], v[222:225], v[90:93]
	v_mfma_f32_16x16x32_bf16 v[94:97], v[32:35], v[248:251], v[94:97]
	v_mfma_f32_16x16x32_bf16 v[98:101], v[144:147], v[248:251], v[98:101]
	v_mfma_f32_16x16x32_bf16 v[70:73], v[36:39], v[196:199], v[70:73]
	v_mfma_f32_16x16x32_bf16 v[74:77], v[148:151], v[196:199], v[74:77]
	v_mfma_f32_16x16x32_bf16 v[78:81], v[36:39], v[218:221], v[78:81]
	v_mfma_f32_16x16x32_bf16 v[82:85], v[148:151], v[218:221], v[82:85]
	v_mfma_f32_16x16x32_bf16 v[86:89], v[36:39], v[226:229], v[86:89]
	v_mfma_f32_16x16x32_bf16 v[90:93], v[148:151], v[226:229], v[90:93]
	v_mfma_f32_16x16x32_bf16 v[94:97], v[36:39], v[206:209], v[94:97]
	v_mfma_f32_16x16x32_bf16 v[98:101], v[148:151], v[206:209], v[98:101]
	v_mfma_f32_16x16x32_bf16 v[102:105], v[152:155], v[192:195], v[102:105]
	v_mfma_f32_16x16x32_bf16 v[106:109], v[184:187], v[192:195], v[106:109]
	v_mfma_f32_16x16x32_bf16 v[110:113], v[152:155], v[214:217], v[110:113]
	v_mfma_f32_16x16x32_bf16 v[40:43], v[184:187], v[214:217], v[42:45]
	v_mfma_f32_16x16x32_bf16 v[44:47], v[152:155], v[222:225], v[46:49]
	v_mfma_f32_16x16x32_bf16 v[48:51], v[184:187], v[222:225], v[50:53]
	v_mfma_f32_16x16x32_bf16 v[52:55], v[152:155], v[248:251], v[54:57]
	v_mfma_f32_16x16x32_bf16 v[56:59], v[184:187], v[248:251], v[58:61]
	v_mfma_f32_16x16x32_bf16 v[102:105], v[180:183], v[196:199], v[102:105]
	v_mfma_f32_16x16x32_bf16 v[106:109], v[188:191], v[196:199], v[106:109]
	v_mfma_f32_16x16x32_bf16 v[110:113], v[180:183], v[218:221], v[110:113]
	v_mfma_f32_16x16x32_bf16 v[40:43], v[188:191], v[218:221], v[40:43]
	v_mfma_f32_16x16x32_bf16 v[44:47], v[180:183], v[226:229], v[44:47]
	v_mfma_f32_16x16x32_bf16 v[48:51], v[188:191], v[226:229], v[48:51]
	v_mfma_f32_16x16x32_bf16 v[52:55], v[180:183], v[206:209], v[52:55]
	v_mfma_f32_16x16x32_bf16 v[56:59], v[188:191], v[206:209], v[56:59]
	s_barrier
	s_setprio 0
	s_add_i32 s52, s52, s22
	s_mov_b64 s[56:57], 0x180
	s_add_i32 s48, s52, 0x2000
	v_lshl_add_u64 v[138:139], v[0:1], 0, s[56:57]
	s_mov_b32 m0, s52
	s_add_u32 s54, s16, 0x18180
	ds_read_b128 v[60:63], v142 offset:49152
	ds_read_b128 v[192:195], v142 offset:50176
	ds_read_b128 v[196:199], v142 offset:51200
	ds_read_b128 v[206:209], v142 offset:52224
	ds_read_b128 v[214:217], v142 offset:53248
	ds_read_b128 v[218:221], v142 offset:54272
	ds_read_b128 v[222:225], v142 offset:55296
	ds_read_b128 v[226:229], v142 offset:56320
	global_load_lds_dwordx4 v[138:139], off
	v_lshl_add_u64 v[138:139], v[2:3], 0, s[56:57]
	s_mov_b32 m0, s48
	s_addc_u32 s55, s17, 0
	s_add_i32 s49, s51, s22
	global_load_lds_dwordx4 v[138:139], off
	v_lshl_add_u64 v[138:139], s[54:55], 0, v[134:135]
	s_mov_b32 m0, s49
	s_add_i32 s51, s49, 0x2000
	global_load_lds_dwordx4 v[138:139], off
	v_lshl_add_u64 v[138:139], s[54:55], 0, v[130:131]
	s_mov_b32 m0, s51
	s_nop 0
	global_load_lds_dwordx4 v[138:139], off
	v_lshl_add_u64 v[138:139], v[4:5], 0, s[56:57]
	s_mov_b32 m0, s28
	s_nop 0
	global_load_lds_dwordx4 v[138:139], off
	v_lshl_add_u64 v[138:139], v[6:7], 0, s[56:57]
	s_mov_b32 m0, s29
	s_nop 0
	global_load_lds_dwordx4 v[138:139], off
	s_waitcnt vmcnt(8)
	s_waitcnt lgkmcnt(0)
	s_setprio 1
	s_barrier
	v_mfma_f32_16x16x32_bf16 v[12:15], v[32:35], v[222:225], v[12:15]
	v_mfma_f32_16x16x32_bf16 v[16:19], v[144:147], v[222:225], v[16:19]
	v_mfma_f32_16x16x32_bf16 v[156:159], v[32:35], v[60:63], v[156:159]
	v_mfma_f32_16x16x32_bf16 v[160:163], v[144:147], v[60:63], v[160:163]
	v_mfma_f32_16x16x32_bf16 v[164:167], v[32:35], v[196:199], v[164:167]
	v_mfma_f32_16x16x32_bf16 v[168:171], v[144:147], v[196:199], v[168:171]
	v_mfma_f32_16x16x32_bf16 v[172:175], v[32:35], v[214:217], v[172:175]
	v_mfma_f32_16x16x32_bf16 v[176:179], v[144:147], v[214:217], v[176:179]
	v_mfma_f32_16x16x32_bf16 v[12:15], v[36:39], v[226:229], v[12:15]
	v_mfma_f32_16x16x32_bf16 v[16:19], v[148:151], v[226:229], v[16:19]
	v_mfma_f32_16x16x32_bf16 v[156:159], v[36:39], v[192:195], v[156:159]
	v_mfma_f32_16x16x32_bf16 v[160:163], v[148:151], v[192:195], v[160:163]
	v_mfma_f32_16x16x32_bf16 v[164:167], v[36:39], v[206:209], v[164:167]
	v_mfma_f32_16x16x32_bf16 v[168:171], v[148:151], v[206:209], v[168:171]
	v_mfma_f32_16x16x32_bf16 v[172:175], v[36:39], v[218:221], v[172:175]
	v_mfma_f32_16x16x32_bf16 v[176:179], v[148:151], v[218:221], v[176:179]
	v_mfma_f32_16x16x32_bf16 v[20:23], v[152:155], v[60:63], v[20:23]
	v_mfma_f32_16x16x32_bf16 v[32:35], v[184:187], v[60:63], v[66:69]
	v_mfma_f32_16x16x32_bf16 v[36:39], v[152:155], v[196:199], v[114:117]
	v_mfma_f32_16x16x32_bf16 v[60:63], v[184:187], v[196:199], v[118:121]
	v_mfma_f32_16x16x32_bf16 v[66:69], v[152:155], v[214:217], v[122:125]
	v_mfma_f32_16x16x32_bf16 v[114:117], v[184:187], v[214:217], v[126:129]
	v_mfma_f32_16x16x32_bf16 v[24:27], v[152:155], v[222:225], v[24:27]
	v_mfma_f32_16x16x32_bf16 v[28:31], v[184:187], v[222:225], v[28:31]
	v_mfma_f32_16x16x32_bf16 v[20:23], v[180:183], v[192:195], v[20:23]
	v_mfma_f32_16x16x32_bf16 v[32:35], v[188:191], v[192:195], v[32:35]
	v_mfma_f32_16x16x32_bf16 v[36:39], v[180:183], v[206:209], v[36:39]
	v_mfma_f32_16x16x32_bf16 v[60:63], v[188:191], v[206:209], v[60:63]
	v_mfma_f32_16x16x32_bf16 v[66:69], v[180:183], v[218:221], v[66:69]
	v_mfma_f32_16x16x32_bf16 v[114:117], v[188:191], v[218:221], v[114:117]
	v_mfma_f32_16x16x32_bf16 v[24:27], v[180:183], v[226:229], v[24:27]
	v_mfma_f32_16x16x32_bf16 v[28:31], v[188:191], v[226:229], v[28:31]
	s_barrier
	s_setprio 0
	ds_read_b128 v[118:121], v8
	ds_read_b128 v[122:125], v8 offset:1024
	ds_read_b128 v[126:129], v8 offset:2048
	ds_read_b128 v[144:147], v8 offset:3072
	ds_read_b128 v[148:151], v9
	ds_read_b128 v[152:155], v9 offset:1024
	ds_read_b128 v[180:183], v9 offset:2048
	ds_read_b128 v[184:187], v9 offset:3072
	s_add_u32 s54, s14, 0x18180
	s_addc_u32 s55, s15, 0
	s_mov_b32 m0, s50
	v_lshl_add_u64 v[138:139], s[54:55], 0, v[136:137]
	ds_read_b128 v[188:191], v142
	ds_read_b128 v[192:195], v142 offset:1024
	ds_read_b128 v[196:199], v142 offset:2048
	ds_read_b128 v[206:209], v142 offset:3072
	ds_read_b128 v[214:217], v142 offset:4096
	ds_read_b128 v[218:221], v142 offset:5120
	ds_read_b128 v[222:225], v142 offset:6144
	ds_read_b128 v[226:229], v142 offset:7168
	global_load_lds_dwordx4 v[138:139], off
	v_lshl_add_u64 v[138:139], s[54:55], 0, v[132:133]
	s_mov_b32 m0, s2
	s_nop 0
	global_load_lds_dwordx4 v[138:139], off
	s_waitcnt vmcnt(8)
	s_waitcnt lgkmcnt(0)
	s_setprio 1
	s_barrier
	v_mfma_f32_16x16x32_bf16 v[70:73], v[118:121], v[188:191], v[70:73]
	v_mfma_f32_16x16x32_bf16 v[74:77], v[126:129], v[188:191], v[74:77]
	v_mfma_f32_16x16x32_bf16 v[78:81], v[118:121], v[196:199], v[78:81]
	v_mfma_f32_16x16x32_bf16 v[82:85], v[126:129], v[196:199], v[82:85]
	v_mfma_f32_16x16x32_bf16 v[86:89], v[118:121], v[214:217], v[86:89]
	v_mfma_f32_16x16x32_bf16 v[90:93], v[126:129], v[214:217], v[90:93]
	v_mfma_f32_16x16x32_bf16 v[94:97], v[118:121], v[222:225], v[94:97]
	v_mfma_f32_16x16x32_bf16 v[98:101], v[126:129], v[222:225], v[98:101]
	v_mfma_f32_16x16x32_bf16 v[70:73], v[122:125], v[192:195], v[70:73]
	v_mfma_f32_16x16x32_bf16 v[74:77], v[144:147], v[192:195], v[74:77]
	v_mfma_f32_16x16x32_bf16 v[78:81], v[122:125], v[206:209], v[78:81]
	v_mfma_f32_16x16x32_bf16 v[82:85], v[144:147], v[206:209], v[82:85]
	v_mfma_f32_16x16x32_bf16 v[86:89], v[122:125], v[218:221], v[86:89]
	v_mfma_f32_16x16x32_bf16 v[90:93], v[144:147], v[218:221], v[90:93]
	v_mfma_f32_16x16x32_bf16 v[94:97], v[122:125], v[226:229], v[94:97]
	v_mfma_f32_16x16x32_bf16 v[98:101], v[144:147], v[226:229], v[98:101]
	v_mfma_f32_16x16x32_bf16 v[102:105], v[148:151], v[188:191], v[102:105]
	v_mfma_f32_16x16x32_bf16 v[106:109], v[180:183], v[188:191], v[106:109]
	v_mfma_f32_16x16x32_bf16 v[110:113], v[148:151], v[196:199], v[110:113]
	v_mfma_f32_16x16x32_bf16 v[40:43], v[180:183], v[196:199], v[40:43]
	v_mfma_f32_16x16x32_bf16 v[44:47], v[148:151], v[214:217], v[44:47]
	v_mfma_f32_16x16x32_bf16 v[48:51], v[180:183], v[214:217], v[48:51]
	v_mfma_f32_16x16x32_bf16 v[52:55], v[148:151], v[222:225], v[52:55]
	v_mfma_f32_16x16x32_bf16 v[56:59], v[180:183], v[222:225], v[56:59]
	v_mfma_f32_16x16x32_bf16 v[102:105], v[152:155], v[192:195], v[102:105]
	v_mfma_f32_16x16x32_bf16 v[106:109], v[184:187], v[192:195], v[106:109]
	v_mfma_f32_16x16x32_bf16 v[110:113], v[152:155], v[206:209], v[110:113]
	v_mfma_f32_16x16x32_bf16 v[40:43], v[184:187], v[206:209], v[40:43]
	v_mfma_f32_16x16x32_bf16 v[44:47], v[152:155], v[218:221], v[44:47]
	v_mfma_f32_16x16x32_bf16 v[48:51], v[184:187], v[218:221], v[48:51]
	v_mfma_f32_16x16x32_bf16 v[52:55], v[152:155], v[226:229], v[52:55]
	v_mfma_f32_16x16x32_bf16 v[56:59], v[184:187], v[226:229], v[56:59]
	s_barrier
; #define PG8_STAGE(bufoff, gbase, voff) do { _Pragma("unroll") for (int _i = 0; _i < 2; ++_i) \
;         __builtin_amdgcn_global_load_lds((const unsigned*)((const char*)(gbase) + (voff)[_i]), (PG8_LAS unsigned*)(lds + (bufoff) + ldsw + _i * 8192), 16, 0, 0); } while (0)
; #define PG8_LDA(dst, b, h) do { _Pragma("unroll") for (int m = 0; m < 4; ++m) _Pragma("unroll") for (int k = 0; k < 2; ++k) dst[m][k] = *(const PG8_LAS bf16x8*)(lds + PG8_SA(b, h) + aoff + m * 2048 + k * 1024); } while (0)
; #define PG8_LDB(dst, b, h) do { _Pragma("unroll") for (int n = 0; n < 2; ++n) _Pragma("unroll") for (int k = 0; k < 2; ++k) dst[n][k] = *(const PG8_LAS bf16x8*)(lds + PG8_SB(b, h) + boff + n * 2048 + k * 1024); } while (0)
; #define PG8_MMA(ai, bj, At, Bt) do { __builtin_amdgcn_s_setprio(1); _Pragma("unroll") for (int m = 0; m < 4; ++m) _Pragma("unroll") for (int n = 0; n < 2; ++n) _Pragma("unroll") for (int k = 0; k < 2; ++k) \
;         acc[ai][bj][m][n] = __builtin_amdgcn_mfma_f32_16x16x32_bf16(Bt[n][k], At[m][k], acc[ai][bj][m][n], 0, 0, 0); __builtin_amdgcn_s_setprio(0); } while (0)
; #define PG8_WAIT_V(n) asm volatile("s_waitcnt vmcnt(" #n ")" ::: "memory")
; #define PG8_WAIT_L(n) asm volatile("s_waitcnt lgkmcnt(" #n ")" ::: "memory")
; #define PG8_BAR __builtin_amdgcn_s_barrier()
; #define PG8_SCHED __builtin_amdgcn_sched_barrier(0)
; template <class Epi, class Sched, bool ALIGN_EPI = false, bool SP2 = false>
; __device__ __forceinline__ void gemm_phase(PG8_LAS unsigned char* lds, const Gemm g, const Sched& S, const Epi& E, const int tid) {
;     ...
;             PG8_LDA(At, 0, 1); PG8_STAGE(PG8_SB(0, 0), b2, voffB); PG8_STAGE(PG8_SB(0, 1), b2 + hstep, voffB); PG8_STAGE(PG8_SA(0, 0), a2, voffA);
;             PG8_WAIT_V(8); PG8_WAIT_L(0); PG8_BAR; PG8_MMA(1, 0, At, B0); PG8_MMA(1, 1, At, B1); PG8_BAR; PG8_SCHED;
;             PG8_LDB(B0, 1, 0); PG8_LDB(B1, 1, 1); PG8_SCHED; PG8_LDA(At, 1, 0); PG8_STAGE(PG8_SA(0, 1), a2 + hstep, voffA);
;             PG8_WAIT_V(8); PG8_WAIT_L(0); PG8_BAR; PG8_MMA(0, 0, At, B0); PG8_MMA(0, 1, At, B1); PG8_BAR; PG8_SCHED;
	s_setprio 0
	s_mov_b64 s[56:57], 0x200
	s_mov_b32 m0, s47
	v_lshl_add_u64 v[138:139], v[0:1], 0, s[56:57]
	s_add_u32 s54, s16, 0x18200
	ds_read_b128 v[188:191], v142 offset:16384
	ds_read_b128 v[192:195], v142 offset:17408
	ds_read_b128 v[196:199], v142 offset:18432
	ds_read_b128 v[206:209], v142 offset:19456
	ds_read_b128 v[214:217], v142 offset:20480
	ds_read_b128 v[218:221], v142 offset:21504
	ds_read_b128 v[222:225], v142 offset:22528
	ds_read_b128 v[226:229], v142 offset:23552
	global_load_lds_dwordx4 v[138:139], off
	v_lshl_add_u64 v[138:139], v[2:3], 0, s[56:57]
	s_mov_b32 m0, s3
	s_addc_u32 s55, s17, 0
	global_load_lds_dwordx4 v[138:139], off
	v_lshl_add_u64 v[138:139], s[54:55], 0, v[134:135]
	s_mov_b32 m0, s45
	s_nop 0
	global_load_lds_dwordx4 v[138:139], off
	v_lshl_add_u64 v[138:139], s[54:55], 0, v[130:131]
	s_mov_b32 m0, s46
	s_nop 0
	global_load_lds_dwordx4 v[138:139], off
	v_lshl_add_u64 v[138:139], v[4:5], 0, s[56:57]
	s_mov_b32 m0, s23
	s_nop 0
	global_load_lds_dwordx4 v[138:139], off
	v_lshl_add_u64 v[138:139], v[6:7], 0, s[56:57]
	s_mov_b32 m0, s24
	s_nop 0
	global_load_lds_dwordx4 v[138:139], off
	s_waitcnt vmcnt(8)
	s_waitcnt lgkmcnt(0)
	s_setprio 1
	s_barrier
	v_mfma_f32_16x16x32_bf16 v[12:15], v[118:121], v[222:225], v[12:15]
	v_mfma_f32_16x16x32_bf16 v[16:19], v[126:129], v[222:225], v[16:19]
	v_mfma_f32_16x16x32_bf16 v[156:159], v[118:121], v[188:191], v[156:159]
	v_mfma_f32_16x16x32_bf16 v[160:163], v[126:129], v[188:191], v[160:163]
	v_mfma_f32_16x16x32_bf16 v[164:167], v[118:121], v[196:199], v[164:167]
	v_mfma_f32_16x16x32_bf16 v[168:171], v[126:129], v[196:199], v[168:171]
	v_mfma_f32_16x16x32_bf16 v[172:175], v[118:121], v[214:217], v[172:175]
	v_mfma_f32_16x16x32_bf16 v[176:179], v[126:129], v[214:217], v[176:179]
	v_mfma_f32_16x16x32_bf16 v[12:15], v[122:125], v[226:229], v[12:15]
	v_mfma_f32_16x16x32_bf16 v[16:19], v[144:147], v[226:229], v[16:19]
	v_mfma_f32_16x16x32_bf16 v[156:159], v[122:125], v[192:195], v[156:159]
	v_mfma_f32_16x16x32_bf16 v[160:163], v[144:147], v[192:195], v[160:163]
	v_mfma_f32_16x16x32_bf16 v[164:167], v[122:125], v[206:209], v[164:167]
	v_mfma_f32_16x16x32_bf16 v[168:171], v[144:147], v[206:209], v[168:171]
	v_mfma_f32_16x16x32_bf16 v[172:175], v[122:125], v[218:221], v[172:175]
	v_mfma_f32_16x16x32_bf16 v[176:179], v[144:147], v[218:221], v[176:179]
	v_mfma_f32_16x16x32_bf16 v[20:23], v[148:151], v[188:191], v[20:23]
	v_mfma_f32_16x16x32_bf16 v[32:35], v[180:183], v[188:191], v[32:35]
	v_mfma_f32_16x16x32_bf16 v[36:39], v[148:151], v[196:199], v[36:39]
	v_mfma_f32_16x16x32_bf16 v[60:63], v[180:183], v[196:199], v[60:63]
	v_mfma_f32_16x16x32_bf16 v[66:69], v[148:151], v[214:217], v[66:69]
	v_mfma_f32_16x16x32_bf16 v[114:117], v[180:183], v[214:217], v[114:117]
	v_mfma_f32_16x16x32_bf16 v[24:27], v[148:151], v[222:225], v[24:27]
	v_mfma_f32_16x16x32_bf16 v[28:31], v[180:183], v[222:225], v[28:31]
	v_mfma_f32_16x16x32_bf16 v[20:23], v[152:155], v[192:195], v[20:23]
	v_mfma_f32_16x16x32_bf16 v[32:35], v[184:187], v[192:195], v[32:35]
	v_mfma_f32_16x16x32_bf16 v[36:39], v[152:155], v[206:209], v[36:39]
	v_mfma_f32_16x16x32_bf16 v[60:63], v[184:187], v[206:209], v[60:63]
	v_mfma_f32_16x16x32_bf16 v[66:69], v[152:155], v[218:221], v[66:69]
	v_mfma_f32_16x16x32_bf16 v[114:117], v[184:187], v[218:221], v[114:117]
	v_mfma_f32_16x16x32_bf16 v[24:27], v[152:155], v[226:229], v[24:27]
	v_mfma_f32_16x16x32_bf16 v[28:31], v[184:187], v[226:229], v[28:31]
	s_barrier
	s_setprio 0
	ds_read_b128 v[118:121], v10
	ds_read_b128 v[122:125], v10 offset:1024
	ds_read_b128 v[126:129], v10 offset:2048
	ds_read_b128 v[144:147], v10 offset:3072
	ds_read_b128 v[148:151], v11
	ds_read_b128 v[152:155], v11 offset:1024
	ds_read_b128 v[180:183], v11 offset:2048
	ds_read_b128 v[184:187], v11 offset:3072
	s_add_u32 s54, s14, 0x18200
	s_addc_u32 s55, s15, 0
	s_mov_b32 m0, s25
	v_lshl_add_u64 v[138:139], s[54:55], 0, v[136:137]
	ds_read_b128 v[188:191], v142 offset:32768
	ds_read_b128 v[192:195], v142 offset:33792
	ds_read_b128 v[196:199], v142 offset:34816
	ds_read_b128 v[206:209], v142 offset:35840
	ds_read_b128 v[214:217], v142 offset:36864
	ds_read_b128 v[218:221], v142 offset:37888
	ds_read_b128 v[222:225], v142 offset:38912
	ds_read_b128 v[226:229], v142 offset:39936
	global_load_lds_dwordx4 v[138:139], off
	v_lshl_add_u64 v[138:139], s[54:55], 0, v[132:133]
	s_mov_b32 m0, s26
	s_nop 0
	global_load_lds_dwordx4 v[138:139], off
	s_waitcnt vmcnt(8)
	s_waitcnt lgkmcnt(0)
	s_setprio 1
	s_barrier
	v_mfma_f32_16x16x32_bf16 v[70:73], v[118:121], v[188:191], v[70:73]
	v_mfma_f32_16x16x32_bf16 v[74:77], v[126:129], v[188:191], v[74:77]
	v_mfma_f32_16x16x32_bf16 v[78:81], v[118:121], v[196:199], v[78:81]
	v_mfma_f32_16x16x32_bf16 v[82:85], v[126:129], v[196:199], v[82:85]
	v_mfma_f32_16x16x32_bf16 v[86:89], v[118:121], v[214:217], v[86:89]
	v_mfma_f32_16x16x32_bf16 v[90:93], v[126:129], v[214:217], v[90:93]
	v_mfma_f32_16x16x32_bf16 v[94:97], v[118:121], v[222:225], v[94:97]
	v_mfma_f32_16x16x32_bf16 v[98:101], v[126:129], v[222:225], v[98:101]
	v_mfma_f32_16x16x32_bf16 v[70:73], v[122:125], v[192:195], v[70:73]
	v_mfma_f32_16x16x32_bf16 v[74:77], v[144:147], v[192:195], v[74:77]
	v_mfma_f32_16x16x32_bf16 v[78:81], v[122:125], v[206:209], v[78:81]
	v_mfma_f32_16x16x32_bf16 v[82:85], v[144:147], v[206:209], v[82:85]
	v_mfma_f32_16x16x32_bf16 v[86:89], v[122:125], v[218:221], v[86:89]
	v_mfma_f32_16x16x32_bf16 v[90:93], v[144:147], v[218:221], v[90:93]
	v_mfma_f32_16x16x32_bf16 v[94:97], v[122:125], v[226:229], v[94:97]
	v_mfma_f32_16x16x32_bf16 v[98:101], v[144:147], v[226:229], v[98:101]
	v_mfma_f32_16x16x32_bf16 v[102:105], v[148:151], v[188:191], v[102:105]
	v_mfma_f32_16x16x32_bf16 v[106:109], v[180:183], v[188:191], v[106:109]
	v_mfma_f32_16x16x32_bf16 v[110:113], v[148:151], v[196:199], v[110:113]
	v_mfma_f32_16x16x32_bf16 v[40:43], v[180:183], v[196:199], v[40:43]
	v_mfma_f32_16x16x32_bf16 v[44:47], v[148:151], v[214:217], v[44:47]
	v_mfma_f32_16x16x32_bf16 v[48:51], v[180:183], v[214:217], v[48:51]
	v_mfma_f32_16x16x32_bf16 v[52:55], v[148:151], v[222:225], v[52:55]
	v_mfma_f32_16x16x32_bf16 v[56:59], v[180:183], v[222:225], v[56:59]
	v_mfma_f32_16x16x32_bf16 v[102:105], v[152:155], v[192:195], v[102:105]
	v_mfma_f32_16x16x32_bf16 v[106:109], v[184:187], v[192:195], v[106:109]
	v_mfma_f32_16x16x32_bf16 v[110:113], v[152:155], v[206:209], v[110:113]
	v_mfma_f32_16x16x32_bf16 v[40:43], v[184:187], v[206:209], v[40:43]
	v_mfma_f32_16x16x32_bf16 v[44:47], v[152:155], v[218:221], v[44:47]
	v_mfma_f32_16x16x32_bf16 v[48:51], v[184:187], v[218:221], v[48:51]
	v_mfma_f32_16x16x32_bf16 v[52:55], v[152:155], v[226:229], v[52:55]
	v_mfma_f32_16x16x32_bf16 v[56:59], v[184:187], v[226:229], v[56:59]
	s_barrier
; #define PG8_STAGE(bufoff, gbase, voff) do { _Pragma("unroll") for (int _i = 0; _i < 2; ++_i) \
;         __builtin_amdgcn_global_load_lds((const unsigned*)((const char*)(gbase) + (voff)[_i]), (PG8_LAS unsigned*)(lds + (bufoff) + ldsw + _i * 8192), 16, 0, 0); } while (0)
; #define PG8_LDA(dst, b, h) do { _Pragma("unroll") for (int m = 0; m < 4; ++m) _Pragma("unroll") for (int k = 0; k < 2; ++k) dst[m][k] = *(const PG8_LAS bf16x8*)(lds + PG8_SA(b, h) + aoff + m * 2048 + k * 1024); } while (0)
; #define PG8_LDB(dst, b, h) do { _Pragma("unroll") for (int n = 0; n < 2; ++n) _Pragma("unroll") for (int k = 0; k < 2; ++k) dst[n][k] = *(const PG8_LAS bf16x8*)(lds + PG8_SB(b, h) + boff + n * 2048 + k * 1024); } while (0)
; #define PG8_MMA(ai, bj, At, Bt) do { __builtin_amdgcn_s_setprio(1); _Pragma("unroll") for (int m = 0; m < 4; ++m) _Pragma("unroll") for (int n = 0; n < 2; ++n) _Pragma("unroll") for (int k = 0; k < 2; ++k) \
;         acc[ai][bj][m][n] = __builtin_amdgcn_mfma_f32_16x16x32_bf16(Bt[n][k], At[m][k], acc[ai][bj][m][n], 0, 0, 0); __builtin_amdgcn_s_setprio(0); } while (0)
; #define PG8_WAIT_V(n) asm volatile("s_waitcnt vmcnt(" #n ")" ::: "memory")
; #define PG8_WAIT_L(n) asm volatile("s_waitcnt lgkmcnt(" #n ")" ::: "memory")
; #define PG8_BAR __builtin_amdgcn_s_barrier()
; #define PG8_SCHED __builtin_amdgcn_sched_barrier(0)
; template <class Epi, class Sched, bool ALIGN_EPI = false, bool SP2 = false>
; __device__ __forceinline__ void gemm_phase(PG8_LAS unsigned char* lds, const Gemm g, const Sched& S, const Epi& E, const int tid) {
;     ...
;             PG8_LDA(At, 1, 1); PG8_STAGE(PG8_SB(1, 0), b3, voffB); PG8_STAGE(PG8_SB(1, 1), b3 + hstep, voffB); PG8_STAGE(PG8_SA(1, 0), a3, voffA);
;             PG8_WAIT_V(8); PG8_WAIT_L(0); PG8_BAR; PG8_MMA(1, 0, At, B0); PG8_MMA(1, 1, At, B1); PG8_BAR; PG8_SCHED;
;             } else {
;             PG8_LDB(B0, 0, 0); PG8_SCHED; PG8_LDA(At, 0, 0); PG8_STAGE(PG8_SA(1, 1), a1 + hstep, voffA);
	s_setprio 0
	s_mov_b64 s[54:55], 0x280
	s_mov_b32 m0, s52
	v_lshl_add_u64 v[0:1], v[0:1], 0, s[54:55]
	s_add_u32 s16, s16, 0x18280
	ds_read_b128 v[188:191], v142 offset:49152
	ds_read_b128 v[192:195], v142 offset:50176
	ds_read_b128 v[196:199], v142 offset:51200
	ds_read_b128 v[206:209], v142 offset:52224
	ds_read_b128 v[214:217], v142 offset:53248
	ds_read_b128 v[218:221], v142 offset:54272
	ds_read_b128 v[222:225], v142 offset:55296
	ds_read_b128 v[226:229], v142 offset:56320
	global_load_lds_dwordx4 v[0:1], off
	v_lshl_add_u64 v[0:1], v[2:3], 0, s[54:55]
	s_mov_b32 m0, s48
	s_addc_u32 s17, s17, 0
	global_load_lds_dwordx4 v[0:1], off
	v_lshl_add_u64 v[0:1], s[16:17], 0, v[134:135]
	s_mov_b32 m0, s49
	s_nop 0
	global_load_lds_dwordx4 v[0:1], off
	v_lshl_add_u64 v[0:1], s[16:17], 0, v[130:131]
	s_mov_b32 m0, s51
	s_nop 0
	global_load_lds_dwordx4 v[0:1], off
	v_lshl_add_u64 v[0:1], v[4:5], 0, s[54:55]
	s_mov_b32 m0, s28
	s_nop 0
	global_load_lds_dwordx4 v[0:1], off
	v_lshl_add_u64 v[0:1], v[6:7], 0, s[54:55]
	s_mov_b32 m0, s29
	s_nop 0
	global_load_lds_dwordx4 v[0:1], off
	s_waitcnt vmcnt(8)
	s_waitcnt lgkmcnt(0)
	s_setprio 1
	s_barrier
	v_mfma_f32_16x16x32_bf16 v[0:3], v[118:121], v[188:191], v[156:159]
	v_mfma_f32_16x16x32_bf16 v[4:7], v[126:129], v[188:191], v[160:163]
	v_mfma_f32_16x16x32_bf16 v[12:15], v[118:121], v[222:225], v[12:15]
	v_mfma_f32_16x16x32_bf16 v[16:19], v[126:129], v[222:225], v[16:19]
	v_mfma_f32_16x16x32_bf16 v[0:3], v[122:125], v[192:195], v[0:3]
	v_mfma_f32_16x16x32_bf16 v[4:7], v[144:147], v[192:195], v[4:7]
	v_mfma_f32_16x16x32_bf16 v[156:159], v[118:121], v[196:199], v[164:167]
	v_mfma_f32_16x16x32_bf16 v[160:163], v[126:129], v[196:199], v[168:171]
	v_mfma_f32_16x16x32_bf16 v[164:167], v[118:121], v[214:217], v[172:175]
	v_mfma_f32_16x16x32_bf16 v[168:171], v[126:129], v[214:217], v[176:179]
	v_mfma_f32_16x16x32_bf16 v[12:15], v[122:125], v[226:229], v[12:15]
	v_mfma_f32_16x16x32_bf16 v[16:19], v[144:147], v[226:229], v[16:19]
	v_mfma_f32_16x16x32_bf16 v[156:159], v[122:125], v[206:209], v[156:159]
	v_mfma_f32_16x16x32_bf16 v[160:163], v[144:147], v[206:209], v[160:163]
	v_mfma_f32_16x16x32_bf16 v[164:167], v[122:125], v[218:221], v[164:167]
	v_mfma_f32_16x16x32_bf16 v[168:171], v[144:147], v[218:221], v[168:171]
	v_mfma_f32_16x16x32_bf16 v[20:23], v[148:151], v[188:191], v[20:23]
	v_mfma_f32_16x16x32_bf16 v[32:35], v[180:183], v[188:191], v[32:35]
	v_mfma_f32_16x16x32_bf16 v[36:39], v[148:151], v[196:199], v[36:39]
	v_mfma_f32_16x16x32_bf16 v[60:63], v[180:183], v[196:199], v[60:63]
	v_mfma_f32_16x16x32_bf16 v[66:69], v[148:151], v[214:217], v[66:69]
	v_mfma_f32_16x16x32_bf16 v[114:117], v[180:183], v[214:217], v[114:117]
	v_mfma_f32_16x16x32_bf16 v[24:27], v[148:151], v[222:225], v[24:27]
	v_mfma_f32_16x16x32_bf16 v[28:31], v[180:183], v[222:225], v[28:31]
	v_mfma_f32_16x16x32_bf16 v[20:23], v[152:155], v[192:195], v[20:23]
	v_mfma_f32_16x16x32_bf16 v[32:35], v[184:187], v[192:195], v[32:35]
	v_mfma_f32_16x16x32_bf16 v[36:39], v[152:155], v[206:209], v[36:39]
	v_mfma_f32_16x16x32_bf16 v[60:63], v[184:187], v[206:209], v[60:63]
	v_mfma_f32_16x16x32_bf16 v[66:69], v[152:155], v[218:221], v[66:69]
	v_mfma_f32_16x16x32_bf16 v[114:117], v[184:187], v[218:221], v[114:117]
	v_mfma_f32_16x16x32_bf16 v[24:27], v[152:155], v[226:229], v[24:27]
	v_mfma_f32_16x16x32_bf16 v[28:31], v[184:187], v[226:229], v[28:31]
	s_barrier
	s_setprio 0
	ds_read_b128 v[118:121], v8
	ds_read_b128 v[122:125], v8 offset:1024
	ds_read_b128 v[126:129], v8 offset:2048
	ds_read_b128 v[144:147], v8 offset:3072
	ds_read_b128 v[148:151], v9
	ds_read_b128 v[152:155], v9 offset:1024
	ds_read_b128 v[172:175], v9 offset:2048
	ds_read_b128 v[176:179], v9 offset:3072
	s_add_u32 s14, s14, 0x18280
	s_addc_u32 s15, s15, 0
	s_mov_b32 m0, s50
	v_lshl_add_u64 v[8:9], s[14:15], 0, v[136:137]
	ds_read_b128 v[180:183], v142
	ds_read_b128 v[184:187], v142 offset:1024
	ds_read_b128 v[188:191], v142 offset:2048
	ds_read_b128 v[192:195], v142 offset:3072
	ds_read_b128 v[196:199], v142 offset:4096
	ds_read_b128 v[206:209], v142 offset:5120
	ds_read_b128 v[214:217], v142 offset:6144
	ds_read_b128 v[218:221], v142 offset:7168
	global_load_lds_dwordx4 v[8:9], off
	v_lshl_add_u64 v[8:9], s[14:15], 0, v[132:133]
	s_mov_b32 m0, s2
	s_nop 0
	global_load_lds_dwordx4 v[8:9], off
	s_waitcnt vmcnt(8)
	s_waitcnt lgkmcnt(0)
	s_setprio 1
	s_barrier
	v_mfma_f32_16x16x32_bf16 v[94:97], v[118:121], v[214:217], v[94:97]
	v_mfma_f32_16x16x32_bf16 v[70:73], v[118:121], v[180:183], v[70:73]
	v_mfma_f32_16x16x32_bf16 v[74:77], v[126:129], v[180:183], v[74:77]
	v_mfma_f32_16x16x32_bf16 v[78:81], v[118:121], v[188:191], v[78:81]
	v_mfma_f32_16x16x32_bf16 v[82:85], v[126:129], v[188:191], v[82:85]
	v_mfma_f32_16x16x32_bf16 v[86:89], v[118:121], v[196:199], v[86:89]
	v_mfma_f32_16x16x32_bf16 v[90:93], v[126:129], v[196:199], v[90:93]
	v_mfma_f32_16x16x32_bf16 v[222:225], v[122:125], v[218:221], v[94:97]
	v_mfma_f32_16x16x32_bf16 v[94:97], v[126:129], v[214:217], v[98:101]
	v_mfma_f32_16x16x32_bf16 v[70:73], v[122:125], v[184:187], v[70:73]
	v_mfma_f32_16x16x32_bf16 v[74:77], v[144:147], v[184:187], v[74:77]
	v_mfma_f32_16x16x32_bf16 v[78:81], v[122:125], v[192:195], v[78:81]
	v_mfma_f32_16x16x32_bf16 v[82:85], v[144:147], v[192:195], v[82:85]
	v_mfma_f32_16x16x32_bf16 v[86:89], v[122:125], v[206:209], v[86:89]
	v_mfma_f32_16x16x32_bf16 v[90:93], v[144:147], v[206:209], v[90:93]
	v_mfma_f32_16x16x32_bf16 v[98:101], v[144:147], v[218:221], v[94:97]
	v_mfma_f32_16x16x32_bf16 v[94:97], v[148:151], v[180:183], v[102:105]
	v_mfma_f32_16x16x32_bf16 v[102:105], v[152:155], v[184:187], v[94:97]
	v_mfma_f32_16x16x32_bf16 v[94:97], v[172:175], v[180:183], v[106:109]
	v_mfma_f32_16x16x32_bf16 v[40:43], v[172:175], v[188:191], v[40:43]
	v_mfma_f32_16x16x32_bf16 v[44:47], v[148:151], v[196:199], v[44:47]
	v_mfma_f32_16x16x32_bf16 v[48:51], v[172:175], v[196:199], v[48:51]
	v_mfma_f32_16x16x32_bf16 v[52:55], v[148:151], v[214:217], v[52:55]
	v_mfma_f32_16x16x32_bf16 v[56:59], v[172:175], v[214:217], v[56:59]
	v_mfma_f32_16x16x32_bf16 v[180:183], v[176:179], v[184:187], v[94:97]
	v_mfma_f32_16x16x32_bf16 v[94:97], v[148:151], v[188:191], v[110:113]
	v_mfma_f32_16x16x32_bf16 v[40:43], v[176:179], v[192:195], v[40:43]
	v_mfma_f32_16x16x32_bf16 v[44:47], v[152:155], v[206:209], v[44:47]
	v_mfma_f32_16x16x32_bf16 v[48:51], v[176:179], v[206:209], v[48:51]
	v_mfma_f32_16x16x32_bf16 v[52:55], v[152:155], v[218:221], v[52:55]
	v_mfma_f32_16x16x32_bf16 v[56:59], v[176:179], v[218:221], v[56:59]
	v_mfma_f32_16x16x32_bf16 v[184:187], v[152:155], v[192:195], v[94:97]
	s_barrier
; #define PG8_STAGE(bufoff, gbase, voff) do { _Pragma("unroll") for (int _i = 0; _i < 2; ++_i) \
;         __builtin_amdgcn_global_load_lds((const unsigned*)((const char*)(gbase) + (voff)[_i]), (PG8_LAS unsigned*)(lds + (bufoff) + ldsw + _i * 8192), 16, 0, 0); } while (0)
; #define PG8_LDA(dst, b, h) do { _Pragma("unroll") for (int m = 0; m < 4; ++m) _Pragma("unroll") for (int k = 0; k < 2; ++k) dst[m][k] = *(const PG8_LAS bf16x8*)(lds + PG8_SA(b, h) + aoff + m * 2048 + k * 1024); } while (0)
; #define PG8_LDB(dst, b, h) do { _Pragma("unroll") for (int n = 0; n < 2; ++n) _Pragma("unroll") for (int k = 0; k < 2; ++k) dst[n][k] = *(const PG8_LAS bf16x8*)(lds + PG8_SB(b, h) + boff + n * 2048 + k * 1024); } while (0)
; #define PG8_MMA(ai, bj, At, Bt) do { __builtin_amdgcn_s_setprio(1); _Pragma("unroll") for (int m = 0; m < 4; ++m) _Pragma("unroll") for (int n = 0; n < 2; ++n) _Pragma("unroll") for (int k = 0; k < 2; ++k) \
;         acc[ai][bj][m][n] = __builtin_amdgcn_mfma_f32_16x16x32_bf16(Bt[n][k], At[m][k], acc[ai][bj][m][n], 0, 0, 0); __builtin_amdgcn_s_setprio(0); } while (0)
; #define PG8_WAIT_V(n) asm volatile("s_waitcnt vmcnt(" #n ")" ::: "memory")
; #define PG8_WAIT_L(n) asm volatile("s_waitcnt lgkmcnt(" #n ")" ::: "memory")
; #define PG8_BAR __builtin_amdgcn_s_barrier()
; #define PG8_SCHED __builtin_amdgcn_sched_barrier(0)
;     __device__ __forceinline__ bool next(int i, Unit& u) const { return i < lim && base.next(i, u); }
; template <class Epi, class Sched, bool ALIGN_EPI = false, bool SP2 = false>
; __device__ __forceinline__ void gemm_phase(PG8_LAS unsigned char* lds, const Gemm g, const Sched& S, const Epi& E, const int tid) {
;     ...
;         const bool has_next = S.next(ui + 1, nxt);
;         const char* nA = has_next ? (const char*)g.A + (size_t)nxt.pm * tstep : cA; const char* nB = has_next ? (const char*)g.Bt + (size_t)nxt.pn * tstep : cB;
;     ...
;             PG8_LDA(At, 0, 1); PG8_STAGE(PG8_SB(0, 0), b2, voffB); PG8_STAGE(PG8_SB(0, 1), b2 + hstep, voffB); PG8_STAGE(PG8_SA(0, 0), a2, voffA);
;             PG8_WAIT_V(8); PG8_WAIT_L(0); PG8_BAR; PG8_MMA(1, 0, At, B0); PG8_MMA(1, 1, At, B1); PG8_BAR; PG8_SCHED;
;             PG8_LDB(B0, 1, 0); PG8_LDB(B1, 1, 1); PG8_SCHED; PG8_LDA(At, 1, 0); PG8_STAGE(PG8_SA(0, 1), a2 + hstep, voffA);
;             PG8_WAIT_V(8); PG8_WAIT_L(0); PG8_BAR; PG8_MMA(0, 0, At, B0); PG8_MMA(0, 1, At, B1); PG8_BAR; PG8_SCHED;
	s_setprio 0
	s_mov_b32 m0, s47
	v_lshl_add_u64 v[138:139], s[12:13], 0, v[134:135]
	s_add_u32 s2, s12, 0x18000
	ds_read_b128 v[94:97], v142 offset:16384
	ds_read_b128 v[106:109], v142 offset:17408
	ds_read_b128 v[110:113], v142 offset:18432
	ds_read_b128 v[188:191], v142 offset:19456
	ds_read_b128 v[192:195], v142 offset:20480
	ds_read_b128 v[196:199], v142 offset:21504
	ds_read_b128 v[206:209], v142 offset:22528
	ds_read_b128 v[214:217], v142 offset:23552
	global_load_lds_dwordx4 v[138:139], off
	v_lshl_add_u64 v[252:253], s[12:13], 0, v[130:131]
	s_mov_b32 m0, s3
	s_addc_u32 s3, s13, 0
	global_load_lds_dwordx4 v[252:253], off
	v_lshl_add_u64 v[8:9], s[2:3], 0, v[134:135]
	s_mov_b32 m0, s45
	v_lshl_add_u64 v[246:247], s[10:11], 0, v[136:137]
	global_load_lds_dwordx4 v[8:9], off
	v_lshl_add_u64 v[8:9], s[2:3], 0, v[130:131]
	s_mov_b32 m0, s46
	v_lshl_add_u64 v[210:211], s[10:11], 0, v[132:133]
	global_load_lds_dwordx4 v[8:9], off
	s_mov_b32 m0, s23
	s_nop 0
	global_load_lds_dwordx4 v[246:247], off
	s_mov_b32 m0, s24
	s_nop 0
	global_load_lds_dwordx4 v[210:211], off
	s_waitcnt vmcnt(8)
	s_waitcnt lgkmcnt(0)
	s_setprio 1
	s_barrier
	v_mfma_f32_16x16x32_bf16 v[0:3], v[118:121], v[94:97], v[0:3]
	v_mfma_f32_16x16x32_bf16 v[4:7], v[126:129], v[94:97], v[4:7]
	v_mfma_f32_16x16x32_bf16 v[12:15], v[118:121], v[206:209], v[12:15]
	v_mfma_f32_16x16x32_bf16 v[16:19], v[126:129], v[206:209], v[16:19]
	v_mfma_f32_16x16x32_bf16 v[0:3], v[122:125], v[106:109], v[0:3]
	v_mfma_f32_16x16x32_bf16 v[4:7], v[144:147], v[106:109], v[4:7]
	v_mfma_f32_16x16x32_bf16 v[156:159], v[118:121], v[110:113], v[156:159]
	v_mfma_f32_16x16x32_bf16 v[160:163], v[126:129], v[110:113], v[160:163]
	v_mfma_f32_16x16x32_bf16 v[164:167], v[118:121], v[192:195], v[164:167]
	v_mfma_f32_16x16x32_bf16 v[168:171], v[126:129], v[192:195], v[168:171]
	v_mfma_f32_16x16x32_bf16 v[12:15], v[122:125], v[214:217], v[12:15]
	v_mfma_f32_16x16x32_bf16 v[16:19], v[144:147], v[214:217], v[16:19]
	v_mfma_f32_16x16x32_bf16 v[156:159], v[122:125], v[188:191], v[156:159]
	v_mfma_f32_16x16x32_bf16 v[160:163], v[144:147], v[188:191], v[160:163]
	v_mfma_f32_16x16x32_bf16 v[164:167], v[122:125], v[196:199], v[164:167]
	v_mfma_f32_16x16x32_bf16 v[168:171], v[144:147], v[196:199], v[168:171]
	v_mfma_f32_16x16x32_bf16 v[60:63], v[172:175], v[110:113], v[60:63]
	v_mfma_f32_16x16x32_bf16 v[20:23], v[148:151], v[94:97], v[20:23]
	v_mfma_f32_16x16x32_bf16 v[32:35], v[172:175], v[94:97], v[32:35]
	v_mfma_f32_16x16x32_bf16 v[36:39], v[148:151], v[110:113], v[36:39]
	v_mfma_f32_16x16x32_bf16 v[144:147], v[176:179], v[188:191], v[60:63]
	v_mfma_f32_16x16x32_bf16 v[60:63], v[148:151], v[192:195], v[66:69]
	v_mfma_f32_16x16x32_bf16 v[24:27], v[148:151], v[206:209], v[24:27]
	v_mfma_f32_16x16x32_bf16 v[20:23], v[152:155], v[106:109], v[20:23]
	v_mfma_f32_16x16x32_bf16 v[32:35], v[176:179], v[106:109], v[32:35]
	v_mfma_f32_16x16x32_bf16 v[36:39], v[152:155], v[188:191], v[36:39]
	v_mfma_f32_16x16x32_bf16 v[188:191], v[152:155], v[196:199], v[60:63]
	v_mfma_f32_16x16x32_bf16 v[60:63], v[172:175], v[192:195], v[114:117]
	v_mfma_f32_16x16x32_bf16 v[148:151], v[152:155], v[214:217], v[24:27]
	v_mfma_f32_16x16x32_bf16 v[24:27], v[172:175], v[206:209], v[28:31]
	v_mfma_f32_16x16x32_bf16 v[192:195], v[176:179], v[196:199], v[60:63]
	v_mfma_f32_16x16x32_bf16 v[152:155], v[176:179], v[214:217], v[24:27]
	s_barrier
	s_setprio 0
	ds_read_b128 v[172:175], v10
	ds_read_b128 v[176:179], v10 offset:1024
	ds_read_b128 v[196:199], v10 offset:2048
	ds_read_b128 v[206:209], v10 offset:3072
	ds_read_b128 v[214:217], v11
	ds_read_b128 v[218:221], v11 offset:1024
	ds_read_b128 v[226:229], v11 offset:2048
	ds_read_b128 v[248:251], v11 offset:3072
	s_add_u32 s2, s10, 0x18000
	s_addc_u32 s3, s11, 0
	s_mov_b32 m0, s25
	v_lshl_add_u64 v[94:95], s[2:3], 0, v[136:137]
	ds_read_b128 v[8:11], v142 offset:32768
	ds_read_b128 v[24:27], v142 offset:33792
	ds_read_b128 v[28:31], v142 offset:34816
	ds_read_b128 v[60:63], v142 offset:35840
	ds_read_b128 v[66:69], v142 offset:36864
	ds_read_b128 v[234:237], v142 offset:37888
	ds_read_b128 v[238:241], v142 offset:38912
	ds_read_b128 v[230:233], v142 offset:39936
	global_load_lds_dwordx4 v[94:95], off
	v_lshl_add_u64 v[94:95], s[2:3], 0, v[132:133]
	s_mov_b32 m0, s26
	s_nop 0
	global_load_lds_dwordx4 v[94:95], off
	s_waitcnt vmcnt(8)
	s_waitcnt lgkmcnt(0)
	s_setprio 1
	s_barrier
; #define PG8_STAGE(bufoff, gbase, voff) do { _Pragma("unroll") for (int _i = 0; _i < 2; ++_i) \
;         __builtin_amdgcn_global_load_lds((const unsigned*)((const char*)(gbase) + (voff)[_i]), (PG8_LAS unsigned*)(lds + (bufoff) + ldsw + _i * 8192), 16, 0, 0); } while (0)
; #define PG8_LDA(dst, b, h) do { _Pragma("unroll") for (int m = 0; m < 4; ++m) _Pragma("unroll") for (int k = 0; k < 2; ++k) dst[m][k] = *(const PG8_LAS bf16x8*)(lds + PG8_SA(b, h) + aoff + m * 2048 + k * 1024); } while (0)
; #define PG8_LDB(dst, b, h) do { _Pragma("unroll") for (int n = 0; n < 2; ++n) _Pragma("unroll") for (int k = 0; k < 2; ++k) dst[n][k] = *(const PG8_LAS bf16x8*)(lds + PG8_SB(b, h) + boff + n * 2048 + k * 1024); } while (0)
; #define PG8_MMA(ai, bj, At, Bt) do { __builtin_amdgcn_s_setprio(1); _Pragma("unroll") for (int m = 0; m < 4; ++m) _Pragma("unroll") for (int n = 0; n < 2; ++n) _Pragma("unroll") for (int k = 0; k < 2; ++k) \
;         acc[ai][bj][m][n] = __builtin_amdgcn_mfma_f32_16x16x32_bf16(Bt[n][k], At[m][k], acc[ai][bj][m][n], 0, 0, 0); __builtin_amdgcn_s_setprio(0); } while (0)
; #define PG8_WAIT_V(n) asm volatile("s_waitcnt vmcnt(" #n ")" ::: "memory")
; #define PG8_WAIT_L(n) asm volatile("s_waitcnt lgkmcnt(" #n ")" ::: "memory")
; #define PG8_BAR __builtin_amdgcn_s_barrier()
; #define PG8_SCHED __builtin_amdgcn_sched_barrier(0)
; template <class Epi, class Sched, bool ALIGN_EPI = false, bool SP2 = false>
; __device__ __forceinline__ void gemm_phase(PG8_LAS unsigned char* lds, const Gemm g, const Sched& S, const Epi& E, const int tid) {
;     ...
;             PG8_WAIT_V(8); PG8_WAIT_L(0); PG8_BAR; PG8_MMA(1, 0, At, B0); PG8_MMA(1, 1, At, B1); PG8_BAR; PG8_SCHED;
;             PG8_LDB(B0, 1, 0); PG8_LDB(B1, 1, 1); PG8_SCHED; PG8_LDA(At, 1, 0); PG8_STAGE(PG8_SA(0, 1), a2 + hstep, voffA);
;             PG8_WAIT_V(8); PG8_WAIT_L(0); PG8_BAR; PG8_MMA(0, 0, At, B0); PG8_MMA(0, 1, At, B1); PG8_BAR; PG8_SCHED;
;             PG8_LDA(At, 1, 1); PG8_STAGE(PG8_SB(1, 0), b3, voffB); PG8_STAGE(PG8_SB(1, 1), b3 + hstep, voffB); PG8_STAGE(PG8_SA(1, 0), a3, voffA);
;             PG8_WAIT_V(8); PG8_WAIT_L(0); PG8_BAR; PG8_MMA(1, 0, At, B0); PG8_MMA(1, 1, At, B1); PG8_BAR; PG8_SCHED;
;     ...
;         if constexpr (ALIGN_EPI) { if (wr == 0) PG8_BAR; }
	v_mfma_f32_16x16x32_bf16 v[70:73], v[172:175], v[8:11], v[70:73]
	v_mfma_f32_16x16x32_bf16 v[126:129], v[176:179], v[24:27], v[70:73]
	v_mfma_f32_16x16x32_bf16 v[70:73], v[196:199], v[8:11], v[74:77]
	v_mfma_f32_16x16x32_bf16 v[122:125], v[206:209], v[24:27], v[70:73]
	v_mfma_f32_16x16x32_bf16 v[70:73], v[172:175], v[28:31], v[78:81]
	v_mfma_f32_16x16x32_bf16 v[110:113], v[176:179], v[60:63], v[70:73]
	v_mfma_f32_16x16x32_bf16 v[70:73], v[196:199], v[28:31], v[82:85]
	v_mfma_f32_16x16x32_bf16 v[106:109], v[206:209], v[60:63], v[70:73]
	v_mfma_f32_16x16x32_bf16 v[70:73], v[172:175], v[66:69], v[86:89]
	v_mfma_f32_16x16x32_bf16 v[94:97], v[176:179], v[234:237], v[70:73]
	v_mfma_f32_16x16x32_bf16 v[70:73], v[196:199], v[66:69], v[90:93]
	v_mfma_f32_16x16x32_bf16 v[90:93], v[206:209], v[234:237], v[70:73]
	v_mfma_f32_16x16x32_bf16 v[70:73], v[172:175], v[238:241], v[222:225]
	v_mfma_f32_16x16x32_bf16 v[78:81], v[176:179], v[230:233], v[70:73]
	v_mfma_f32_16x16x32_bf16 v[70:73], v[196:199], v[238:241], v[98:101]
	v_mfma_f32_16x16x32_bf16 v[74:77], v[206:209], v[230:233], v[70:73]
	v_mfma_f32_16x16x32_bf16 v[70:73], v[214:217], v[8:11], v[102:105]
	v_mfma_f32_16x16x32_bf16 v[8:11], v[226:229], v[8:11], v[180:183]
	v_mfma_f32_16x16x32_bf16 v[118:121], v[248:251], v[24:27], v[8:11]
	v_mfma_f32_16x16x32_bf16 v[8:11], v[214:217], v[28:31], v[184:187]
	v_mfma_f32_16x16x32_bf16 v[98:101], v[218:221], v[60:63], v[8:11]
	v_mfma_f32_16x16x32_bf16 v[8:11], v[226:229], v[28:31], v[40:43]
	v_mfma_f32_16x16x32_bf16 v[102:105], v[248:251], v[60:63], v[8:11]
	v_mfma_f32_16x16x32_bf16 v[8:11], v[214:217], v[66:69], v[44:47]
	v_mfma_f32_16x16x32_bf16 v[82:85], v[218:221], v[234:237], v[8:11]
	v_mfma_f32_16x16x32_bf16 v[8:11], v[226:229], v[66:69], v[48:51]
	v_mfma_f32_16x16x32_bf16 v[86:89], v[248:251], v[234:237], v[8:11]
	v_mfma_f32_16x16x32_bf16 v[8:11], v[214:217], v[238:241], v[52:55]
	v_mfma_f32_16x16x32_bf16 v[66:69], v[218:221], v[230:233], v[8:11]
	v_mfma_f32_16x16x32_bf16 v[8:11], v[226:229], v[238:241], v[56:59]
	v_mfma_f32_16x16x32_bf16 v[114:117], v[218:221], v[24:27], v[70:73]
	v_mfma_f32_16x16x32_bf16 v[70:73], v[248:251], v[230:233], v[8:11]
	s_barrier
	s_setprio 0
	s_mov_b32 m0, s52
	s_nop 2
	v_lshl_add_u64 v[8:9], v[138:139], 0, s[94:95]
	s_add_u32 s2, s12, 0x18080
	ds_read_b128 v[52:55], v142 offset:49152
	ds_read_b128 v[180:183], v142 offset:50176
	ds_read_b128 v[184:187], v142 offset:51200
	ds_read_b128 v[222:225], v142 offset:52224
	ds_read_b128 v[230:233], v142 offset:53248
	ds_read_b128 v[234:237], v142 offset:54272
	ds_read_b128 v[238:241], v142 offset:55296
	ds_read_b128 v[200:203], v142 offset:56320
	global_load_lds_dwordx4 v[8:9], off
	v_lshl_add_u64 v[8:9], v[252:253], 0, s[94:95]
	s_mov_b32 m0, s48
	s_addc_u32 s3, s13, 0
	global_load_lds_dwordx4 v[8:9], off
	v_lshl_add_u64 v[8:9], s[2:3], 0, v[134:135]
	s_mov_b32 m0, s49
	s_nop 0
	global_load_lds_dwordx4 v[8:9], off
	v_lshl_add_u64 v[8:9], s[2:3], 0, v[130:131]
	s_mov_b32 m0, s51
	s_nop 0
	global_load_lds_dwordx4 v[8:9], off
	v_lshl_add_u64 v[8:9], v[246:247], 0, s[94:95]
	s_mov_b32 m0, s28
	s_nop 0
	global_load_lds_dwordx4 v[8:9], off
	v_lshl_add_u64 v[8:9], v[210:211], 0, s[94:95]
	s_mov_b32 m0, s29
	s_nop 0
	global_load_lds_dwordx4 v[8:9], off
	s_waitcnt vmcnt(8)
	s_waitcnt lgkmcnt(0)
	s_setprio 1
	s_barrier
	v_mfma_f32_16x16x32_bf16 v[0:3], v[172:175], v[52:55], v[0:3]
	v_mfma_f32_16x16x32_bf16 v[60:63], v[176:179], v[180:183], v[0:3]
	v_mfma_f32_16x16x32_bf16 v[0:3], v[196:199], v[52:55], v[4:7]
	v_mfma_f32_16x16x32_bf16 v[56:59], v[206:209], v[180:183], v[0:3]
	v_mfma_f32_16x16x32_bf16 v[0:3], v[172:175], v[184:187], v[156:159]
	v_mfma_f32_16x16x32_bf16 v[44:47], v[176:179], v[222:225], v[0:3]
	v_mfma_f32_16x16x32_bf16 v[0:3], v[196:199], v[184:187], v[160:163]
	v_mfma_f32_16x16x32_bf16 v[40:43], v[206:209], v[222:225], v[0:3]
	v_mfma_f32_16x16x32_bf16 v[0:3], v[172:175], v[230:233], v[164:167]
	v_mfma_f32_16x16x32_bf16 v[28:31], v[176:179], v[234:237], v[0:3]
	v_mfma_f32_16x16x32_bf16 v[0:3], v[196:199], v[230:233], v[168:171]
	v_mfma_f32_16x16x32_bf16 v[24:27], v[206:209], v[234:237], v[0:3]
	v_mfma_f32_16x16x32_bf16 v[0:3], v[172:175], v[238:241], v[12:15]
	v_mfma_f32_16x16x32_bf16 v[8:11], v[176:179], v[200:203], v[0:3]
	v_mfma_f32_16x16x32_bf16 v[0:3], v[196:199], v[238:241], v[16:19]
	v_mfma_f32_16x16x32_bf16 v[12:15], v[206:209], v[200:203], v[0:3]
	v_mfma_f32_16x16x32_bf16 v[0:3], v[214:217], v[52:55], v[20:23]
	v_mfma_f32_16x16x32_bf16 v[48:51], v[218:221], v[180:183], v[0:3]
	v_mfma_f32_16x16x32_bf16 v[0:3], v[226:229], v[52:55], v[32:35]
	v_mfma_f32_16x16x32_bf16 v[52:55], v[248:251], v[180:183], v[0:3]
	v_mfma_f32_16x16x32_bf16 v[0:3], v[214:217], v[184:187], v[36:39]
	v_mfma_f32_16x16x32_bf16 v[32:35], v[218:221], v[222:225], v[0:3]
	v_mfma_f32_16x16x32_bf16 v[0:3], v[226:229], v[184:187], v[144:147]
	v_mfma_f32_16x16x32_bf16 v[36:39], v[248:251], v[222:225], v[0:3]
	v_mfma_f32_16x16x32_bf16 v[0:3], v[214:217], v[230:233], v[188:191]
	v_mfma_f32_16x16x32_bf16 v[16:19], v[218:221], v[234:237], v[0:3]
	v_mfma_f32_16x16x32_bf16 v[0:3], v[226:229], v[230:233], v[192:195]
	v_mfma_f32_16x16x32_bf16 v[20:23], v[248:251], v[234:237], v[0:3]
	v_mfma_f32_16x16x32_bf16 v[0:3], v[214:217], v[238:241], v[148:151]
	v_mfma_f32_16x16x32_bf16 v[4:7], v[226:229], v[238:241], v[152:155]
	v_mfma_f32_16x16x32_bf16 v[0:3], v[218:221], v[200:203], v[0:3]
	v_mfma_f32_16x16x32_bf16 v[4:7], v[248:251], v[200:203], v[4:7]
	s_barrier
	s_setprio 0
	s_andn2_b64 vcc, exec, s[8:9]
	s_cbranch_vccnz .LBB0_350
	s_barrier

; #define PG8_STAGE(bufoff, gbase, voff) do { _Pragma("unroll") for (int _i = 0; _i < 2; ++_i) \
;         __builtin_amdgcn_global_load_lds((const unsigned*)((const char*)(gbase) + (voff)[_i]), (PG8_LAS unsigned*)(lds + (bufoff) + ldsw + _i * 8192), 16, 0, 0); } while (0)
; #define PG8_LDA(dst, b, h) do { _Pragma("unroll") for (int m = 0; m < 4; ++m) _Pragma("unroll") for (int k = 0; k < 2; ++k) dst[m][k] = *(const PG8_LAS bf16x8*)(lds + PG8_SA(b, h) + aoff + m * 2048 + k * 1024); } while (0)
; #define PG8_LDB(dst, b, h) do { _Pragma("unroll") for (int n = 0; n < 2; ++n) _Pragma("unroll") for (int k = 0; k < 2; ++k) dst[n][k] = *(const PG8_LAS bf16x8*)(lds + PG8_SB(b, h) + boff + n * 2048 + k * 1024); } while (0)
; #define PG8_MMA(ai, bj, At, Bt) do { __builtin_amdgcn_s_setprio(1); _Pragma("unroll") for (int m = 0; m < 4; ++m) _Pragma("unroll") for (int n = 0; n < 2; ++n) _Pragma("unroll") for (int k = 0; k < 2; ++k) \
;         acc[ai][bj][m][n] = __builtin_amdgcn_mfma_f32_16x16x32_bf16(Bt[n][k], At[m][k], acc[ai][bj][m][n], 0, 0, 0); __builtin_amdgcn_s_setprio(0); } while (0)
; #define PG8_WAIT_V(n) asm volatile("s_waitcnt vmcnt(" #n ")" ::: "memory")
; #define PG8_BAR __builtin_amdgcn_s_barrier()
; template <class Epi, class Sched, bool ALIGN_EPI = false, bool SP2 = false>
; __device__ __forceinline__ void gemm_phase(PG8_LAS unsigned char* lds, const Gemm g, const Sched& S, const Epi& E, const int tid) {
;     ...
;         for (int t = 0; t < nt; t += 2) {
;             const bool last = (t == nt - 2);
;             const char* a1 = cA + (size_t)(t + 1) * kstep;
;             const char* a2 = last ? nA : cA + (size_t)(t + 2) * kstep; const char* b2 = last ? nB : cB + (size_t)(t + 2) * kstep;
;             const char* a3 = a2 + kstep; const char* b3 = b2 + kstep;
;             if (last && has_next) S.a_ready(nxt);
;             if constexpr (SP2) {
;             PG8_LDB(B0, 0, 0); PG8_LDB(B1, 0, 1); PG8_SCHED; PG8_LDA(At, 0, 0); PG8_STAGE(PG8_SA(1, 1), a1 + hstep, voffA);
;             PG8_WAIT_V(8); PG8_WAIT_L(0); PG8_BAR; PG8_MMA(0, 0, At, B0); PG8_MMA(0, 1, At, B1); PG8_BAR; PG8_SCHED;
;             PG8_LDA(At, 0, 1); PG8_STAGE(PG8_SB(0, 0), b2, voffB); PG8_STAGE(PG8_SB(0, 1), b2 + hstep, voffB); PG8_STAGE(PG8_SA(0, 0), a2, voffA);
;             PG8_WAIT_V(8); PG8_WAIT_L(0); PG8_BAR; PG8_MMA(1, 0, At, B0); PG8_MMA(1, 1, At, B1); PG8_BAR; PG8_SCHED;
.LBB0_511:
	s_add_u32 s6, s24, s4
	s_addc_u32 s7, s25, s5
	s_add_u32 s6, s6, 0x2c00100
	s_addc_u32 s7, s7, 0
	s_add_u32 s27, s22, s4
	s_addc_u32 s28, s23, s5
	s_add_i32 s29, 0, 0x10000
	s_cmpk_eq_i32 s4, 0x700
	s_cselect_b32 s9, s3, s7
	s_cselect_b32 s8, s2, s6
	v_add_u32_e32 v149, s29, v142
	s_cselect_b32 s7, s1, s28
	s_cselect_b32 s6, s0, s27
	s_add_i32 s27, 0, 0x14000
	ds_read_b128 v[144:147], v149
	ds_read_b128 v[150:153], v149 offset:1024
	ds_read_b128 v[154:157], v149 offset:2048
	ds_read_b128 v[158:161], v149 offset:3072
	v_add_u32_e32 v149, s27, v142
	ds_read_b128 v[162:165], v149
	ds_read_b128 v[166:169], v149 offset:1024
	ds_read_b128 v[170:173], v149 offset:2048
	ds_read_b128 v[174:177], v149 offset:3072
	v_lshl_add_u64 v[202:203], v[138:139], 0, s[4:5]
	s_add_i32 m0, s13, 0xc000
	ds_read_b128 v[178:181], v143
	ds_read_b128 v[182:185], v143 offset:1024
	ds_read_b128 v[186:189], v143 offset:2048
	ds_read_b128 v[190:193], v143 offset:3072
	ds_read_b128 v[194:197], v143 offset:4096
	ds_read_b128 v[198:201], v143 offset:5120
	ds_read_b128 v[214:217], v143 offset:6144
	ds_read_b128 v[218:221], v143 offset:7168
	global_load_lds_dwordx4 v[202:203], off
	v_lshl_add_u64 v[202:203], v[136:137], 0, s[4:5]
	s_add_i32 m0, s13, 0xe000
	s_nop 0
	global_load_lds_dwordx4 v[202:203], off
	s_waitcnt vmcnt(8)
	s_waitcnt lgkmcnt(0)
	s_setprio 1
	s_barrier
	v_mfma_f32_16x16x32_bf16 v[126:129], v[144:147], v[178:181], v[126:129]
	v_mfma_f32_16x16x32_bf16 v[122:125], v[154:157], v[178:181], v[122:125]
	v_mfma_f32_16x16x32_bf16 v[118:121], v[144:147], v[186:189], v[118:121]
	v_mfma_f32_16x16x32_bf16 v[114:117], v[154:157], v[186:189], v[114:117]
	v_mfma_f32_16x16x32_bf16 v[110:113], v[144:147], v[194:197], v[110:113]
	v_mfma_f32_16x16x32_bf16 v[106:109], v[154:157], v[194:197], v[106:109]
	v_mfma_f32_16x16x32_bf16 v[102:105], v[144:147], v[214:217], v[102:105]
	v_mfma_f32_16x16x32_bf16 v[98:101], v[154:157], v[214:217], v[98:101]
	v_mfma_f32_16x16x32_bf16 v[126:129], v[150:153], v[182:185], v[126:129]
	v_mfma_f32_16x16x32_bf16 v[122:125], v[158:161], v[182:185], v[122:125]
	v_mfma_f32_16x16x32_bf16 v[118:121], v[150:153], v[190:193], v[118:121]
	v_mfma_f32_16x16x32_bf16 v[114:117], v[158:161], v[190:193], v[114:117]
	v_mfma_f32_16x16x32_bf16 v[110:113], v[150:153], v[198:201], v[110:113]
	v_mfma_f32_16x16x32_bf16 v[106:109], v[158:161], v[198:201], v[106:109]
	v_mfma_f32_16x16x32_bf16 v[102:105], v[150:153], v[218:221], v[102:105]
	v_mfma_f32_16x16x32_bf16 v[98:101], v[158:161], v[218:221], v[98:101]
	v_mfma_f32_16x16x32_bf16 v[60:63], v[162:165], v[178:181], v[60:63]
	v_mfma_f32_16x16x32_bf16 v[56:59], v[170:173], v[178:181], v[56:59]
	v_mfma_f32_16x16x32_bf16 v[52:55], v[162:165], v[186:189], v[52:55]
	v_mfma_f32_16x16x32_bf16 v[48:51], v[170:173], v[186:189], v[48:51]
	v_mfma_f32_16x16x32_bf16 v[44:47], v[162:165], v[194:197], v[44:47]
	v_mfma_f32_16x16x32_bf16 v[40:43], v[170:173], v[194:197], v[40:43]
	v_mfma_f32_16x16x32_bf16 v[36:39], v[162:165], v[214:217], v[36:39]
	v_mfma_f32_16x16x32_bf16 v[32:35], v[170:173], v[214:217], v[32:35]
	v_mfma_f32_16x16x32_bf16 v[60:63], v[166:169], v[182:185], v[60:63]
	v_mfma_f32_16x16x32_bf16 v[56:59], v[174:177], v[182:185], v[56:59]
	v_mfma_f32_16x16x32_bf16 v[52:55], v[166:169], v[190:193], v[52:55]
	v_mfma_f32_16x16x32_bf16 v[48:51], v[174:177], v[190:193], v[48:51]
	v_mfma_f32_16x16x32_bf16 v[44:47], v[166:169], v[198:201], v[44:47]
	v_mfma_f32_16x16x32_bf16 v[40:43], v[174:177], v[198:201], v[40:43]
	v_mfma_f32_16x16x32_bf16 v[36:39], v[166:169], v[218:221], v[36:39]
	v_mfma_f32_16x16x32_bf16 v[32:35], v[174:177], v[218:221], v[32:35]
	s_barrier
	s_setprio 0
	s_add_i32 s28, s29, s12
	v_lshl_add_u64 v[202:203], s[6:7], 0, v[64:65]
	s_mov_b32 m0, s28
	ds_read_b128 v[178:181], v143 offset:16384
	ds_read_b128 v[182:185], v143 offset:17408
	ds_read_b128 v[186:189], v143 offset:18432
	ds_read_b128 v[190:193], v143 offset:19456
	ds_read_b128 v[194:197], v143 offset:20480
	ds_read_b128 v[198:201], v143 offset:21504
	ds_read_b128 v[214:217], v143 offset:22528
	ds_read_b128 v[218:221], v143 offset:23552
	global_load_lds_dwordx4 v[202:203], off
	s_add_i32 m0, s28, 0x2000
	s_add_u32 s28, s6, 0x40000
	v_lshl_add_u64 v[206:207], s[6:7], 0, v[134:135]
	s_addc_u32 s29, s7, 0
	s_add_i32 s27, s27, s12
	global_load_lds_dwordx4 v[206:207], off
	v_lshl_add_u64 v[208:209], s[28:29], 0, v[64:65]
	s_mov_b32 m0, s27
	v_lshl_add_u64 v[222:223], s[8:9], 0, v[132:133]
	global_load_lds_dwordx4 v[208:209], off
	v_lshl_add_u64 v[208:209], s[28:29], 0, v[134:135]
	s_add_i32 m0, s27, 0x2000
	s_nop 0
	global_load_lds_dwordx4 v[208:209], off
	v_lshl_add_u64 v[208:209], s[8:9], 0, v[130:131]
	s_mov_b32 m0, s13
	s_nop 0
	global_load_lds_dwordx4 v[208:209], off
	s_mov_b32 m0, s16
	s_nop 0
	global_load_lds_dwordx4 v[222:223], off
	s_waitcnt vmcnt(8)
	s_waitcnt lgkmcnt(0)
	s_setprio 1
	s_barrier
; #define PG8_STAGE(bufoff, gbase, voff) do { _Pragma("unroll") for (int _i = 0; _i < 2; ++_i) \
;         __builtin_amdgcn_global_load_lds((const unsigned*)((const char*)(gbase) + (voff)[_i]), (PG8_LAS unsigned*)(lds + (bufoff) + ldsw + _i * 8192), 16, 0, 0); } while (0)
; #define PG8_LDA(dst, b, h) do { _Pragma("unroll") for (int m = 0; m < 4; ++m) _Pragma("unroll") for (int k = 0; k < 2; ++k) dst[m][k] = *(const PG8_LAS bf16x8*)(lds + PG8_SA(b, h) + aoff + m * 2048 + k * 1024); } while (0)
; #define PG8_LDB(dst, b, h) do { _Pragma("unroll") for (int n = 0; n < 2; ++n) _Pragma("unroll") for (int k = 0; k < 2; ++k) dst[n][k] = *(const PG8_LAS bf16x8*)(lds + PG8_SB(b, h) + boff + n * 2048 + k * 1024); } while (0)
; #define PG8_MMA(ai, bj, At, Bt) do { __builtin_amdgcn_s_setprio(1); _Pragma("unroll") for (int m = 0; m < 4; ++m) _Pragma("unroll") for (int n = 0; n < 2; ++n) _Pragma("unroll") for (int k = 0; k < 2; ++k) \
;         acc[ai][bj][m][n] = __builtin_amdgcn_mfma_f32_16x16x32_bf16(Bt[n][k], At[m][k], acc[ai][bj][m][n], 0, 0, 0); __builtin_amdgcn_s_setprio(0); } while (0)
; #define PG8_WAIT_V(n) asm volatile("s_waitcnt vmcnt(" #n ")" ::: "memory")
; #define PG8_WAIT_L(n) asm volatile("s_waitcnt lgkmcnt(" #n ")" ::: "memory")
; #define PG8_BAR __builtin_amdgcn_s_barrier()
; #define PG8_SCHED __builtin_amdgcn_sched_barrier(0)
; template <class Epi, class Sched, bool ALIGN_EPI = false, bool SP2 = false>
; __device__ __forceinline__ void gemm_phase(PG8_LAS unsigned char* lds, const Gemm g, const Sched& S, const Epi& E, const int tid) {
;     ...
;             PG8_WAIT_V(8); PG8_WAIT_L(0); PG8_BAR; PG8_MMA(1, 0, At, B0); PG8_MMA(1, 1, At, B1); PG8_BAR; PG8_SCHED;
;             PG8_LDB(B0, 1, 0); PG8_LDB(B1, 1, 1); PG8_SCHED; PG8_LDA(At, 1, 0); PG8_STAGE(PG8_SA(0, 1), a2 + hstep, voffA);
;             PG8_WAIT_V(8); PG8_WAIT_L(0); PG8_BAR; PG8_MMA(0, 0, At, B0); PG8_MMA(0, 1, At, B1); PG8_BAR; PG8_SCHED;
	v_mfma_f32_16x16x32_bf16 v[94:97], v[144:147], v[178:181], v[94:97]
	v_mfma_f32_16x16x32_bf16 v[90:93], v[154:157], v[178:181], v[90:93]
	v_mfma_f32_16x16x32_bf16 v[86:89], v[144:147], v[186:189], v[86:89]
	v_mfma_f32_16x16x32_bf16 v[82:85], v[154:157], v[186:189], v[82:85]
	v_mfma_f32_16x16x32_bf16 v[78:81], v[144:147], v[194:197], v[78:81]
	v_mfma_f32_16x16x32_bf16 v[74:77], v[154:157], v[194:197], v[74:77]
	v_mfma_f32_16x16x32_bf16 v[70:73], v[144:147], v[214:217], v[70:73]
	v_mfma_f32_16x16x32_bf16 v[66:69], v[154:157], v[214:217], v[66:69]
	v_mfma_f32_16x16x32_bf16 v[94:97], v[150:153], v[182:185], v[94:97]
	v_mfma_f32_16x16x32_bf16 v[90:93], v[158:161], v[182:185], v[90:93]
	v_mfma_f32_16x16x32_bf16 v[86:89], v[150:153], v[190:193], v[86:89]
	v_mfma_f32_16x16x32_bf16 v[82:85], v[158:161], v[190:193], v[82:85]
	v_mfma_f32_16x16x32_bf16 v[78:81], v[150:153], v[198:201], v[78:81]
	v_mfma_f32_16x16x32_bf16 v[74:77], v[158:161], v[198:201], v[74:77]
	v_mfma_f32_16x16x32_bf16 v[70:73], v[150:153], v[218:221], v[70:73]
	v_mfma_f32_16x16x32_bf16 v[66:69], v[158:161], v[218:221], v[66:69]
	v_mfma_f32_16x16x32_bf16 v[28:31], v[162:165], v[178:181], v[28:31]
	v_mfma_f32_16x16x32_bf16 v[24:27], v[170:173], v[178:181], v[24:27]
	v_mfma_f32_16x16x32_bf16 v[20:23], v[162:165], v[186:189], v[20:23]
	v_mfma_f32_16x16x32_bf16 v[16:19], v[170:173], v[186:189], v[16:19]
	v_mfma_f32_16x16x32_bf16 v[12:15], v[162:165], v[194:197], v[12:15]
	v_mfma_f32_16x16x32_bf16 v[8:11], v[170:173], v[194:197], v[8:11]
	v_mfma_f32_16x16x32_bf16 v[4:7], v[162:165], v[214:217], v[4:7]
	v_mfma_f32_16x16x32_bf16 v[0:3], v[170:173], v[214:217], v[0:3]
	v_mfma_f32_16x16x32_bf16 v[28:31], v[166:169], v[182:185], v[28:31]
	v_mfma_f32_16x16x32_bf16 v[24:27], v[174:177], v[182:185], v[24:27]
	v_mfma_f32_16x16x32_bf16 v[20:23], v[166:169], v[190:193], v[20:23]
	v_mfma_f32_16x16x32_bf16 v[16:19], v[174:177], v[190:193], v[16:19]
	v_mfma_f32_16x16x32_bf16 v[12:15], v[166:169], v[198:201], v[12:15]
	v_mfma_f32_16x16x32_bf16 v[8:11], v[174:177], v[198:201], v[8:11]
	v_mfma_f32_16x16x32_bf16 v[4:7], v[166:169], v[218:221], v[4:7]
	v_mfma_f32_16x16x32_bf16 v[0:3], v[174:177], v[218:221], v[0:3]
	s_barrier
	s_setprio 0
	s_add_i32 s27, 0, 0x18000
	v_add_u32_e32 v149, s27, v142
	s_add_i32 s28, 0, 0x1c000
	ds_read_b128 v[144:147], v149
	ds_read_b128 v[150:153], v149 offset:1024
	ds_read_b128 v[154:157], v149 offset:2048
	ds_read_b128 v[158:161], v149 offset:3072
	v_add_u32_e32 v149, s28, v142
	ds_read_b128 v[162:165], v149
	ds_read_b128 v[166:169], v149 offset:1024
	ds_read_b128 v[170:173], v149 offset:2048
	ds_read_b128 v[174:177], v149 offset:3072
	s_add_u32 s8, s8, 0x40000
	s_addc_u32 s9, s9, 0
	s_mov_b32 m0, s17
	v_lshl_add_u64 v[224:225], s[8:9], 0, v[130:131]
	ds_read_b128 v[178:181], v143 offset:32768
	ds_read_b128 v[182:185], v143 offset:33792
	ds_read_b128 v[186:189], v143 offset:34816
	ds_read_b128 v[190:193], v143 offset:35840
	ds_read_b128 v[194:197], v143 offset:36864
	ds_read_b128 v[198:201], v143 offset:37888
	ds_read_b128 v[214:217], v143 offset:38912
	ds_read_b128 v[218:221], v143 offset:39936
	global_load_lds_dwordx4 v[224:225], off
	v_lshl_add_u64 v[224:225], s[8:9], 0, v[132:133]
	s_mov_b32 m0, s18
	s_nop 0
	global_load_lds_dwordx4 v[224:225], off
	s_waitcnt vmcnt(8)
	s_waitcnt lgkmcnt(0)
	s_setprio 1
	s_barrier
	v_mfma_f32_16x16x32_bf16 v[126:129], v[144:147], v[178:181], v[126:129]
	v_mfma_f32_16x16x32_bf16 v[122:125], v[154:157], v[178:181], v[122:125]
	v_mfma_f32_16x16x32_bf16 v[118:121], v[144:147], v[186:189], v[118:121]
	v_mfma_f32_16x16x32_bf16 v[114:117], v[154:157], v[186:189], v[114:117]
	v_mfma_f32_16x16x32_bf16 v[110:113], v[144:147], v[194:197], v[110:113]
	v_mfma_f32_16x16x32_bf16 v[106:109], v[154:157], v[194:197], v[106:109]
	v_mfma_f32_16x16x32_bf16 v[102:105], v[144:147], v[214:217], v[102:105]
	v_mfma_f32_16x16x32_bf16 v[98:101], v[154:157], v[214:217], v[98:101]
	v_mfma_f32_16x16x32_bf16 v[126:129], v[150:153], v[182:185], v[126:129]
	v_mfma_f32_16x16x32_bf16 v[122:125], v[158:161], v[182:185], v[122:125]
	v_mfma_f32_16x16x32_bf16 v[118:121], v[150:153], v[190:193], v[118:121]
	v_mfma_f32_16x16x32_bf16 v[114:117], v[158:161], v[190:193], v[114:117]
	v_mfma_f32_16x16x32_bf16 v[110:113], v[150:153], v[198:201], v[110:113]
	v_mfma_f32_16x16x32_bf16 v[106:109], v[158:161], v[198:201], v[106:109]
	v_mfma_f32_16x16x32_bf16 v[102:105], v[150:153], v[218:221], v[102:105]
	v_mfma_f32_16x16x32_bf16 v[98:101], v[158:161], v[218:221], v[98:101]
	v_mfma_f32_16x16x32_bf16 v[60:63], v[162:165], v[178:181], v[60:63]
	v_mfma_f32_16x16x32_bf16 v[56:59], v[170:173], v[178:181], v[56:59]
	v_mfma_f32_16x16x32_bf16 v[52:55], v[162:165], v[186:189], v[52:55]
	v_mfma_f32_16x16x32_bf16 v[48:51], v[170:173], v[186:189], v[48:51]
	v_mfma_f32_16x16x32_bf16 v[44:47], v[162:165], v[194:197], v[44:47]
	v_mfma_f32_16x16x32_bf16 v[40:43], v[170:173], v[194:197], v[40:43]
	v_mfma_f32_16x16x32_bf16 v[36:39], v[162:165], v[214:217], v[36:39]
	v_mfma_f32_16x16x32_bf16 v[32:35], v[170:173], v[214:217], v[32:35]
	v_mfma_f32_16x16x32_bf16 v[60:63], v[166:169], v[182:185], v[60:63]
	v_mfma_f32_16x16x32_bf16 v[56:59], v[174:177], v[182:185], v[56:59]
	v_mfma_f32_16x16x32_bf16 v[52:55], v[166:169], v[190:193], v[52:55]
	v_mfma_f32_16x16x32_bf16 v[48:51], v[174:177], v[190:193], v[48:51]
	v_mfma_f32_16x16x32_bf16 v[44:47], v[166:169], v[198:201], v[44:47]
	v_mfma_f32_16x16x32_bf16 v[40:43], v[174:177], v[198:201], v[40:43]
	v_mfma_f32_16x16x32_bf16 v[36:39], v[166:169], v[218:221], v[36:39]
	v_mfma_f32_16x16x32_bf16 v[32:35], v[174:177], v[218:221], v[32:35]
	s_barrier
; #define PG8_STAGE(bufoff, gbase, voff) do { _Pragma("unroll") for (int _i = 0; _i < 2; ++_i) \
;         __builtin_amdgcn_global_load_lds((const unsigned*)((const char*)(gbase) + (voff)[_i]), (PG8_LAS unsigned*)(lds + (bufoff) + ldsw + _i * 8192), 16, 0, 0); } while (0)
; #define PG8_LDA(dst, b, h) do { _Pragma("unroll") for (int m = 0; m < 4; ++m) _Pragma("unroll") for (int k = 0; k < 2; ++k) dst[m][k] = *(const PG8_LAS bf16x8*)(lds + PG8_SA(b, h) + aoff + m * 2048 + k * 1024); } while (0)
; #define PG8_MMA(ai, bj, At, Bt) do { __builtin_amdgcn_s_setprio(1); _Pragma("unroll") for (int m = 0; m < 4; ++m) _Pragma("unroll") for (int n = 0; n < 2; ++n) _Pragma("unroll") for (int k = 0; k < 2; ++k) \
;         acc[ai][bj][m][n] = __builtin_amdgcn_mfma_f32_16x16x32_bf16(Bt[n][k], At[m][k], acc[ai][bj][m][n], 0, 0, 0); __builtin_amdgcn_s_setprio(0); } while (0)
; #define PG8_WAIT_V(n) asm volatile("s_waitcnt vmcnt(" #n ")" ::: "memory")
; template <class Epi, class Sched, bool ALIGN_EPI = false, bool SP2 = false>
; __device__ __forceinline__ void gemm_phase(PG8_LAS unsigned char* lds, const Gemm g, const Sched& S, const Epi& E, const int tid) {
;     ...
;             PG8_LDA(At, 1, 1); PG8_STAGE(PG8_SB(1, 0), b3, voffB); PG8_STAGE(PG8_SB(1, 1), b3 + hstep, voffB); PG8_STAGE(PG8_SA(1, 0), a3, voffA);
;             PG8_WAIT_V(8); PG8_WAIT_L(0); PG8_BAR; PG8_MMA(1, 0, At, B0); PG8_MMA(1, 1, At, B1); PG8_BAR; PG8_SCHED;
;     __device__ __forceinline__ void operator()(const f32x4 (&acc)[2][2][4][2], const Unit& u, int wr, int wc, int fr, int fq) const {
;     ...
;                 const int gcol = col - LDQ;
;                 const f32x4 b0 = *(const f32x4*)(bgate + gcol), b1 = *(const f32x4*)(bgate + gcol + 4);
; #pragma unroll
;                 for (int ai = 0; ai < 2; ++ai)
; #pragma unroll
;                     for (int m = 0; m < 4; ++m) {
;                         const int row = row0 + ai * 128 + m * 16;
;                         const f32x4 v0 = acc[ai][bj][m][0] + b0, v1 = acc[ai][bj][m][1] + b1;
;                         u32x4 w; w.x = pk2(sigmoidf_(v0[0]), sigmoidf_(v0[1])); w.y = pk2(sigmoidf_(v0[2]), sigmoidf_(v0[3]));
;                         w.z = pk2(sigmoidf_(v1[0]), sigmoidf_(v1[1])); w.w = pk2(sigmoidf_(v1[2]), sigmoidf_(v1[3]));
;                         __builtin_nontemporal_store(w, (u32x4*)(gates + (unsigned)(row * NG + gcol)));
	s_setprio 0
	s_add_i32 s8, s27, s12
	v_lshl_add_u64 v[202:203], v[202:203], 0, s[94:95]
	s_mov_b32 m0, s8
	ds_read_b128 v[178:181], v143 offset:49152
	ds_read_b128 v[182:185], v143 offset:50176
	ds_read_b128 v[186:189], v143 offset:51200
	ds_read_b128 v[190:193], v143 offset:52224
	ds_read_b128 v[194:197], v143 offset:53248
	ds_read_b128 v[198:201], v143 offset:54272
	ds_read_b128 v[214:217], v143 offset:55296
	ds_read_b128 v[218:221], v143 offset:56320
	global_load_lds_dwordx4 v[202:203], off
	s_add_i32 m0, s8, 0x2000
	s_add_u32 s6, s6, 0x40080
	v_lshl_add_u64 v[202:203], v[206:207], 0, s[94:95]
	s_addc_u32 s7, s7, 0
	s_add_i32 s8, s28, s12
	global_load_lds_dwordx4 v[202:203], off
	v_lshl_add_u64 v[202:203], s[6:7], 0, v[64:65]
	s_mov_b32 m0, s8
	s_nop 0
	global_load_lds_dwordx4 v[202:203], off
	v_lshl_add_u64 v[202:203], s[6:7], 0, v[134:135]
	s_add_i32 m0, s8, 0x2000
	s_nop 0
	global_load_lds_dwordx4 v[202:203], off
	v_lshl_add_u64 v[202:203], v[208:209], 0, s[94:95]
	s_mov_b32 m0, s20
	s_nop 0
	global_load_lds_dwordx4 v[202:203], off
	v_lshl_add_u64 v[202:203], v[222:223], 0, s[94:95]
	s_mov_b32 m0, s21
	s_nop 0
	global_load_lds_dwordx4 v[202:203], off
	s_waitcnt vmcnt(8)
	s_waitcnt lgkmcnt(0)
	s_setprio 1
	s_barrier
	v_mfma_f32_16x16x32_bf16 v[94:97], v[144:147], v[178:181], v[94:97]
	v_mfma_f32_16x16x32_bf16 v[90:93], v[154:157], v[178:181], v[90:93]
	v_mfma_f32_16x16x32_bf16 v[86:89], v[144:147], v[186:189], v[86:89]
	v_mfma_f32_16x16x32_bf16 v[82:85], v[154:157], v[186:189], v[82:85]
	v_mfma_f32_16x16x32_bf16 v[78:81], v[144:147], v[194:197], v[78:81]
	v_mfma_f32_16x16x32_bf16 v[74:77], v[154:157], v[194:197], v[74:77]
	v_mfma_f32_16x16x32_bf16 v[70:73], v[144:147], v[214:217], v[70:73]
	v_mfma_f32_16x16x32_bf16 v[66:69], v[154:157], v[214:217], v[66:69]
	v_mfma_f32_16x16x32_bf16 v[94:97], v[150:153], v[182:185], v[94:97]
	v_mfma_f32_16x16x32_bf16 v[90:93], v[158:161], v[182:185], v[90:93]
	v_mfma_f32_16x16x32_bf16 v[86:89], v[150:153], v[190:193], v[86:89]
	v_mfma_f32_16x16x32_bf16 v[82:85], v[158:161], v[190:193], v[82:85]
	v_mfma_f32_16x16x32_bf16 v[78:81], v[150:153], v[198:201], v[78:81]
	v_mfma_f32_16x16x32_bf16 v[74:77], v[158:161], v[198:201], v[74:77]
	v_mfma_f32_16x16x32_bf16 v[70:73], v[150:153], v[218:221], v[70:73]
	v_mfma_f32_16x16x32_bf16 v[66:69], v[158:161], v[218:221], v[66:69]
	v_mfma_f32_16x16x32_bf16 v[28:31], v[162:165], v[178:181], v[28:31]
	v_mfma_f32_16x16x32_bf16 v[24:27], v[170:173], v[178:181], v[24:27]
	v_mfma_f32_16x16x32_bf16 v[20:23], v[162:165], v[186:189], v[20:23]
	v_mfma_f32_16x16x32_bf16 v[16:19], v[170:173], v[186:189], v[16:19]
	v_mfma_f32_16x16x32_bf16 v[12:15], v[162:165], v[194:197], v[12:15]
	v_mfma_f32_16x16x32_bf16 v[8:11], v[170:173], v[194:197], v[8:11]
	v_mfma_f32_16x16x32_bf16 v[4:7], v[162:165], v[214:217], v[4:7]
	v_mfma_f32_16x16x32_bf16 v[0:3], v[170:173], v[214:217], v[0:3]
	v_mfma_f32_16x16x32_bf16 v[28:31], v[166:169], v[182:185], v[28:31]
	v_mfma_f32_16x16x32_bf16 v[24:27], v[174:177], v[182:185], v[24:27]
	v_mfma_f32_16x16x32_bf16 v[20:23], v[166:169], v[190:193], v[20:23]
	v_mfma_f32_16x16x32_bf16 v[16:19], v[174:177], v[190:193], v[16:19]
	v_mfma_f32_16x16x32_bf16 v[12:15], v[166:169], v[198:201], v[12:15]
	v_mfma_f32_16x16x32_bf16 v[8:11], v[174:177], v[198:201], v[8:11]
	v_mfma_f32_16x16x32_bf16 v[4:7], v[166:169], v[218:221], v[4:7]
	v_mfma_f32_16x16x32_bf16 v[0:3], v[174:177], v[218:221], v[0:3]
	s_barrier
	s_setprio 0
	s_add_i32 s26, s26, 2
	s_add_u32 s4, s4, 0x100
	s_addc_u32 s5, s5, 0
	s_cmp_gt_u32 s26, 13
	s_cbranch_scc0 .LBB0_511
	s_and_b32 s12, 0xffff, s11
	s_lshl_b32 s13, s19, 8
	s_lshl_b32 s11, s12, 8
	s_and_b32 s2, s13, 0xff00
	s_and_b32 s14, 0xffff, s14
	v_or_b32_e32 v64, s15, v148
	s_cmpk_gt_u32 s14, 0x8f
	v_or_b32_e32 v186, s2, v64
	s_cselect_b64 s[2:3], -1, 0
	v_cmp_eq_u32_e64 s[0:1], 0, v141
	v_add_u32_e32 v187, s11, v140
	s_mov_b64 s[4:5], -1
	s_and_b64 vcc, exec, s[2:3]
	s_cbranch_vccz .LBB0_514
	v_add_u32_e32 v138, 0xffffee00, v186
	v_ashrrev_i32_e32 v139, 31, v138
	v_lshl_add_u64 v[134:135], v[138:139], 2, s[52:53]
	global_load_dwordx4 v[130:133], v[134:135], off offset:16
	s_nop 0
	global_load_dwordx4 v[134:137], v[134:135], off
	s_waitcnt vmcnt(0)
	v_pk_add_f32 v[146:147], v[122:123], v[130:131]
	v_pk_add_f32 v[140:141], v[126:127], v[134:135]
	v_pk_add_f32 v[142:143], v[128:129], v[136:137]
	v_mul_f32_e32 v64, 0xbfb8aa3b, v140
	v_mul_f32_e32 v139, 0xbfb8aa3b, v141
	v_exp_f32_e32 v64, v64
	v_exp_f32_e32 v139, v139
	v_pk_add_f32 v[144:145], v[124:125], v[132:133]
	v_add_f32_e32 v64, 1.0, v64
	v_add_f32_e32 v139, 1.0, v139
	v_rcp_f32_e32 v64, v64
	v_rcp_f32_e32 v139, v139
	s_nop 0
	v_cvt_pk_bf16_f32 v140, v64, v139
	v_mul_f32_e32 v64, 0xbfb8aa3b, v142
	v_mul_f32_e32 v139, 0xbfb8aa3b, v143
	v_exp_f32_e32 v64, v64
	v_exp_f32_e32 v139, v139
	v_add_f32_e32 v64, 1.0, v64
	v_add_f32_e32 v139, 1.0, v139
	v_rcp_f32_e32 v64, v64
	v_rcp_f32_e32 v139, v139
	s_nop 0
	v_cvt_pk_bf16_f32 v141, v64, v139
	v_mul_f32_e32 v64, 0xbfb8aa3b, v146
	v_mul_f32_e32 v139, 0xbfb8aa3b, v147
	v_exp_f32_e32 v64, v64
	v_exp_f32_e32 v139, v139
	v_pk_add_f32 v[146:147], v[114:115], v[130:131]
	v_add_f32_e32 v64, 1.0, v64
	v_add_f32_e32 v139, 1.0, v139
	v_rcp_f32_e32 v64, v64
	v_rcp_f32_e32 v139, v139
	s_nop 0
	v_cvt_pk_bf16_f32 v142, v64, v139
	v_mul_f32_e32 v64, 0xbfb8aa3b, v144
	v_mul_f32_e32 v139, 0xbfb8aa3b, v145
	v_exp_f32_e32 v64, v64
	v_exp_f32_e32 v139, v139
	v_add_f32_e32 v64, 1.0, v64
	v_add_f32_e32 v139, 1.0, v139
	v_rcp_f32_e32 v64, v64
	v_rcp_f32_e32 v139, v139
	s_nop 0
	v_cvt_pk_bf16_f32 v143, v64, v139
	v_mad_u64_u32 v[138:139], s[4:5], v187, s76, v[138:139]
; __device__ __forceinline__ unsigned pk2(float lo, float hi) { f32x2_t v = {lo, hi}; bf16x2_t b = __builtin_convertvector(v, bf16x2_t); return __builtin_bit_cast(unsigned, b); }
; __device__ __forceinline__ float sigmoidf_(float x) { return __builtin_amdgcn_rcpf(1.0f + __expf(-x)); }
;     __device__ __forceinline__ void operator()(const f32x4 (&acc)[2][2][4][2], const Unit& u, int wr, int wc, int fr, int fq) const {
;     ...
; #pragma unroll
;                 for (int ai = 0; ai < 2; ++ai)
; #pragma unroll
;                     for (int m = 0; m < 4; ++m) {
;                         const int row = row0 + ai * 128 + m * 16;
;                         const f32x4 v0 = acc[ai][bj][m][0] + b0, v1 = acc[ai][bj][m][1] + b1;
;                         u32x4 w; w.x = pk2(sigmoidf_(v0[0]), sigmoidf_(v0[1])); w.y = pk2(sigmoidf_(v0[2]), sigmoidf_(v0[3]));
;                         w.z = pk2(sigmoidf_(v1[0]), sigmoidf_(v1[1])); w.w = pk2(sigmoidf_(v1[2]), sigmoidf_(v1[3]));
;                         __builtin_nontemporal_store(w, (u32x4*)(gates + (unsigned)(row * NG + gcol)));
	v_mov_b32_e32 v139, v65
	v_lshl_add_u64 v[144:145], v[138:139], 1, s[36:37]
	flat_store_dwordx4 v[144:145], v[140:143] nt
	v_pk_add_f32 v[144:145], v[116:117], v[132:133]
	s_mov_b64 s[4:5], 0
	v_pk_add_f32 v[140:141], v[118:119], v[134:135]
	v_pk_add_f32 v[142:143], v[120:121], v[136:137]
	v_mul_f32_e32 v64, 0xbfb8aa3b, v140
	v_mul_f32_e32 v139, 0xbfb8aa3b, v141
	v_exp_f32_e32 v64, v64
	v_exp_f32_e32 v139, v139
	v_add_f32_e32 v64, 1.0, v64
	v_add_f32_e32 v139, 1.0, v139
	v_rcp_f32_e32 v64, v64
	v_rcp_f32_e32 v139, v139
	s_nop 0
	v_cvt_pk_bf16_f32 v140, v64, v139
	v_mul_f32_e32 v64, 0xbfb8aa3b, v142
	v_mul_f32_e32 v139, 0xbfb8aa3b, v143
	v_exp_f32_e32 v64, v64
	v_exp_f32_e32 v139, v139
	v_add_f32_e32 v64, 1.0, v64
	v_add_f32_e32 v139, 1.0, v139
	v_rcp_f32_e32 v64, v64
	v_rcp_f32_e32 v139, v139
	s_nop 0
	v_cvt_pk_bf16_f32 v141, v64, v139
	v_mul_f32_e32 v64, 0xbfb8aa3b, v146
	v_mul_f32_e32 v139, 0xbfb8aa3b, v147
	v_exp_f32_e32 v64, v64
	v_exp_f32_e32 v139, v139
	v_pk_add_f32 v[146:147], v[110:111], v[134:135]
	v_add_f32_e32 v64, 1.0, v64
	v_add_f32_e32 v139, 1.0, v139
	v_rcp_f32_e32 v64, v64
	v_rcp_f32_e32 v139, v139
	s_nop 0
	v_cvt_pk_bf16_f32 v142, v64, v139
	v_mul_f32_e32 v64, 0xbfb8aa3b, v144
	v_mul_f32_e32 v139, 0xbfb8aa3b, v145
	v_exp_f32_e32 v64, v64
	v_exp_f32_e32 v139, v139
	v_add_f32_e32 v64, 1.0, v64
	v_add_f32_e32 v139, 1.0, v139
	v_rcp_f32_e32 v64, v64
	v_rcp_f32_e32 v139, v139
	s_nop 0
	v_cvt_pk_bf16_f32 v143, v64, v139
	v_add_u32_e32 v64, 0xc000, v138
	v_lshl_add_u64 v[144:145], v[64:65], 1, s[36:37]
	v_mul_f32_e32 v64, 0xbfb8aa3b, v146
	v_mul_f32_e32 v139, 0xbfb8aa3b, v147
	v_exp_f32_e32 v64, v64
	v_exp_f32_e32 v139, v139
	flat_store_dwordx4 v[144:145], v[140:143] nt
	v_pk_add_f32 v[144:145], v[112:113], v[136:137]
	v_add_f32_e32 v64, 1.0, v64
	v_add_f32_e32 v139, 1.0, v139
	v_rcp_f32_e32 v64, v64
	v_rcp_f32_e32 v139, v139
	v_pk_add_f32 v[142:143], v[106:107], v[130:131]
	v_pk_add_f32 v[140:141], v[108:109], v[132:133]
	v_pk_add_f32 v[146:147], v[98:99], v[130:131]
	v_cvt_pk_bf16_f32 v150, v64, v139
	v_mul_f32_e32 v64, 0xbfb8aa3b, v144
	v_mul_f32_e32 v139, 0xbfb8aa3b, v145
	v_exp_f32_e32 v64, v64
	v_exp_f32_e32 v139, v139
	v_pk_add_f32 v[144:145], v[100:101], v[132:133]
	v_add_f32_e32 v64, 1.0, v64
	v_add_f32_e32 v139, 1.0, v139
	v_rcp_f32_e32 v64, v64
	v_rcp_f32_e32 v139, v139
	s_nop 0
	v_cvt_pk_bf16_f32 v151, v64, v139
	v_mul_f32_e32 v64, 0xbfb8aa3b, v142
	v_mul_f32_e32 v139, 0xbfb8aa3b, v143
	v_exp_f32_e32 v64, v64
	v_exp_f32_e32 v139, v139
	v_pk_add_f32 v[142:143], v[104:105], v[136:137]
	v_add_f32_e32 v64, 1.0, v64
	v_add_f32_e32 v139, 1.0, v139
	v_rcp_f32_e32 v64, v64
	v_rcp_f32_e32 v139, v139
	s_nop 0
	v_cvt_pk_bf16_f32 v152, v64, v139
	v_mul_f32_e32 v64, 0xbfb8aa3b, v140
	v_mul_f32_e32 v139, 0xbfb8aa3b, v141
	v_exp_f32_e32 v64, v64
	v_exp_f32_e32 v139, v139
	v_add_f32_e32 v64, 1.0, v64
	v_add_f32_e32 v139, 1.0, v139
	v_rcp_f32_e32 v64, v64
	v_rcp_f32_e32 v139, v139
	s_nop 0
	v_cvt_pk_bf16_f32 v153, v64, v139
	v_add_u32_e32 v64, 0x18000, v138
	v_lshl_add_u64 v[140:141], v[64:65], 1, s[36:37]
	flat_store_dwordx4 v[140:141], v[150:153] nt
	v_pk_add_f32 v[140:141], v[102:103], v[134:135]
	s_nop 0
	v_mul_f32_e32 v64, 0xbfb8aa3b, v140
	v_mul_f32_e32 v139, 0xbfb8aa3b, v141
	v_exp_f32_e32 v64, v64
	v_exp_f32_e32 v139, v139
	v_add_f32_e32 v64, 1.0, v64
	v_add_f32_e32 v139, 1.0, v139
	v_rcp_f32_e32 v64, v64
	v_rcp_f32_e32 v139, v139
	s_nop 0
	v_cvt_pk_bf16_f32 v140, v64, v139
	v_mul_f32_e32 v64, 0xbfb8aa3b, v142
	v_mul_f32_e32 v139, 0xbfb8aa3b, v143
	v_exp_f32_e32 v64, v64
	v_exp_f32_e32 v139, v139
	v_add_f32_e32 v64, 1.0, v64
	v_add_f32_e32 v139, 1.0, v139
	v_rcp_f32_e32 v64, v64
	v_rcp_f32_e32 v139, v139
	s_nop 0
	v_cvt_pk_bf16_f32 v141, v64, v139
	v_mul_f32_e32 v64, 0xbfb8aa3b, v146
	v_mul_f32_e32 v139, 0xbfb8aa3b, v147
	v_exp_f32_e32 v64, v64
	v_exp_f32_e32 v139, v139
	v_pk_add_f32 v[146:147], v[90:91], v[130:131]
	v_add_f32_e32 v64, 1.0, v64
	v_add_f32_e32 v139, 1.0, v139
	v_rcp_f32_e32 v64, v64
	v_rcp_f32_e32 v139, v139
	s_nop 0
	v_cvt_pk_bf16_f32 v142, v64, v139
	v_mul_f32_e32 v64, 0xbfb8aa3b, v144
	v_mul_f32_e32 v139, 0xbfb8aa3b, v145
	v_exp_f32_e32 v64, v64
	v_exp_f32_e32 v139, v139
	v_add_f32_e32 v64, 1.0, v64
	v_add_f32_e32 v139, 1.0, v139
	v_rcp_f32_e32 v64, v64
	v_rcp_f32_e32 v139, v139
	s_nop 0
	v_cvt_pk_bf16_f32 v143, v64, v139
	v_add_u32_e32 v64, 0x24000, v138
	v_lshl_add_u64 v[144:145], v[64:65], 1, s[36:37]
	flat_store_dwordx4 v[144:145], v[140:143] nt
	v_pk_add_f32 v[144:145], v[92:93], v[132:133]
	s_nop 0
	v_pk_add_f32 v[140:141], v[94:95], v[134:135]
	v_pk_add_f32 v[142:143], v[96:97], v[136:137]
	v_mul_f32_e32 v64, 0xbfb8aa3b, v140
	v_mul_f32_e32 v139, 0xbfb8aa3b, v141
	v_exp_f32_e32 v64, v64
	v_exp_f32_e32 v139, v139
	v_add_f32_e32 v64, 1.0, v64
	v_add_f32_e32 v139, 1.0, v139
	v_rcp_f32_e32 v64, v64
	v_rcp_f32_e32 v139, v139
	s_nop 0
	v_cvt_pk_bf16_f32 v140, v64, v139
	v_mul_f32_e32 v64, 0xbfb8aa3b, v142
	v_mul_f32_e32 v139, 0xbfb8aa3b, v143
	v_exp_f32_e32 v64, v64
	v_exp_f32_e32 v139, v139
	v_add_f32_e32 v64, 1.0, v64
	v_add_f32_e32 v139, 1.0, v139
; __device__ __forceinline__ unsigned pk2(float lo, float hi) { f32x2_t v = {lo, hi}; bf16x2_t b = __builtin_convertvector(v, bf16x2_t); return __builtin_bit_cast(unsigned, b); }
; __device__ __forceinline__ float sigmoidf_(float x) { return __builtin_amdgcn_rcpf(1.0f + __expf(-x)); }
;     __device__ __forceinline__ void operator()(const f32x4 (&acc)[2][2][4][2], const Unit& u, int wr, int wc, int fr, int fq) const {
;     ...
; #pragma unroll
;                 for (int ai = 0; ai < 2; ++ai)
; #pragma unroll
;                     for (int m = 0; m < 4; ++m) {
;                         const int row = row0 + ai * 128 + m * 16;
;                         const f32x4 v0 = acc[ai][bj][m][0] + b0, v1 = acc[ai][bj][m][1] + b1;
;                         u32x4 w; w.x = pk2(sigmoidf_(v0[0]), sigmoidf_(v0[1])); w.y = pk2(sigmoidf_(v0[2]), sigmoidf_(v0[3]));
;                         w.z = pk2(sigmoidf_(v1[0]), sigmoidf_(v1[1])); w.w = pk2(sigmoidf_(v1[2]), sigmoidf_(v1[3]));
;                         __builtin_nontemporal_store(w, (u32x4*)(gates + (unsigned)(row * NG + gcol)));
	v_rcp_f32_e32 v64, v64
	v_rcp_f32_e32 v139, v139
	s_nop 0
	v_cvt_pk_bf16_f32 v141, v64, v139
	v_mul_f32_e32 v64, 0xbfb8aa3b, v146
	v_mul_f32_e32 v139, 0xbfb8aa3b, v147
	v_exp_f32_e32 v64, v64
	v_exp_f32_e32 v139, v139
	v_pk_add_f32 v[146:147], v[82:83], v[130:131]
	v_add_f32_e32 v64, 1.0, v64
	v_add_f32_e32 v139, 1.0, v139
	v_rcp_f32_e32 v64, v64
	v_rcp_f32_e32 v139, v139
	s_nop 0
	v_cvt_pk_bf16_f32 v142, v64, v139
	v_mul_f32_e32 v64, 0xbfb8aa3b, v144
	v_mul_f32_e32 v139, 0xbfb8aa3b, v145
	v_exp_f32_e32 v64, v64
	v_exp_f32_e32 v139, v139
	v_add_f32_e32 v64, 1.0, v64
	v_add_f32_e32 v139, 1.0, v139
	v_rcp_f32_e32 v64, v64
	v_rcp_f32_e32 v139, v139
	s_nop 0
	v_cvt_pk_bf16_f32 v143, v64, v139
	v_add_u32_e32 v64, 0x60000, v138
	v_lshl_add_u64 v[144:145], v[64:65], 1, s[36:37]
	flat_store_dwordx4 v[144:145], v[140:143] nt
	v_pk_add_f32 v[144:145], v[84:85], v[132:133]
	s_nop 0
	v_pk_add_f32 v[140:141], v[86:87], v[134:135]
	v_pk_add_f32 v[142:143], v[88:89], v[136:137]
	v_mul_f32_e32 v64, 0xbfb8aa3b, v140
	v_mul_f32_e32 v139, 0xbfb8aa3b, v141
	v_exp_f32_e32 v64, v64
	v_exp_f32_e32 v139, v139
	v_add_f32_e32 v64, 1.0, v64
	v_add_f32_e32 v139, 1.0, v139
	v_rcp_f32_e32 v64, v64
	v_rcp_f32_e32 v139, v139
	s_nop 0
	v_cvt_pk_bf16_f32 v140, v64, v139
	v_mul_f32_e32 v64, 0xbfb8aa3b, v142
	v_mul_f32_e32 v139, 0xbfb8aa3b, v143
	v_exp_f32_e32 v64, v64
	v_exp_f32_e32 v139, v139
	v_add_f32_e32 v64, 1.0, v64
	v_add_f32_e32 v139, 1.0, v139
	v_rcp_f32_e32 v64, v64
	v_rcp_f32_e32 v139, v139
	s_nop 0
	v_cvt_pk_bf16_f32 v141, v64, v139
	v_mul_f32_e32 v64, 0xbfb8aa3b, v146
	v_mul_f32_e32 v139, 0xbfb8aa3b, v147
	v_exp_f32_e32 v64, v64
	v_exp_f32_e32 v139, v139
	v_pk_add_f32 v[146:147], v[74:75], v[130:131]
	v_add_f32_e32 v64, 1.0, v64
	v_add_f32_e32 v139, 1.0, v139
	v_rcp_f32_e32 v64, v64
	v_rcp_f32_e32 v139, v139
	s_nop 0
	v_cvt_pk_bf16_f32 v142, v64, v139
	v_mul_f32_e32 v64, 0xbfb8aa3b, v144
	v_mul_f32_e32 v139, 0xbfb8aa3b, v145
	v_exp_f32_e32 v64, v64
	v_exp_f32_e32 v139, v139
	v_add_f32_e32 v64, 1.0, v64
	v_add_f32_e32 v139, 1.0, v139
	v_rcp_f32_e32 v64, v64
	v_rcp_f32_e32 v139, v139
	s_nop 0
	v_cvt_pk_bf16_f32 v143, v64, v139
	v_add_u32_e32 v64, 0x6c000, v138
	v_lshl_add_u64 v[144:145], v[64:65], 1, s[36:37]
	flat_store_dwordx4 v[144:145], v[140:143] nt
	v_pk_add_f32 v[144:145], v[76:77], v[132:133]
	s_nop 0
	v_pk_add_f32 v[140:141], v[78:79], v[134:135]
	v_pk_add_f32 v[142:143], v[80:81], v[136:137]
	v_mul_f32_e32 v64, 0xbfb8aa3b, v140
	v_mul_f32_e32 v139, 0xbfb8aa3b, v141
	v_exp_f32_e32 v64, v64
	v_exp_f32_e32 v139, v139
	v_pk_add_f32 v[134:135], v[70:71], v[134:135]
	v_pk_add_f32 v[136:137], v[72:73], v[136:137]
	v_add_f32_e32 v64, 1.0, v64
	v_add_f32_e32 v139, 1.0, v139
	v_rcp_f32_e32 v64, v64
	v_rcp_f32_e32 v139, v139
	s_nop 0
	v_cvt_pk_bf16_f32 v140, v64, v139
	v_mul_f32_e32 v64, 0xbfb8aa3b, v142
	v_mul_f32_e32 v139, 0xbfb8aa3b, v143
	v_exp_f32_e32 v64, v64
	v_exp_f32_e32 v139, v139
	v_add_f32_e32 v64, 1.0, v64
	v_add_f32_e32 v139, 1.0, v139
	v_rcp_f32_e32 v64, v64
	v_rcp_f32_e32 v139, v139
	s_nop 0
	v_cvt_pk_bf16_f32 v141, v64, v139
	v_mul_f32_e32 v64, 0xbfb8aa3b, v146
	v_mul_f32_e32 v139, 0xbfb8aa3b, v147
	v_exp_f32_e32 v64, v64
	v_exp_f32_e32 v139, v139
	v_add_f32_e32 v64, 1.0, v64
	v_add_f32_e32 v139, 1.0, v139
	v_rcp_f32_e32 v64, v64
	v_rcp_f32_e32 v139, v139
	s_nop 0
	v_cvt_pk_bf16_f32 v142, v64, v139
	v_mul_f32_e32 v64, 0xbfb8aa3b, v144
	v_mul_f32_e32 v139, 0xbfb8aa3b, v145
	v_exp_f32_e32 v64, v64
	v_exp_f32_e32 v139, v139
	v_add_f32_e32 v64, 1.0, v64
	v_add_f32_e32 v139, 1.0, v139
	v_rcp_f32_e32 v64, v64
	v_rcp_f32_e32 v139, v139
	s_nop 0
	v_cvt_pk_bf16_f32 v143, v64, v139
	v_add_u32_e32 v64, 0x78000, v138
	v_lshl_add_u64 v[144:145], v[64:65], 1, s[36:37]
	flat_store_dwordx4 v[144:145], v[140:143] nt
	v_mul_f32_e32 v64, 0xbfb8aa3b, v134
	v_exp_f32_e32 v64, v64
	v_pk_add_f32 v[140:141], v[68:69], v[132:133]
	v_pk_add_f32 v[132:133], v[66:67], v[130:131]
	v_mul_f32_e32 v130, 0xbfb8aa3b, v135
	v_exp_f32_e32 v130, v130
	v_add_f32_e32 v64, 1.0, v64
	v_rcp_f32_e32 v64, v64
	v_mul_f32_e32 v131, 0xbfb8aa3b, v137
	v_add_f32_e32 v130, 1.0, v130
	v_rcp_f32_e32 v130, v130
	v_exp_f32_e32 v131, v131
	v_cvt_pk_bf16_f32 v130, v64, v130
	v_mul_f32_e32 v64, 0xbfb8aa3b, v136
	v_exp_f32_e32 v64, v64
	v_add_f32_e32 v131, 1.0, v131
	v_rcp_f32_e32 v131, v131
	v_add_f32_e32 v64, 1.0, v64
	v_rcp_f32_e32 v64, v64
	s_nop 0
	v_cvt_pk_bf16_f32 v131, v64, v131
	v_mul_f32_e32 v64, 0xbfb8aa3b, v132
	v_mul_f32_e32 v132, 0xbfb8aa3b, v133
	v_exp_f32_e32 v64, v64
	v_exp_f32_e32 v132, v132
	v_mul_f32_e32 v133, 0xbfb8aa3b, v141
	v_exp_f32_e32 v133, v133
	v_add_f32_e32 v64, 1.0, v64
	v_add_f32_e32 v132, 1.0, v132
	v_rcp_f32_e32 v64, v64
	v_rcp_f32_e32 v132, v132
	v_add_f32_e32 v133, 1.0, v133
	v_rcp_f32_e32 v133, v133
	v_cvt_pk_bf16_f32 v132, v64, v132
	v_mul_f32_e32 v64, 0xbfb8aa3b, v140
	v_exp_f32_e32 v64, v64
	s_nop 0
	v_add_f32_e32 v64, 1.0, v64
	v_rcp_f32_e32 v64, v64
	s_nop 0
	v_cvt_pk_bf16_f32 v133, v64, v133
	v_add_u32_e32 v64, 0x84000, v138
	v_lshl_add_u64 v[134:135], v[64:65], 1, s[36:37]
	flat_store_dwordx4 v[134:135], v[130:133] nt

; #define PG8_STAGE(bufoff, gbase, voff) do { _Pragma("unroll") for (int _i = 0; _i < 2; ++_i) \
;         __builtin_amdgcn_global_load_lds((const unsigned*)((const char*)(gbase) + (voff)[_i]), (PG8_LAS unsigned*)(lds + (bufoff) + ldsw + _i * 8192), 16, 0, 0); } while (0)
; #define PG8_LDA(dst, b, h) do { _Pragma("unroll") for (int m = 0; m < 4; ++m) _Pragma("unroll") for (int k = 0; k < 2; ++k) dst[m][k] = *(const PG8_LAS bf16x8*)(lds + PG8_SA(b, h) + aoff + m * 2048 + k * 1024); } while (0)
; #define PG8_LDB(dst, b, h) do { _Pragma("unroll") for (int n = 0; n < 2; ++n) _Pragma("unroll") for (int k = 0; k < 2; ++k) dst[n][k] = *(const PG8_LAS bf16x8*)(lds + PG8_SB(b, h) + boff + n * 2048 + k * 1024); } while (0)
; #define PG8_MMA(ai, bj, At, Bt) do { __builtin_amdgcn_s_setprio(1); _Pragma("unroll") for (int m = 0; m < 4; ++m) _Pragma("unroll") for (int n = 0; n < 2; ++n) _Pragma("unroll") for (int k = 0; k < 2; ++k) \
;         acc[ai][bj][m][n] = __builtin_amdgcn_mfma_f32_16x16x32_bf16(Bt[n][k], At[m][k], acc[ai][bj][m][n], 0, 0, 0); __builtin_amdgcn_s_setprio(0); } while (0)
; #define PG8_WAIT_V(n) asm volatile("s_waitcnt vmcnt(" #n ")" ::: "memory")
; #define PG8_BAR __builtin_amdgcn_s_barrier()
; template <class Epi, class Sched, bool ALIGN_EPI = false, bool SP2 = false>
; __device__ __forceinline__ void gemm_phase(PG8_LAS unsigned char* lds, const Gemm g, const Sched& S, const Epi& E, const int tid) {
;     ...
;         for (int t = 0; t < nt; t += 2) {
;             const bool last = (t == nt - 2);
;             const char* a1 = cA + (size_t)(t + 1) * kstep;
;             const char* a2 = last ? nA : cA + (size_t)(t + 2) * kstep; const char* b2 = last ? nB : cB + (size_t)(t + 2) * kstep;
;             const char* a3 = a2 + kstep; const char* b3 = b2 + kstep;
;             if (last && has_next) S.a_ready(nxt);
;             if constexpr (SP2) {
;             PG8_LDB(B0, 0, 0); PG8_LDB(B1, 0, 1); PG8_SCHED; PG8_LDA(At, 0, 0); PG8_STAGE(PG8_SA(1, 1), a1 + hstep, voffA);
;             PG8_WAIT_V(8); PG8_WAIT_L(0); PG8_BAR; PG8_MMA(0, 0, At, B0); PG8_MMA(0, 1, At, B1); PG8_BAR; PG8_SCHED;
;             PG8_LDA(At, 0, 1); PG8_STAGE(PG8_SB(0, 0), b2, voffB); PG8_STAGE(PG8_SB(0, 1), b2 + hstep, voffB); PG8_STAGE(PG8_SA(0, 0), a2, voffA);
;             PG8_WAIT_V(8); PG8_WAIT_L(0); PG8_BAR; PG8_MMA(1, 0, At, B0); PG8_MMA(1, 1, At, B1); PG8_BAR; PG8_SCHED;
.LBB0_704:
	s_add_u32 s24, s2, 0xfffc0080
	s_addc_u32 s25, s3, -1
	s_add_i32 s51, 0, 0x10000
	s_cmp_eq_u32 s50, 12
	s_cselect_b32 s27, s17, s25
	s_cselect_b32 s26, s29, s24
	v_add_u32_e32 v64, s51, v213
	s_cselect_b32 s25, s15, s49
	s_cselect_b32 s24, s47, s48
	s_add_i32 s54, 0, 0x14000
	ds_read_b128 v[130:133], v64
	ds_read_b128 v[134:137], v64 offset:1024
	ds_read_b128 v[138:141], v64 offset:2048
	ds_read_b128 v[142:145], v64 offset:3072
	v_add_u32_e32 v64, s54, v213
	ds_read_b128 v[146:149], v64
	ds_read_b128 v[150:153], v64 offset:1024
	ds_read_b128 v[154:157], v64 offset:2048
	ds_read_b128 v[158:161], v64 offset:3072
	v_lshl_add_u64 v[202:203], s[2:3], 0, v[198:199]
	s_add_i32 m0, s35, 0xc000
	ds_read_b128 v[162:165], v227
	ds_read_b128 v[166:169], v227 offset:1024
	ds_read_b128 v[170:173], v227 offset:2048
	ds_read_b128 v[174:177], v227 offset:3072
	ds_read_b128 v[178:181], v227 offset:4096
	ds_read_b128 v[182:185], v227 offset:5120
	ds_read_b128 v[218:221], v227 offset:6144
	ds_read_b128 v[222:225], v227 offset:7168
	global_load_lds_dwordx4 v[202:203], off
	v_lshl_add_u64 v[202:203], s[2:3], 0, v[196:197]
	s_add_i32 m0, s35, 0xe000
	s_nop 0
	global_load_lds_dwordx4 v[202:203], off
	s_waitcnt vmcnt(8)
	s_waitcnt lgkmcnt(0)
	s_setprio 1
	s_barrier
	v_mfma_f32_16x16x32_bf16 v[126:129], v[130:133], v[162:165], v[126:129]
	v_mfma_f32_16x16x32_bf16 v[122:125], v[138:141], v[162:165], v[122:125]
	v_mfma_f32_16x16x32_bf16 v[118:121], v[130:133], v[170:173], v[118:121]
	v_mfma_f32_16x16x32_bf16 v[114:117], v[138:141], v[170:173], v[114:117]
	v_mfma_f32_16x16x32_bf16 v[110:113], v[130:133], v[178:181], v[110:113]
	v_mfma_f32_16x16x32_bf16 v[106:109], v[138:141], v[178:181], v[106:109]
	v_mfma_f32_16x16x32_bf16 v[102:105], v[130:133], v[218:221], v[102:105]
	v_mfma_f32_16x16x32_bf16 v[98:101], v[138:141], v[218:221], v[98:101]
	v_mfma_f32_16x16x32_bf16 v[126:129], v[134:137], v[166:169], v[126:129]
	v_mfma_f32_16x16x32_bf16 v[122:125], v[142:145], v[166:169], v[122:125]
	v_mfma_f32_16x16x32_bf16 v[118:121], v[134:137], v[174:177], v[118:121]
	v_mfma_f32_16x16x32_bf16 v[114:117], v[142:145], v[174:177], v[114:117]
	v_mfma_f32_16x16x32_bf16 v[110:113], v[134:137], v[182:185], v[110:113]
	v_mfma_f32_16x16x32_bf16 v[106:109], v[142:145], v[182:185], v[106:109]
	v_mfma_f32_16x16x32_bf16 v[102:105], v[134:137], v[222:225], v[102:105]
	v_mfma_f32_16x16x32_bf16 v[98:101], v[142:145], v[222:225], v[98:101]
	v_mfma_f32_16x16x32_bf16 v[60:63], v[146:149], v[162:165], v[60:63]
	v_mfma_f32_16x16x32_bf16 v[56:59], v[154:157], v[162:165], v[56:59]
	v_mfma_f32_16x16x32_bf16 v[52:55], v[146:149], v[170:173], v[52:55]
	v_mfma_f32_16x16x32_bf16 v[48:51], v[154:157], v[170:173], v[48:51]
	v_mfma_f32_16x16x32_bf16 v[44:47], v[146:149], v[178:181], v[44:47]
	v_mfma_f32_16x16x32_bf16 v[40:43], v[154:157], v[178:181], v[40:43]
	v_mfma_f32_16x16x32_bf16 v[36:39], v[146:149], v[218:221], v[36:39]
	v_mfma_f32_16x16x32_bf16 v[32:35], v[154:157], v[218:221], v[32:35]
	v_mfma_f32_16x16x32_bf16 v[60:63], v[150:153], v[166:169], v[60:63]
	v_mfma_f32_16x16x32_bf16 v[56:59], v[158:161], v[166:169], v[56:59]
	v_mfma_f32_16x16x32_bf16 v[52:55], v[150:153], v[174:177], v[52:55]
	v_mfma_f32_16x16x32_bf16 v[48:51], v[158:161], v[174:177], v[48:51]
	v_mfma_f32_16x16x32_bf16 v[44:47], v[150:153], v[182:185], v[44:47]
	v_mfma_f32_16x16x32_bf16 v[40:43], v[158:161], v[182:185], v[40:43]
	v_mfma_f32_16x16x32_bf16 v[36:39], v[150:153], v[222:225], v[36:39]
	v_mfma_f32_16x16x32_bf16 v[32:35], v[158:161], v[222:225], v[32:35]
	s_barrier
	s_setprio 0
	s_add_i32 s51, s51, s34
	v_lshl_add_u64 v[202:203], s[24:25], 0, v[190:191]
	s_mov_b32 m0, s51
	ds_read_b128 v[162:165], v227 offset:16384
	ds_read_b128 v[166:169], v227 offset:17408
	ds_read_b128 v[170:173], v227 offset:18432
	ds_read_b128 v[174:177], v227 offset:19456
	ds_read_b128 v[178:181], v227 offset:20480
	ds_read_b128 v[182:185], v227 offset:21504
	ds_read_b128 v[218:221], v227 offset:22528
	ds_read_b128 v[222:225], v227 offset:23552
	global_load_lds_dwordx4 v[202:203], off
	s_add_i32 m0, s51, 0x2000
	s_add_u32 s52, s24, 0x40000
	v_lshl_add_u64 v[206:207], s[24:25], 0, v[186:187]
	s_addc_u32 s53, s25, 0
	s_add_i32 s51, s54, s34
	global_load_lds_dwordx4 v[206:207], off
	v_lshl_add_u64 v[208:209], s[52:53], 0, v[190:191]
	s_mov_b32 m0, s51
	v_lshl_add_u64 v[214:215], s[26:27], 0, v[188:189]
	global_load_lds_dwordx4 v[208:209], off
	v_lshl_add_u64 v[208:209], s[52:53], 0, v[186:187]
	s_add_i32 m0, s51, 0x2000
	s_nop 0
	global_load_lds_dwordx4 v[208:209], off
	v_lshl_add_u64 v[208:209], s[26:27], 0, v[192:193]
	s_mov_b32 m0, s35
	s_nop 0
	global_load_lds_dwordx4 v[208:209], off
	s_mov_b32 m0, s39
	s_nop 0
	global_load_lds_dwordx4 v[214:215], off
	s_waitcnt vmcnt(8)
	s_waitcnt lgkmcnt(0)
	s_setprio 1
	s_barrier
; #define PG8_STAGE(bufoff, gbase, voff) do { _Pragma("unroll") for (int _i = 0; _i < 2; ++_i) \
;         __builtin_amdgcn_global_load_lds((const unsigned*)((const char*)(gbase) + (voff)[_i]), (PG8_LAS unsigned*)(lds + (bufoff) + ldsw + _i * 8192), 16, 0, 0); } while (0)
; #define PG8_LDA(dst, b, h) do { _Pragma("unroll") for (int m = 0; m < 4; ++m) _Pragma("unroll") for (int k = 0; k < 2; ++k) dst[m][k] = *(const PG8_LAS bf16x8*)(lds + PG8_SA(b, h) + aoff + m * 2048 + k * 1024); } while (0)
; #define PG8_LDB(dst, b, h) do { _Pragma("unroll") for (int n = 0; n < 2; ++n) _Pragma("unroll") for (int k = 0; k < 2; ++k) dst[n][k] = *(const PG8_LAS bf16x8*)(lds + PG8_SB(b, h) + boff + n * 2048 + k * 1024); } while (0)
; #define PG8_MMA(ai, bj, At, Bt) do { __builtin_amdgcn_s_setprio(1); _Pragma("unroll") for (int m = 0; m < 4; ++m) _Pragma("unroll") for (int n = 0; n < 2; ++n) _Pragma("unroll") for (int k = 0; k < 2; ++k) \
;         acc[ai][bj][m][n] = __builtin_amdgcn_mfma_f32_16x16x32_bf16(Bt[n][k], At[m][k], acc[ai][bj][m][n], 0, 0, 0); __builtin_amdgcn_s_setprio(0); } while (0)
; #define PG8_WAIT_V(n) asm volatile("s_waitcnt vmcnt(" #n ")" ::: "memory")
; #define PG8_WAIT_L(n) asm volatile("s_waitcnt lgkmcnt(" #n ")" ::: "memory")
; #define PG8_BAR __builtin_amdgcn_s_barrier()
; #define PG8_SCHED __builtin_amdgcn_sched_barrier(0)
; template <class Epi, class Sched, bool ALIGN_EPI = false, bool SP2 = false>
; __device__ __forceinline__ void gemm_phase(PG8_LAS unsigned char* lds, const Gemm g, const Sched& S, const Epi& E, const int tid) {
;     ...
;             PG8_WAIT_V(8); PG8_WAIT_L(0); PG8_BAR; PG8_MMA(1, 0, At, B0); PG8_MMA(1, 1, At, B1); PG8_BAR; PG8_SCHED;
;             PG8_LDB(B0, 1, 0); PG8_LDB(B1, 1, 1); PG8_SCHED; PG8_LDA(At, 1, 0); PG8_STAGE(PG8_SA(0, 1), a2 + hstep, voffA);
;             PG8_WAIT_V(8); PG8_WAIT_L(0); PG8_BAR; PG8_MMA(0, 0, At, B0); PG8_MMA(0, 1, At, B1); PG8_BAR; PG8_SCHED;
	v_mfma_f32_16x16x32_bf16 v[94:97], v[130:133], v[162:165], v[94:97]
	v_mfma_f32_16x16x32_bf16 v[90:93], v[138:141], v[162:165], v[90:93]
	v_mfma_f32_16x16x32_bf16 v[86:89], v[130:133], v[170:173], v[86:89]
	v_mfma_f32_16x16x32_bf16 v[82:85], v[138:141], v[170:173], v[82:85]
	v_mfma_f32_16x16x32_bf16 v[78:81], v[130:133], v[178:181], v[78:81]
	v_mfma_f32_16x16x32_bf16 v[74:77], v[138:141], v[178:181], v[74:77]
	v_mfma_f32_16x16x32_bf16 v[70:73], v[130:133], v[218:221], v[70:73]
	v_mfma_f32_16x16x32_bf16 v[66:69], v[138:141], v[218:221], v[66:69]
	v_mfma_f32_16x16x32_bf16 v[94:97], v[134:137], v[166:169], v[94:97]
	v_mfma_f32_16x16x32_bf16 v[90:93], v[142:145], v[166:169], v[90:93]
	v_mfma_f32_16x16x32_bf16 v[86:89], v[134:137], v[174:177], v[86:89]
	v_mfma_f32_16x16x32_bf16 v[82:85], v[142:145], v[174:177], v[82:85]
	v_mfma_f32_16x16x32_bf16 v[78:81], v[134:137], v[182:185], v[78:81]
	v_mfma_f32_16x16x32_bf16 v[74:77], v[142:145], v[182:185], v[74:77]
	v_mfma_f32_16x16x32_bf16 v[70:73], v[134:137], v[222:225], v[70:73]
	v_mfma_f32_16x16x32_bf16 v[66:69], v[142:145], v[222:225], v[66:69]
	v_mfma_f32_16x16x32_bf16 v[28:31], v[146:149], v[162:165], v[28:31]
	v_mfma_f32_16x16x32_bf16 v[24:27], v[154:157], v[162:165], v[24:27]
	v_mfma_f32_16x16x32_bf16 v[20:23], v[146:149], v[170:173], v[20:23]
	v_mfma_f32_16x16x32_bf16 v[16:19], v[154:157], v[170:173], v[16:19]
	v_mfma_f32_16x16x32_bf16 v[12:15], v[146:149], v[178:181], v[12:15]
	v_mfma_f32_16x16x32_bf16 v[8:11], v[154:157], v[178:181], v[8:11]
	v_mfma_f32_16x16x32_bf16 v[4:7], v[146:149], v[218:221], v[4:7]
	v_mfma_f32_16x16x32_bf16 v[0:3], v[154:157], v[218:221], v[0:3]
	v_mfma_f32_16x16x32_bf16 v[28:31], v[150:153], v[166:169], v[28:31]
	v_mfma_f32_16x16x32_bf16 v[24:27], v[158:161], v[166:169], v[24:27]
	v_mfma_f32_16x16x32_bf16 v[20:23], v[150:153], v[174:177], v[20:23]
	v_mfma_f32_16x16x32_bf16 v[16:19], v[158:161], v[174:177], v[16:19]
	v_mfma_f32_16x16x32_bf16 v[12:15], v[150:153], v[182:185], v[12:15]
	v_mfma_f32_16x16x32_bf16 v[8:11], v[158:161], v[182:185], v[8:11]
	v_mfma_f32_16x16x32_bf16 v[4:7], v[150:153], v[222:225], v[4:7]
	v_mfma_f32_16x16x32_bf16 v[0:3], v[158:161], v[222:225], v[0:3]
	s_barrier
	s_setprio 0
	s_add_i32 s51, 0, 0x18000
	v_add_u32_e32 v64, s51, v213
	s_add_i32 s52, 0, 0x1c000
	ds_read_b128 v[130:133], v64
	ds_read_b128 v[134:137], v64 offset:1024
	ds_read_b128 v[138:141], v64 offset:2048
	ds_read_b128 v[142:145], v64 offset:3072
	v_add_u32_e32 v64, s52, v213
	ds_read_b128 v[146:149], v64
	ds_read_b128 v[150:153], v64 offset:1024
	ds_read_b128 v[154:157], v64 offset:2048
	ds_read_b128 v[158:161], v64 offset:3072
	s_add_u32 s26, s26, 0x40000
	s_addc_u32 s27, s27, 0
	s_mov_b32 m0, s42
	v_lshl_add_u64 v[228:229], s[26:27], 0, v[192:193]
	ds_read_b128 v[162:165], v227 offset:32768
	ds_read_b128 v[166:169], v227 offset:33792
	ds_read_b128 v[170:173], v227 offset:34816
	ds_read_b128 v[174:177], v227 offset:35840
	ds_read_b128 v[178:181], v227 offset:36864
	ds_read_b128 v[182:185], v227 offset:37888
	ds_read_b128 v[218:221], v227 offset:38912
	ds_read_b128 v[222:225], v227 offset:39936
	global_load_lds_dwordx4 v[228:229], off
	v_lshl_add_u64 v[228:229], s[26:27], 0, v[188:189]
	s_mov_b32 m0, s43
	s_nop 0
	global_load_lds_dwordx4 v[228:229], off
	s_waitcnt vmcnt(8)
	s_waitcnt lgkmcnt(0)
	s_setprio 1
	s_barrier
	v_mfma_f32_16x16x32_bf16 v[126:129], v[130:133], v[162:165], v[126:129]
	v_mfma_f32_16x16x32_bf16 v[122:125], v[138:141], v[162:165], v[122:125]
	v_mfma_f32_16x16x32_bf16 v[118:121], v[130:133], v[170:173], v[118:121]
	v_mfma_f32_16x16x32_bf16 v[114:117], v[138:141], v[170:173], v[114:117]
	v_mfma_f32_16x16x32_bf16 v[110:113], v[130:133], v[178:181], v[110:113]
	v_mfma_f32_16x16x32_bf16 v[106:109], v[138:141], v[178:181], v[106:109]
	v_mfma_f32_16x16x32_bf16 v[102:105], v[130:133], v[218:221], v[102:105]
	v_mfma_f32_16x16x32_bf16 v[98:101], v[138:141], v[218:221], v[98:101]
	v_mfma_f32_16x16x32_bf16 v[126:129], v[134:137], v[166:169], v[126:129]
	v_mfma_f32_16x16x32_bf16 v[122:125], v[142:145], v[166:169], v[122:125]
	v_mfma_f32_16x16x32_bf16 v[118:121], v[134:137], v[174:177], v[118:121]
	v_mfma_f32_16x16x32_bf16 v[114:117], v[142:145], v[174:177], v[114:117]
	v_mfma_f32_16x16x32_bf16 v[110:113], v[134:137], v[182:185], v[110:113]
	v_mfma_f32_16x16x32_bf16 v[106:109], v[142:145], v[182:185], v[106:109]
	v_mfma_f32_16x16x32_bf16 v[102:105], v[134:137], v[222:225], v[102:105]
	v_mfma_f32_16x16x32_bf16 v[98:101], v[142:145], v[222:225], v[98:101]
	v_mfma_f32_16x16x32_bf16 v[60:63], v[146:149], v[162:165], v[60:63]
	v_mfma_f32_16x16x32_bf16 v[56:59], v[154:157], v[162:165], v[56:59]
	v_mfma_f32_16x16x32_bf16 v[52:55], v[146:149], v[170:173], v[52:55]
	v_mfma_f32_16x16x32_bf16 v[48:51], v[154:157], v[170:173], v[48:51]
	v_mfma_f32_16x16x32_bf16 v[44:47], v[146:149], v[178:181], v[44:47]
	v_mfma_f32_16x16x32_bf16 v[40:43], v[154:157], v[178:181], v[40:43]
	v_mfma_f32_16x16x32_bf16 v[36:39], v[146:149], v[218:221], v[36:39]
	v_mfma_f32_16x16x32_bf16 v[32:35], v[154:157], v[218:221], v[32:35]
	v_mfma_f32_16x16x32_bf16 v[60:63], v[150:153], v[166:169], v[60:63]
	v_mfma_f32_16x16x32_bf16 v[56:59], v[158:161], v[166:169], v[56:59]
	v_mfma_f32_16x16x32_bf16 v[52:55], v[150:153], v[174:177], v[52:55]
	v_mfma_f32_16x16x32_bf16 v[48:51], v[158:161], v[174:177], v[48:51]
	v_mfma_f32_16x16x32_bf16 v[44:47], v[150:153], v[182:185], v[44:47]
	v_mfma_f32_16x16x32_bf16 v[40:43], v[158:161], v[182:185], v[40:43]
	v_mfma_f32_16x16x32_bf16 v[36:39], v[150:153], v[222:225], v[36:39]
	v_mfma_f32_16x16x32_bf16 v[32:35], v[158:161], v[222:225], v[32:35]
	s_barrier
; #define PG8_STAGE(bufoff, gbase, voff) do { _Pragma("unroll") for (int _i = 0; _i < 2; ++_i) \
;         __builtin_amdgcn_global_load_lds((const unsigned*)((const char*)(gbase) + (voff)[_i]), (PG8_LAS unsigned*)(lds + (bufoff) + ldsw + _i * 8192), 16, 0, 0); } while (0)
; #define PG8_LDA(dst, b, h) do { _Pragma("unroll") for (int m = 0; m < 4; ++m) _Pragma("unroll") for (int k = 0; k < 2; ++k) dst[m][k] = *(const PG8_LAS bf16x8*)(lds + PG8_SA(b, h) + aoff + m * 2048 + k * 1024); } while (0)
; #define PG8_MMA(ai, bj, At, Bt) do { __builtin_amdgcn_s_setprio(1); _Pragma("unroll") for (int m = 0; m < 4; ++m) _Pragma("unroll") for (int n = 0; n < 2; ++n) _Pragma("unroll") for (int k = 0; k < 2; ++k) \
;         acc[ai][bj][m][n] = __builtin_amdgcn_mfma_f32_16x16x32_bf16(Bt[n][k], At[m][k], acc[ai][bj][m][n], 0, 0, 0); __builtin_amdgcn_s_setprio(0); } while (0)
; #define PG8_WAIT_V(n) asm volatile("s_waitcnt vmcnt(" #n ")" ::: "memory")
; #define PG8_WAIT_L(n) asm volatile("s_waitcnt lgkmcnt(" #n ")" ::: "memory")
; #define PG8_BAR __builtin_amdgcn_s_barrier()
; #define PG8_SCHED __builtin_amdgcn_sched_barrier(0)
; template <class Epi, class Sched, bool ALIGN_EPI = false, bool SP2 = false>
; __device__ __forceinline__ void gemm_phase(PG8_LAS unsigned char* lds, const Gemm g, const Sched& S, const Epi& E, const int tid) {
;     ...
;             PG8_LDA(At, 1, 1); PG8_STAGE(PG8_SB(1, 0), b3, voffB); PG8_STAGE(PG8_SB(1, 1), b3 + hstep, voffB); PG8_STAGE(PG8_SA(1, 0), a3, voffA);
;             PG8_WAIT_V(8); PG8_WAIT_L(0); PG8_BAR; PG8_MMA(1, 0, At, B0); PG8_MMA(1, 1, At, B1); PG8_BAR; PG8_SCHED;
;     ...
;         if constexpr (ALIGN_EPI) { if (wr == 0) PG8_BAR; }
	s_setprio 0
	s_add_i32 s26, s51, s34
	v_lshl_add_u64 v[202:203], v[202:203], 0, s[94:95]
	s_mov_b32 m0, s26
	ds_read_b128 v[162:165], v227 offset:49152
	ds_read_b128 v[166:169], v227 offset:50176
	ds_read_b128 v[170:173], v227 offset:51200
	ds_read_b128 v[174:177], v227 offset:52224
	ds_read_b128 v[178:181], v227 offset:53248
	ds_read_b128 v[182:185], v227 offset:54272
	ds_read_b128 v[218:221], v227 offset:55296
	ds_read_b128 v[222:225], v227 offset:56320
	global_load_lds_dwordx4 v[202:203], off
	s_add_i32 m0, s26, 0x2000
	s_add_u32 s24, s24, 0x40080
	v_lshl_add_u64 v[202:203], v[206:207], 0, s[94:95]
	s_addc_u32 s25, s25, 0
	s_add_i32 s26, s52, s34
	global_load_lds_dwordx4 v[202:203], off
	v_lshl_add_u64 v[202:203], s[24:25], 0, v[190:191]
	s_mov_b32 m0, s26
	s_nop 0
	global_load_lds_dwordx4 v[202:203], off
	v_lshl_add_u64 v[202:203], s[24:25], 0, v[186:187]
	s_add_i32 m0, s26, 0x2000
	s_nop 0
	global_load_lds_dwordx4 v[202:203], off
	v_lshl_add_u64 v[202:203], v[208:209], 0, s[94:95]
	s_mov_b32 m0, s38
	s_nop 0
	global_load_lds_dwordx4 v[202:203], off
	v_lshl_add_u64 v[202:203], v[214:215], 0, s[94:95]
	s_mov_b32 m0, s44
	s_nop 0
	global_load_lds_dwordx4 v[202:203], off
	s_waitcnt vmcnt(8)
	s_waitcnt lgkmcnt(0)
	s_setprio 1
	s_barrier
	v_mfma_f32_16x16x32_bf16 v[94:97], v[130:133], v[162:165], v[94:97]
	v_mfma_f32_16x16x32_bf16 v[90:93], v[138:141], v[162:165], v[90:93]
	v_mfma_f32_16x16x32_bf16 v[86:89], v[130:133], v[170:173], v[86:89]
	v_mfma_f32_16x16x32_bf16 v[82:85], v[138:141], v[170:173], v[82:85]
	v_mfma_f32_16x16x32_bf16 v[78:81], v[130:133], v[178:181], v[78:81]
	v_mfma_f32_16x16x32_bf16 v[74:77], v[138:141], v[178:181], v[74:77]
	v_mfma_f32_16x16x32_bf16 v[70:73], v[130:133], v[218:221], v[70:73]
	v_mfma_f32_16x16x32_bf16 v[66:69], v[138:141], v[218:221], v[66:69]
	v_mfma_f32_16x16x32_bf16 v[94:97], v[134:137], v[166:169], v[94:97]
	v_mfma_f32_16x16x32_bf16 v[90:93], v[142:145], v[166:169], v[90:93]
	v_mfma_f32_16x16x32_bf16 v[86:89], v[134:137], v[174:177], v[86:89]
	v_mfma_f32_16x16x32_bf16 v[82:85], v[142:145], v[174:177], v[82:85]
	v_mfma_f32_16x16x32_bf16 v[78:81], v[134:137], v[182:185], v[78:81]
	v_mfma_f32_16x16x32_bf16 v[74:77], v[142:145], v[182:185], v[74:77]
	v_mfma_f32_16x16x32_bf16 v[70:73], v[134:137], v[222:225], v[70:73]
	v_mfma_f32_16x16x32_bf16 v[66:69], v[142:145], v[222:225], v[66:69]
	v_mfma_f32_16x16x32_bf16 v[28:31], v[146:149], v[162:165], v[28:31]
	v_mfma_f32_16x16x32_bf16 v[24:27], v[154:157], v[162:165], v[24:27]
	v_mfma_f32_16x16x32_bf16 v[20:23], v[146:149], v[170:173], v[20:23]
	v_mfma_f32_16x16x32_bf16 v[16:19], v[154:157], v[170:173], v[16:19]
	v_mfma_f32_16x16x32_bf16 v[12:15], v[146:149], v[178:181], v[12:15]
	v_mfma_f32_16x16x32_bf16 v[8:11], v[154:157], v[178:181], v[8:11]
	v_mfma_f32_16x16x32_bf16 v[4:7], v[146:149], v[218:221], v[4:7]
	v_mfma_f32_16x16x32_bf16 v[0:3], v[154:157], v[218:221], v[0:3]
	v_mfma_f32_16x16x32_bf16 v[28:31], v[150:153], v[166:169], v[28:31]
	v_mfma_f32_16x16x32_bf16 v[24:27], v[158:161], v[166:169], v[24:27]
	v_mfma_f32_16x16x32_bf16 v[20:23], v[150:153], v[174:177], v[20:23]
	v_mfma_f32_16x16x32_bf16 v[16:19], v[158:161], v[174:177], v[16:19]
	v_mfma_f32_16x16x32_bf16 v[12:15], v[150:153], v[182:185], v[12:15]
	v_mfma_f32_16x16x32_bf16 v[8:11], v[158:161], v[182:185], v[8:11]
	v_mfma_f32_16x16x32_bf16 v[4:7], v[150:153], v[222:225], v[4:7]
	v_mfma_f32_16x16x32_bf16 v[0:3], v[158:161], v[222:225], v[0:3]
	s_barrier
	s_setprio 0
	s_add_i32 s50, s50, 2
	s_add_u32 s48, s48, 0x100
	s_addc_u32 s49, s49, 0
	s_add_u32 s2, s2, 0x100
	s_addc_u32 s3, s3, 0
	s_cmp_gt_u32 s50, 13
	s_cbranch_scc0 .LBB0_704
	s_and_b64 vcc, exec, s[12:13]
	s_cbranch_vccz .LBB0_707
	s_barrier
